# speedup vs baseline: 1.0184x; 1.0034x over previous
; #define PG8_STAGE(bufoff, gbase, voff) do { _Pragma("unroll") for (int _i = 0; _i < 2; ++_i) \
;         __builtin_amdgcn_global_load_lds((const unsigned*)((const char*)(gbase) + (voff)[_i]), (PG8_LAS unsigned*)(lds + (bufoff) + ldsw + _i * 8192), 16, 0, 0); } while (0)
; #define PG8_LDA(dst, b, h) do { _Pragma("unroll") for (int m = 0; m < 4; ++m) _Pragma("unroll") for (int k = 0; k < 2; ++k) dst[m][k] = *(const PG8_LAS bf16x8*)(lds + PG8_SA(b, h) + aoff + m * 2048 + k * 1024); } while (0)
; #define PG8_WAIT_V(n) asm volatile("s_waitcnt vmcnt(" #n ")" ::: "memory")
; template <class Epi, class Sched>
; __device__ __forceinline__ void gemm_phase(PG8_LAS unsigned char* lds, const Gemm g, const Sched& S, const Epi& E) {
;     ...
;         for (int t = 0; t < nt; t += 2) {
;             const bool last = (t == nt - 2);
;             const char* a1 = cA + (size_t)(t + 1) * kstep;
;             const char* a2 = last ? nA : cA + (size_t)(t + 2) * kstep; const char* b2 = last ? nB : cB + (size_t)(t + 2) * kstep;
;             const char* a3 = a2 + kstep; const char* b3 = b2 + kstep;
;             if (last && has_next) S.a_ready(nxt);
;             PG8_LDB(B0, 0, 0); PG8_SCHED; PG8_LDA(At, 0, 0); PG8_STAGE(PG8_SA(1, 1), a1 + hstep, voffA);
;             PG8_WAIT_L(8); PG8_BAR; PG8_WAIT_L(0); PG8_MMA(0, 0, At, B0); PG8_BAR; PG8_SCHED;
;             PG8_LDB(B1, 0, 1); PG8_STAGE(PG8_SB(0, 0), b2, voffB);
;             PG8_BAR; PG8_WAIT_L(0); PG8_MMA(0, 1, At, B1); PG8_BAR;
;             PG8_LDA(At, 0, 1); PG8_STAGE(PG8_SA(0, 0), a2, voffA);
;             PG8_BAR; PG8_WAIT_L(0); PG8_MMA(1, 0, At, B0); PG8_BAR; PG8_SCHED;
;             PG8_STAGE(PG8_SB(0, 1), b2 + hstep, voffB);
;             PG8_WAIT_V(6); PG8_BAR; PG8_MMA(1, 1, At, B1); PG8_BAR;
;             PG8_LDB(B0, 1, 0); PG8_SCHED; PG8_LDA(At, 1, 0); PG8_STAGE(PG8_SA(0, 1), a2 + hstep, voffA);
;             PG8_WAIT_L(8); PG8_BAR; PG8_WAIT_L(0); PG8_MMA(0, 0, At, B0); PG8_BAR; PG8_SCHED;
;             PG8_LDB(B1, 1, 1); PG8_STAGE(PG8_SB(1, 0), b3, voffB);
;             PG8_BAR; PG8_WAIT_L(0); PG8_MMA(0, 1, At, B1); PG8_BAR;
;             PG8_LDA(At, 1, 1); PG8_STAGE(PG8_SA(1, 0), a3, voffA);
;             PG8_BAR; PG8_WAIT_L(0); PG8_MMA(1, 0, At, B0); PG8_BAR; PG8_SCHED;
;             PG8_STAGE(PG8_SB(1, 1), b3 + hstep, voffB);
;             PG8_WAIT_V(6); PG8_BAR; PG8_MMA(1, 1, At, B1); PG8_BAR;
;         }
.LBB0_593:
	ds_read_b128 v[148:151], v161
	ds_read_b128 v[164:167], v161 offset:1024
	ds_read_b128 v[168:171], v161 offset:2048
	ds_read_b128 v[172:175], v161 offset:3072
	s_add_u32 s20, s18, 0xfffc0080
	s_addc_u32 s21, s19, -1
	s_cmp_eq_u32 s61, 12
	s_cselect_b32 s23, s11, s21
	s_cselect_b32 s22, s57, s20
	s_cselect_b32 s21, s9, s60
	s_cselect_b32 s20, s58, s59
	v_lshl_add_u64 v[208:209], s[18:19], 0, v[136:137]
	s_add_i32 m0, s17, 0xc000
	ds_read_b128 v[176:179], v162
	ds_read_b128 v[180:183], v162 offset:1024
	ds_read_b128 v[184:187], v162 offset:2048
	ds_read_b128 v[188:191], v162 offset:3072
	ds_read_b128 v[192:195], v162 offset:4096
	ds_read_b128 v[196:199], v162 offset:5120
	ds_read_b128 v[200:203], v162 offset:6144
	ds_read_b128 v[204:207], v162 offset:7168
	global_load_lds_dwordx4 v[208:209], off
	v_lshl_add_u64 v[208:209], s[18:19], 0, v[138:139]
	s_add_i32 m0, s17, 0xe000
	s_nop 0
	global_load_lds_dwordx4 v[208:209], off
	s_waitcnt lgkmcnt(8)
	s_barrier
	s_waitcnt lgkmcnt(0)
	s_waitcnt lgkmcnt(0)
	v_mfma_f32_16x16x32_bf16 v[124:127], v[148:151], v[176:179], v[124:127]
	v_mfma_f32_16x16x32_bf16 v[120:123], v[168:171], v[176:179], v[120:123]
	v_mfma_f32_16x16x32_bf16 v[112:115], v[148:151], v[184:187], v[112:115]
	v_mfma_f32_16x16x32_bf16 v[104:107], v[168:171], v[184:187], v[104:107]
	v_mfma_f32_16x16x32_bf16 v[96:99], v[148:151], v[192:195], v[96:99]
	v_mfma_f32_16x16x32_bf16 v[88:91], v[168:171], v[192:195], v[88:91]
	v_mfma_f32_16x16x32_bf16 v[80:83], v[148:151], v[200:203], v[80:83]
	v_mfma_f32_16x16x32_bf16 v[72:75], v[168:171], v[200:203], v[72:75]
	v_mfma_f32_16x16x32_bf16 v[124:127], v[164:167], v[180:183], v[124:127]
	v_mfma_f32_16x16x32_bf16 v[120:123], v[172:175], v[180:183], v[120:123]
	v_mfma_f32_16x16x32_bf16 v[112:115], v[164:167], v[188:191], v[112:115]
	v_mfma_f32_16x16x32_bf16 v[104:107], v[172:175], v[188:191], v[104:107]
	v_mfma_f32_16x16x32_bf16 v[96:99], v[164:167], v[196:199], v[96:99]
	v_mfma_f32_16x16x32_bf16 v[88:91], v[172:175], v[196:199], v[88:91]
	v_mfma_f32_16x16x32_bf16 v[80:83], v[164:167], v[204:207], v[80:83]
	v_mfma_f32_16x16x32_bf16 v[72:75], v[172:175], v[204:207], v[72:75]
	s_barrier
	s_add_i32 s30, s50, s27
	v_lshl_add_u64 v[224:225], s[20:21], 0, v[130:131]
	s_mov_b32 m0, s30
	ds_read_b128 v[208:211], v163
	ds_read_b128 v[212:215], v163 offset:1024
	ds_read_b128 v[216:219], v163 offset:2048
	ds_read_b128 v[220:223], v163 offset:3072
	global_load_lds_dwordx4 v[224:225], off
	v_lshl_add_u64 v[226:227], s[20:21], 0, v[134:135]
	s_add_i32 m0, s30, 0x2000
	s_nop 0
	global_load_lds_dwordx4 v[226:227], off
	s_barrier
	s_waitcnt lgkmcnt(0)
	s_waitcnt lgkmcnt(0)
	v_mfma_f32_16x16x32_bf16 v[116:119], v[208:211], v[176:179], v[116:119]
	v_mfma_f32_16x16x32_bf16 v[108:111], v[216:219], v[176:179], v[108:111]
	v_mfma_f32_16x16x32_bf16 v[100:103], v[208:211], v[184:187], v[100:103]
	v_mfma_f32_16x16x32_bf16 v[92:95], v[216:219], v[184:187], v[92:95]
	v_mfma_f32_16x16x32_bf16 v[84:87], v[208:211], v[192:195], v[84:87]
	v_mfma_f32_16x16x32_bf16 v[76:79], v[216:219], v[192:195], v[76:79]
	v_mfma_f32_16x16x32_bf16 v[68:71], v[208:211], v[200:203], v[68:71]
	v_mfma_f32_16x16x32_bf16 v[64:67], v[216:219], v[200:203], v[64:67]
	v_mfma_f32_16x16x32_bf16 v[116:119], v[212:215], v[180:183], v[116:119]
	v_mfma_f32_16x16x32_bf16 v[108:111], v[220:223], v[180:183], v[108:111]
	v_mfma_f32_16x16x32_bf16 v[100:103], v[212:215], v[188:191], v[100:103]
	v_mfma_f32_16x16x32_bf16 v[92:95], v[220:223], v[188:191], v[92:95]
	v_mfma_f32_16x16x32_bf16 v[84:87], v[212:215], v[196:199], v[84:87]
	v_mfma_f32_16x16x32_bf16 v[76:79], v[220:223], v[196:199], v[76:79]
	v_mfma_f32_16x16x32_bf16 v[68:71], v[212:215], v[204:207], v[68:71]
	v_mfma_f32_16x16x32_bf16 v[64:67], v[220:223], v[204:207], v[64:67]
	s_mov_b32 m0, s17
	v_lshl_add_u64 v[228:229], s[22:23], 0, v[128:129]
	s_barrier
	ds_read_b128 v[176:179], v162 offset:16384
	ds_read_b128 v[180:183], v162 offset:17408
	ds_read_b128 v[184:187], v162 offset:18432
	ds_read_b128 v[188:191], v162 offset:19456
	ds_read_b128 v[192:195], v162 offset:20480
	ds_read_b128 v[196:199], v162 offset:21504
	ds_read_b128 v[200:203], v162 offset:22528
	ds_read_b128 v[204:207], v162 offset:23552
	global_load_lds_dwordx4 v[228:229], off
	v_lshl_add_u64 v[230:231], s[22:23], 0, v[132:133]
	s_mov_b32 m0, s42
	s_nop 0
	global_load_lds_dwordx4 v[230:231], off
	s_barrier
	s_waitcnt lgkmcnt(0)
	s_waitcnt lgkmcnt(0)
	v_mfma_f32_16x16x32_bf16 v[60:63], v[148:151], v[176:179], v[60:63]
	v_mfma_f32_16x16x32_bf16 v[56:59], v[168:171], v[176:179], v[56:59]
	v_mfma_f32_16x16x32_bf16 v[52:55], v[148:151], v[184:187], v[52:55]
	v_mfma_f32_16x16x32_bf16 v[44:47], v[168:171], v[184:187], v[44:47]
	v_mfma_f32_16x16x32_bf16 v[36:39], v[148:151], v[192:195], v[36:39]
	v_mfma_f32_16x16x32_bf16 v[28:31], v[168:171], v[192:195], v[28:31]
	v_mfma_f32_16x16x32_bf16 v[20:23], v[148:151], v[200:203], v[20:23]
	v_mfma_f32_16x16x32_bf16 v[12:15], v[168:171], v[200:203], v[12:15]
	v_mfma_f32_16x16x32_bf16 v[60:63], v[164:167], v[180:183], v[60:63]
	v_mfma_f32_16x16x32_bf16 v[56:59], v[172:175], v[180:183], v[56:59]
	v_mfma_f32_16x16x32_bf16 v[52:55], v[164:167], v[188:191], v[52:55]
	v_mfma_f32_16x16x32_bf16 v[44:47], v[172:175], v[188:191], v[44:47]
	v_mfma_f32_16x16x32_bf16 v[36:39], v[164:167], v[196:199], v[36:39]
	v_mfma_f32_16x16x32_bf16 v[28:31], v[172:175], v[196:199], v[28:31]
	v_mfma_f32_16x16x32_bf16 v[20:23], v[164:167], v[204:207], v[20:23]
	v_mfma_f32_16x16x32_bf16 v[12:15], v[172:175], v[204:207], v[12:15]
	s_barrier
; #define PG8_STAGE(bufoff, gbase, voff) do { _Pragma("unroll") for (int _i = 0; _i < 2; ++_i) \
;         __builtin_amdgcn_global_load_lds((const unsigned*)((const char*)(gbase) + (voff)[_i]), (PG8_LAS unsigned*)(lds + (bufoff) + ldsw + _i * 8192), 16, 0, 0); } while (0)
; #define PG8_LDA(dst, b, h) do { _Pragma("unroll") for (int m = 0; m < 4; ++m) _Pragma("unroll") for (int k = 0; k < 2; ++k) dst[m][k] = *(const PG8_LAS bf16x8*)(lds + PG8_SA(b, h) + aoff + m * 2048 + k * 1024); } while (0)
; #define PG8_LDB(dst, b, h) do { _Pragma("unroll") for (int n = 0; n < 2; ++n) _Pragma("unroll") for (int k = 0; k < 2; ++k) dst[n][k] = *(const PG8_LAS bf16x8*)(lds + PG8_SB(b, h) + boff + n * 2048 + k * 1024); } while (0)
; #define PG8_MMA(ai, bj, At, Bt) do { __builtin_amdgcn_s_setprio(1); _Pragma("unroll") for (int m = 0; m < 4; ++m) _Pragma("unroll") for (int n = 0; n < 2; ++n) _Pragma("unroll") for (int k = 0; k < 2; ++k) \
;         acc[ai][bj][m][n] = __builtin_amdgcn_mfma_f32_16x16x32_bf16(Bt[n][k], At[m][k], acc[ai][bj][m][n], 0, 0, 0); __builtin_amdgcn_s_setprio(0); } while (0)
; #define PG8_WAIT_V(n) asm volatile("s_waitcnt vmcnt(" #n ")" ::: "memory")
; #define PG8_BAR __builtin_amdgcn_s_barrier()
; template <class Epi, class Sched>
; __device__ __forceinline__ void gemm_phase(PG8_LAS unsigned char* lds, const Gemm g, const Sched& S, const Epi& E) {
;     ...
;             PG8_WAIT_L(8); PG8_BAR; PG8_WAIT_L(0); PG8_MMA(0, 0, At, B0); PG8_BAR; PG8_SCHED;
;             PG8_LDB(B1, 0, 1); PG8_STAGE(PG8_SB(0, 0), b2, voffB);
;             PG8_BAR; PG8_WAIT_L(0); PG8_MMA(0, 1, At, B1); PG8_BAR;
;             PG8_LDA(At, 0, 1); PG8_STAGE(PG8_SA(0, 0), a2, voffA);
;             PG8_BAR; PG8_WAIT_L(0); PG8_MMA(1, 0, At, B0); PG8_BAR; PG8_SCHED;
;             PG8_STAGE(PG8_SB(0, 1), b2 + hstep, voffB);
;             PG8_WAIT_V(6); PG8_BAR; PG8_MMA(1, 1, At, B1); PG8_BAR;
;             PG8_LDB(B0, 1, 0); PG8_SCHED; PG8_LDA(At, 1, 0); PG8_STAGE(PG8_SA(0, 1), a2 + hstep, voffA);
;             PG8_WAIT_L(8); PG8_BAR; PG8_WAIT_L(0); PG8_MMA(0, 0, At, B0); PG8_BAR; PG8_SCHED;
;             PG8_LDB(B1, 1, 1); PG8_STAGE(PG8_SB(1, 0), b3, voffB);
;             PG8_BAR; PG8_WAIT_L(0); PG8_MMA(0, 1, At, B1); PG8_BAR;
;             PG8_LDA(At, 1, 1); PG8_STAGE(PG8_SA(1, 0), a3, voffA);
;             PG8_BAR; PG8_WAIT_L(0); PG8_MMA(1, 0, At, B0); PG8_BAR; PG8_SCHED;
	s_add_u32 s30, s20, 0x40000
	s_addc_u32 s31, s21, 0
	s_add_i32 s38, s51, s27
	v_lshl_add_u64 v[148:149], s[30:31], 0, v[130:131]
	s_mov_b32 m0, s38
	s_nop 0
	global_load_lds_dwordx4 v[148:149], off
	v_lshl_add_u64 v[148:149], s[30:31], 0, v[134:135]
	s_add_i32 m0, s38, 0x2000
	s_nop 0
	global_load_lds_dwordx4 v[148:149], off
	s_waitcnt vmcnt(6)
	s_barrier
	v_mfma_f32_16x16x32_bf16 v[48:51], v[208:211], v[176:179], v[48:51]
	v_mfma_f32_16x16x32_bf16 v[40:43], v[216:219], v[176:179], v[40:43]
	v_mfma_f32_16x16x32_bf16 v[32:35], v[208:211], v[184:187], v[32:35]
	v_mfma_f32_16x16x32_bf16 v[24:27], v[216:219], v[184:187], v[24:27]
	v_mfma_f32_16x16x32_bf16 v[16:19], v[208:211], v[192:195], v[16:19]
	v_mfma_f32_16x16x32_bf16 v[8:11], v[216:219], v[192:195], v[8:11]
	v_mfma_f32_16x16x32_bf16 v[4:7], v[208:211], v[200:203], v[4:7]
	v_mfma_f32_16x16x32_bf16 v[0:3], v[216:219], v[200:203], v[0:3]
	v_mfma_f32_16x16x32_bf16 v[48:51], v[212:215], v[180:183], v[48:51]
	v_mfma_f32_16x16x32_bf16 v[40:43], v[220:223], v[180:183], v[40:43]
	v_mfma_f32_16x16x32_bf16 v[32:35], v[212:215], v[188:191], v[32:35]
	v_mfma_f32_16x16x32_bf16 v[24:27], v[220:223], v[188:191], v[24:27]
	v_mfma_f32_16x16x32_bf16 v[16:19], v[212:215], v[196:199], v[16:19]
	v_mfma_f32_16x16x32_bf16 v[8:11], v[220:223], v[196:199], v[8:11]
	v_mfma_f32_16x16x32_bf16 v[4:7], v[212:215], v[204:207], v[4:7]
	v_mfma_f32_16x16x32_bf16 v[0:3], v[220:223], v[204:207], v[0:3]
	s_add_i32 s30, 0, 0x18000
	v_add_u32_e32 v172, s30, v159
	s_barrier
	ds_read_b128 v[148:151], v172
	ds_read_b128 v[164:167], v172 offset:1024
	ds_read_b128 v[168:171], v172 offset:2048
	ds_read_b128 v[172:175], v172 offset:3072
	s_add_u32 s22, s22, 0x40000
	s_addc_u32 s23, s23, 0
	s_mov_b32 m0, s43
	v_lshl_add_u64 v[208:209], s[22:23], 0, v[128:129]
	ds_read_b128 v[176:179], v162 offset:32768
	ds_read_b128 v[180:183], v162 offset:33792
	ds_read_b128 v[184:187], v162 offset:34816
	ds_read_b128 v[188:191], v162 offset:35840
	ds_read_b128 v[192:195], v162 offset:36864
	ds_read_b128 v[196:199], v162 offset:37888
	ds_read_b128 v[200:203], v162 offset:38912
	ds_read_b128 v[204:207], v162 offset:39936
	global_load_lds_dwordx4 v[208:209], off
	v_lshl_add_u64 v[208:209], s[22:23], 0, v[132:133]
	s_mov_b32 m0, s44
	s_nop 0
	global_load_lds_dwordx4 v[208:209], off
	s_waitcnt lgkmcnt(8)
	s_barrier
	s_waitcnt lgkmcnt(0)
	s_waitcnt lgkmcnt(0)
	v_mfma_f32_16x16x32_bf16 v[124:127], v[148:151], v[176:179], v[124:127]
	v_mfma_f32_16x16x32_bf16 v[120:123], v[168:171], v[176:179], v[120:123]
	v_mfma_f32_16x16x32_bf16 v[112:115], v[148:151], v[184:187], v[112:115]
	v_mfma_f32_16x16x32_bf16 v[104:107], v[168:171], v[184:187], v[104:107]
	v_mfma_f32_16x16x32_bf16 v[96:99], v[148:151], v[192:195], v[96:99]
	v_mfma_f32_16x16x32_bf16 v[88:91], v[168:171], v[192:195], v[88:91]
	v_mfma_f32_16x16x32_bf16 v[80:83], v[148:151], v[200:203], v[80:83]
	v_mfma_f32_16x16x32_bf16 v[72:75], v[168:171], v[200:203], v[72:75]
	v_mfma_f32_16x16x32_bf16 v[124:127], v[164:167], v[180:183], v[124:127]
	v_mfma_f32_16x16x32_bf16 v[120:123], v[172:175], v[180:183], v[120:123]
	v_mfma_f32_16x16x32_bf16 v[112:115], v[164:167], v[188:191], v[112:115]
	v_mfma_f32_16x16x32_bf16 v[104:107], v[172:175], v[188:191], v[104:107]
	v_mfma_f32_16x16x32_bf16 v[96:99], v[164:167], v[196:199], v[96:99]
	v_mfma_f32_16x16x32_bf16 v[88:91], v[172:175], v[196:199], v[88:91]
	v_mfma_f32_16x16x32_bf16 v[80:83], v[164:167], v[204:207], v[80:83]
	v_mfma_f32_16x16x32_bf16 v[72:75], v[172:175], v[204:207], v[72:75]
	s_barrier
	s_add_i32 s22, 0, 0x1c000
	s_add_i32 s23, s30, s27
	v_add_u32_e32 v220, s22, v159
	v_lshl_add_u64 v[224:225], v[224:225], 0, s[6:7]
	s_mov_b32 m0, s23
	ds_read_b128 v[208:211], v220
	ds_read_b128 v[212:215], v220 offset:1024
	ds_read_b128 v[216:219], v220 offset:2048
	ds_read_b128 v[220:223], v220 offset:3072
	global_load_lds_dwordx4 v[224:225], off
	v_lshl_add_u64 v[224:225], v[226:227], 0, s[6:7]
	s_add_i32 m0, s23, 0x2000
	s_nop 0
	global_load_lds_dwordx4 v[224:225], off
	s_barrier
	s_waitcnt lgkmcnt(0)
	s_waitcnt lgkmcnt(0)
	v_mfma_f32_16x16x32_bf16 v[116:119], v[208:211], v[176:179], v[116:119]
	v_mfma_f32_16x16x32_bf16 v[108:111], v[216:219], v[176:179], v[108:111]
	v_mfma_f32_16x16x32_bf16 v[100:103], v[208:211], v[184:187], v[100:103]
	v_mfma_f32_16x16x32_bf16 v[92:95], v[216:219], v[184:187], v[92:95]
	v_mfma_f32_16x16x32_bf16 v[84:87], v[208:211], v[192:195], v[84:87]
	v_mfma_f32_16x16x32_bf16 v[76:79], v[216:219], v[192:195], v[76:79]
	v_mfma_f32_16x16x32_bf16 v[68:71], v[208:211], v[200:203], v[68:71]
	v_mfma_f32_16x16x32_bf16 v[64:67], v[216:219], v[200:203], v[64:67]
	v_mfma_f32_16x16x32_bf16 v[116:119], v[212:215], v[180:183], v[116:119]
	v_mfma_f32_16x16x32_bf16 v[108:111], v[220:223], v[180:183], v[108:111]
	v_mfma_f32_16x16x32_bf16 v[100:103], v[212:215], v[188:191], v[100:103]
	v_mfma_f32_16x16x32_bf16 v[92:95], v[220:223], v[188:191], v[92:95]
	v_mfma_f32_16x16x32_bf16 v[84:87], v[212:215], v[196:199], v[84:87]
	v_mfma_f32_16x16x32_bf16 v[76:79], v[220:223], v[196:199], v[76:79]
	v_mfma_f32_16x16x32_bf16 v[68:71], v[212:215], v[204:207], v[68:71]
	v_mfma_f32_16x16x32_bf16 v[64:67], v[220:223], v[204:207], v[64:67]
	s_mov_b32 m0, s46
	v_lshl_add_u64 v[224:225], v[228:229], 0, s[6:7]
	s_barrier
	ds_read_b128 v[176:179], v162 offset:49152
	ds_read_b128 v[180:183], v162 offset:50176
	ds_read_b128 v[184:187], v162 offset:51200
	ds_read_b128 v[188:191], v162 offset:52224
	ds_read_b128 v[192:195], v162 offset:53248
	ds_read_b128 v[196:199], v162 offset:54272
	ds_read_b128 v[200:203], v162 offset:55296
	ds_read_b128 v[204:207], v162 offset:56320
	global_load_lds_dwordx4 v[224:225], off
	v_lshl_add_u64 v[224:225], v[230:231], 0, s[6:7]
	s_mov_b32 m0, s47
	s_nop 0
	global_load_lds_dwordx4 v[224:225], off
	s_barrier
; #define PG8_STAGE(bufoff, gbase, voff) do { _Pragma("unroll") for (int _i = 0; _i < 2; ++_i) \
;         __builtin_amdgcn_global_load_lds((const unsigned*)((const char*)(gbase) + (voff)[_i]), (PG8_LAS unsigned*)(lds + (bufoff) + ldsw + _i * 8192), 16, 0, 0); } while (0)
; #define PG8_LDA(dst, b, h) do { _Pragma("unroll") for (int m = 0; m < 4; ++m) _Pragma("unroll") for (int k = 0; k < 2; ++k) dst[m][k] = *(const PG8_LAS bf16x8*)(lds + PG8_SA(b, h) + aoff + m * 2048 + k * 1024); } while (0)
; #define PG8_MMA(ai, bj, At, Bt) do { __builtin_amdgcn_s_setprio(1); _Pragma("unroll") for (int m = 0; m < 4; ++m) _Pragma("unroll") for (int n = 0; n < 2; ++n) _Pragma("unroll") for (int k = 0; k < 2; ++k) \
;         acc[ai][bj][m][n] = __builtin_amdgcn_mfma_f32_16x16x32_bf16(Bt[n][k], At[m][k], acc[ai][bj][m][n], 0, 0, 0); __builtin_amdgcn_s_setprio(0); } while (0)
; #define PG8_WAIT_V(n) asm volatile("s_waitcnt vmcnt(" #n ")" ::: "memory")
; #define PG8_WAIT_L(n) asm volatile("s_waitcnt lgkmcnt(" #n ")" ::: "memory")
; #define PG8_BAR __builtin_amdgcn_s_barrier()
; #define PG8_SCHED __builtin_amdgcn_sched_barrier(0)
; template <class Epi, class Sched>
; __device__ __forceinline__ void gemm_phase(PG8_LAS unsigned char* lds, const Gemm g, const Sched& S, const Epi& E) {
;     ...
;             PG8_BAR; PG8_WAIT_L(0); PG8_MMA(0, 1, At, B1); PG8_BAR;
;             PG8_LDA(At, 1, 1); PG8_STAGE(PG8_SA(1, 0), a3, voffA);
;             PG8_BAR; PG8_WAIT_L(0); PG8_MMA(1, 0, At, B0); PG8_BAR; PG8_SCHED;
;             PG8_STAGE(PG8_SB(1, 1), b3 + hstep, voffB);
;             PG8_WAIT_V(6); PG8_BAR; PG8_MMA(1, 1, At, B1); PG8_BAR;
	s_waitcnt lgkmcnt(0)
	s_waitcnt lgkmcnt(0)
	v_mfma_f32_16x16x32_bf16 v[60:63], v[148:151], v[176:179], v[60:63]
	v_mfma_f32_16x16x32_bf16 v[56:59], v[168:171], v[176:179], v[56:59]
	v_mfma_f32_16x16x32_bf16 v[52:55], v[148:151], v[184:187], v[52:55]
	v_mfma_f32_16x16x32_bf16 v[44:47], v[168:171], v[184:187], v[44:47]
	v_mfma_f32_16x16x32_bf16 v[36:39], v[148:151], v[192:195], v[36:39]
	v_mfma_f32_16x16x32_bf16 v[28:31], v[168:171], v[192:195], v[28:31]
	v_mfma_f32_16x16x32_bf16 v[20:23], v[148:151], v[200:203], v[20:23]
	v_mfma_f32_16x16x32_bf16 v[12:15], v[168:171], v[200:203], v[12:15]
	v_mfma_f32_16x16x32_bf16 v[60:63], v[164:167], v[180:183], v[60:63]
	v_mfma_f32_16x16x32_bf16 v[56:59], v[172:175], v[180:183], v[56:59]
	v_mfma_f32_16x16x32_bf16 v[52:55], v[164:167], v[188:191], v[52:55]
	v_mfma_f32_16x16x32_bf16 v[44:47], v[172:175], v[188:191], v[44:47]
	v_mfma_f32_16x16x32_bf16 v[36:39], v[164:167], v[196:199], v[36:39]
	v_mfma_f32_16x16x32_bf16 v[28:31], v[172:175], v[196:199], v[28:31]
	v_mfma_f32_16x16x32_bf16 v[20:23], v[164:167], v[204:207], v[20:23]
	v_mfma_f32_16x16x32_bf16 v[12:15], v[172:175], v[204:207], v[12:15]
	s_barrier
	s_add_u32 s20, s20, 0x40080
	s_addc_u32 s21, s21, 0
	s_add_i32 s22, s22, s27
	v_lshl_add_u64 v[148:149], s[20:21], 0, v[130:131]
	s_mov_b32 m0, s22
	s_nop 0
	global_load_lds_dwordx4 v[148:149], off
	v_lshl_add_u64 v[148:149], s[20:21], 0, v[134:135]
	s_add_i32 m0, s22, 0x2000
	s_nop 0
	global_load_lds_dwordx4 v[148:149], off
	s_waitcnt vmcnt(6)
	s_barrier
	v_mfma_f32_16x16x32_bf16 v[48:51], v[208:211], v[176:179], v[48:51]
	v_mfma_f32_16x16x32_bf16 v[40:43], v[216:219], v[176:179], v[40:43]
	v_mfma_f32_16x16x32_bf16 v[32:35], v[208:211], v[184:187], v[32:35]
	v_mfma_f32_16x16x32_bf16 v[24:27], v[216:219], v[184:187], v[24:27]
	v_mfma_f32_16x16x32_bf16 v[16:19], v[208:211], v[192:195], v[16:19]
	v_mfma_f32_16x16x32_bf16 v[8:11], v[216:219], v[192:195], v[8:11]
	v_mfma_f32_16x16x32_bf16 v[4:7], v[208:211], v[200:203], v[4:7]
	v_mfma_f32_16x16x32_bf16 v[0:3], v[216:219], v[200:203], v[0:3]
	v_mfma_f32_16x16x32_bf16 v[48:51], v[212:215], v[180:183], v[48:51]
	v_mfma_f32_16x16x32_bf16 v[40:43], v[220:223], v[180:183], v[40:43]
	v_mfma_f32_16x16x32_bf16 v[32:35], v[212:215], v[188:191], v[32:35]
	v_mfma_f32_16x16x32_bf16 v[24:27], v[220:223], v[188:191], v[24:27]
	v_mfma_f32_16x16x32_bf16 v[16:19], v[212:215], v[196:199], v[16:19]
	v_mfma_f32_16x16x32_bf16 v[8:11], v[220:223], v[196:199], v[8:11]
	v_mfma_f32_16x16x32_bf16 v[4:7], v[212:215], v[204:207], v[4:7]
	v_mfma_f32_16x16x32_bf16 v[0:3], v[220:223], v[204:207], v[0:3]
	s_add_i32 s61, s61, 2
	s_add_u32 s18, s18, 0x100
	s_addc_u32 s19, s19, 0
	s_add_u32 s59, s59, 0x100
	s_addc_u32 s60, s60, 0
	s_cmp_gt_u32 s61, 13
	s_barrier
	s_cbranch_scc0 .LBB0_593
; __device__ __forceinline__ uint4 pk8(f32x4 a, f32x4 b) { return make_uint4(cvt_pk_bf16(a[0], a[1]), cvt_pk_bf16(a[2], a[3]), cvt_pk_bf16(b[0], b[1]), cvt_pk_bf16(b[2], b[3])); }
;     __device__ __forceinline__ void operator()(AccRef acc, const Unit& u, int wr, int wc, int fr, int fq) const {
;         const int pi = u.pn / tpp; bf16_t* base = pi == 0 ? pl[0] : (pi == 1 ? pl[1] : (pi == 2 ? pl[2] : pl[3]));
;         const int cbase = (u.pn - pi * tpp) * 256 + wc * 32 + 8 * fq;
; #pragma unroll
;         for (int ai = 0; ai < 2; ++ai)
; #pragma unroll
;             for (int m = 0; m < 4; ++m) {
;                 const int r = u.pm * 256 + ai * 128 + wr * 64 + m * 16 + fr;
;                 float s = 1.f;
;                 if (SCALE == 1) s = rs[r];
;                 if (SCALE == 2) s = rsqrtf(rs[r] * (1.f / D) + EPS);
;                 bf16_t* rowp = base + (size_t)r * ldc + cbase;
; #pragma unroll
;                 for (int bj = 0; bj < 2; ++bj) *(uint4*)(rowp + bj * 128) = pk8(acc[ai][bj][m][0] * s, acc[ai][bj][m][1] * s);
;             }
	s_mul_hi_i32 s9, s56, 0x10624dd3
	s_lshr_b32 s11, s9, 31
	s_lshr_b32 s9, s9, 6
	s_add_i32 s9, s9, s11
	s_mulk_i32 s9, 0x3e8
	s_sub_i32 s9, s56, s9
	v_lshl_or_b32 v148, s9, 8, v160
	v_lshl_add_u32 v150, s16, 8, v158
	v_ashrrev_i32_e32 v149, 31, v148
	v_ashrrev_i32_e32 v151, 31, v150
	v_lshl_add_u64 v[148:149], v[148:149], 1, s[88:89]
	v_bfe_i32 v250, v144, 0, 1
	v_and_b32_e32 v250, 0xfffff040, v250
	v_bfe_u32 v251, v146, 1, 1
	v_mul_u32_u24_e32 v251, 0xf80, v251
	v_add_u32_e32 v250, v250, v251
	v_and_b32_e32 v251, 1, v146
	v_lshl_add_u32 v250, v251, 6, v250
	v_ashrrev_i32_e32 v251, 31, v250
	v_lshl_add_u64 v[148:149], v[250:251], 0, v[148:149]
	v_lshlrev_b64 v[164:165], 12, v[150:151]
	v_lshl_add_u64 v[164:165], v[148:149], 0, v[164:165]
	v_cvt_pk_bf16_f32 v124, v124, v125
	v_cvt_pk_bf16_f32 v125, v126, v127
	v_cvt_pk_bf16_f32 v126, v120, v121
	v_cvt_pk_bf16_f32 v127, v122, v123
	global_store_dwordx4 v[164:165], v[124:127], off
	v_cvt_pk_bf16_f32 v116, v116, v117
	v_cvt_pk_bf16_f32 v117, v118, v119
	v_cvt_pk_bf16_f32 v118, v108, v109
	v_or_b32_e32 v108, 16, v150
	v_ashrrev_i32_e32 v109, 31, v108
	v_lshlrev_b64 v[108:109], 12, v[108:109]
	v_cvt_pk_bf16_f32 v119, v110, v111
	global_store_dwordx4 v[164:165], v[116:119], off offset:256
	s_and_b64 vcc, exec, s[4:5]
	s_mov_b32 s56, s8
	v_lshl_add_u64 v[116:117], v[148:149], 0, v[108:109]
	v_cvt_pk_bf16_f32 v108, v112, v113
	v_cvt_pk_bf16_f32 v109, v114, v115
	v_cvt_pk_bf16_f32 v110, v104, v105
	v_cvt_pk_bf16_f32 v111, v106, v107
	global_store_dwordx4 v[116:117], v[108:111], off
	v_cvt_pk_bf16_f32 v100, v100, v101
	v_cvt_pk_bf16_f32 v101, v102, v103
	v_cvt_pk_bf16_f32 v102, v92, v93
	v_or_b32_e32 v92, 32, v150
	v_ashrrev_i32_e32 v93, 31, v92
	v_lshlrev_b64 v[92:93], 12, v[92:93]
	v_cvt_pk_bf16_f32 v103, v94, v95
	global_store_dwordx4 v[116:117], v[100:103], off offset:256
	s_mov_b32 s16, s10
	s_mov_b64 s[20:21], s[14:15]
	v_lshl_add_u64 v[100:101], v[148:149], 0, v[92:93]
	v_cvt_pk_bf16_f32 v92, v96, v97
	v_cvt_pk_bf16_f32 v93, v98, v99
	v_cvt_pk_bf16_f32 v94, v88, v89
	v_cvt_pk_bf16_f32 v95, v90, v91
	global_store_dwordx4 v[100:101], v[92:95], off
	v_cvt_pk_bf16_f32 v84, v84, v85
	v_cvt_pk_bf16_f32 v85, v86, v87
	v_cvt_pk_bf16_f32 v86, v76, v77
	v_or_b32_e32 v76, 48, v150
	v_ashrrev_i32_e32 v77, 31, v76
	v_lshlrev_b64 v[76:77], 12, v[76:77]
	v_cvt_pk_bf16_f32 v87, v78, v79
	global_store_dwordx4 v[100:101], v[84:87], off offset:256
	s_mov_b64 s[18:19], s[12:13]
	s_nop 0
	v_lshl_add_u64 v[84:85], v[148:149], 0, v[76:77]
	v_cvt_pk_bf16_f32 v76, v80, v81
	v_cvt_pk_bf16_f32 v77, v82, v83
	v_cvt_pk_bf16_f32 v78, v72, v73
	v_cvt_pk_bf16_f32 v79, v74, v75
	global_store_dwordx4 v[84:85], v[76:79], off
	v_cvt_pk_bf16_f32 v68, v68, v69
	v_cvt_pk_bf16_f32 v69, v70, v71
	v_cvt_pk_bf16_f32 v70, v64, v65
	v_add_u32_e32 v64, 0x80, v150
	v_ashrrev_i32_e32 v65, 31, v64
	v_lshlrev_b64 v[64:65], 12, v[64:65]
	v_lshl_add_u64 v[64:65], v[148:149], 0, v[64:65]
	v_cvt_pk_bf16_f32 v71, v66, v67
	global_store_dwordx4 v[84:85], v[68:71], off offset:256
	v_cvt_pk_bf16_f32 v60, v60, v61
	v_cvt_pk_bf16_f32 v61, v62, v63
	v_cvt_pk_bf16_f32 v62, v56, v57
	v_cvt_pk_bf16_f32 v63, v58, v59
	global_store_dwordx4 v[64:65], v[60:63], off
	v_cvt_pk_bf16_f32 v48, v48, v49
	v_cvt_pk_bf16_f32 v49, v50, v51
	v_cvt_pk_bf16_f32 v50, v40, v41
	v_add_u32_e32 v40, 0x90, v150
	v_ashrrev_i32_e32 v41, 31, v40
	v_lshlrev_b64 v[40:41], 12, v[40:41]
	v_cvt_pk_bf16_f32 v51, v42, v43
	global_store_dwordx4 v[64:65], v[48:51], off offset:256
	s_nop 1
	v_lshl_add_u64 v[48:49], v[148:149], 0, v[40:41]
	v_cvt_pk_bf16_f32 v40, v52, v53
	v_cvt_pk_bf16_f32 v41, v54, v55
	v_cvt_pk_bf16_f32 v42, v44, v45
	v_cvt_pk_bf16_f32 v43, v46, v47
	global_store_dwordx4 v[48:49], v[40:43], off
	v_cvt_pk_bf16_f32 v32, v32, v33
	v_cvt_pk_bf16_f32 v33, v34, v35
	v_cvt_pk_bf16_f32 v34, v24, v25
	v_add_u32_e32 v24, 0xa0, v150
	v_ashrrev_i32_e32 v25, 31, v24
	v_lshlrev_b64 v[24:25], 12, v[24:25]
	v_cvt_pk_bf16_f32 v35, v26, v27
	global_store_dwordx4 v[48:49], v[32:35], off offset:256
	s_nop 1
	v_lshl_add_u64 v[32:33], v[148:149], 0, v[24:25]
	v_cvt_pk_bf16_f32 v24, v36, v37
	v_cvt_pk_bf16_f32 v25, v38, v39
	v_cvt_pk_bf16_f32 v26, v28, v29
	v_cvt_pk_bf16_f32 v27, v30, v31
	global_store_dwordx4 v[32:33], v[24:27], off
	v_cvt_pk_bf16_f32 v16, v16, v17
	v_cvt_pk_bf16_f32 v17, v18, v19
	v_cvt_pk_bf16_f32 v18, v8, v9
	v_add_u32_e32 v8, 0xb0, v150
	v_ashrrev_i32_e32 v9, 31, v8
	v_lshlrev_b64 v[8:9], 12, v[8:9]
	v_cvt_pk_bf16_f32 v19, v10, v11
	global_store_dwordx4 v[32:33], v[16:19], off offset:256
	s_nop 1
	v_lshl_add_u64 v[16:17], v[148:149], 0, v[8:9]
	v_cvt_pk_bf16_f32 v8, v20, v21
	v_cvt_pk_bf16_f32 v9, v22, v23
	v_cvt_pk_bf16_f32 v10, v12, v13
	v_cvt_pk_bf16_f32 v11, v14, v15
	global_store_dwordx4 v[16:17], v[8:11], off
	v_cvt_pk_bf16_f32 v4, v4, v5
	v_cvt_pk_bf16_f32 v5, v6, v7
	v_cvt_pk_bf16_f32 v6, v0, v1
	v_cvt_pk_bf16_f32 v7, v2, v3
	global_store_dwordx4 v[16:17], v[4:7], off offset:256
	s_cbranch_vccz .LBB0_586
	s_waitcnt vmcnt(0)
	s_cmpk_gt_u32 s3, 0xff
	s_cbranch_scc1 .LBB0_597
	s_barrier

; #define PG8_STAGE(bufoff, gbase, voff) do { _Pragma("unroll") for (int _i = 0; _i < 2; ++_i) \
;         __builtin_amdgcn_global_load_lds((const unsigned*)((const char*)(gbase) + (voff)[_i]), (PG8_LAS unsigned*)(lds + (bufoff) + ldsw + _i * 8192), 16, 0, 0); } while (0)
; #define PG8_LDA(dst, b, h) do { _Pragma("unroll") for (int m = 0; m < 4; ++m) _Pragma("unroll") for (int k = 0; k < 2; ++k) dst[m][k] = *(const PG8_LAS bf16x8*)(lds + PG8_SA(b, h) + aoff + m * 2048 + k * 1024); } while (0)
; #define PG8_WAIT_V(n) asm volatile("s_waitcnt vmcnt(" #n ")" ::: "memory")
; template <class Epi, class Sched>
; __device__ __forceinline__ void gemm_phase(PG8_LAS unsigned char* lds, const Gemm g, const Sched& S, const Epi& E) {
;     ...
;         for (int t = 0; t < nt; t += 2) {
;             const bool last = (t == nt - 2);
;             const char* a1 = cA + (size_t)(t + 1) * kstep;
;             const char* a2 = last ? nA : cA + (size_t)(t + 2) * kstep; const char* b2 = last ? nB : cB + (size_t)(t + 2) * kstep;
;             const char* a3 = a2 + kstep; const char* b3 = b2 + kstep;
;             if (last && has_next) S.a_ready(nxt);
;             PG8_LDB(B0, 0, 0); PG8_SCHED; PG8_LDA(At, 0, 0); PG8_STAGE(PG8_SA(1, 1), a1 + hstep, voffA);
;             PG8_WAIT_L(8); PG8_BAR; PG8_WAIT_L(0); PG8_MMA(0, 0, At, B0); PG8_BAR; PG8_SCHED;
;             PG8_LDB(B1, 0, 1); PG8_STAGE(PG8_SB(0, 0), b2, voffB);
;             PG8_BAR; PG8_WAIT_L(0); PG8_MMA(0, 1, At, B1); PG8_BAR;
;             PG8_LDA(At, 0, 1); PG8_STAGE(PG8_SA(0, 0), a2, voffA);
;             PG8_BAR; PG8_WAIT_L(0); PG8_MMA(1, 0, At, B0); PG8_BAR; PG8_SCHED;
;             PG8_STAGE(PG8_SB(0, 1), b2 + hstep, voffB);
;             PG8_WAIT_V(6); PG8_BAR; PG8_MMA(1, 1, At, B1); PG8_BAR;
;             PG8_LDB(B0, 1, 0); PG8_SCHED; PG8_LDA(At, 1, 0); PG8_STAGE(PG8_SA(0, 1), a2 + hstep, voffA);
;             PG8_WAIT_L(8); PG8_BAR; PG8_WAIT_L(0); PG8_MMA(0, 0, At, B0); PG8_BAR; PG8_SCHED;
;             PG8_LDB(B1, 1, 1); PG8_STAGE(PG8_SB(1, 0), b3, voffB);
;             PG8_BAR; PG8_WAIT_L(0); PG8_MMA(0, 1, At, B1); PG8_BAR;
;             PG8_LDA(At, 1, 1); PG8_STAGE(PG8_SA(1, 0), a3, voffA);
;             PG8_BAR; PG8_WAIT_L(0); PG8_MMA(1, 0, At, B0); PG8_BAR; PG8_SCHED;
;             PG8_STAGE(PG8_SB(1, 1), b3 + hstep, voffB);
;             PG8_WAIT_V(6); PG8_BAR; PG8_MMA(1, 1, At, B1); PG8_BAR;
;         }
.LBB0_613:
	ds_read_b128 v[148:151], v145
	ds_read_b128 v[160:163], v145 offset:1024
	ds_read_b128 v[164:167], v145 offset:2048
	ds_read_b128 v[168:171], v145 offset:3072
	s_add_u32 s18, s16, 0xfffc0080
	s_addc_u32 s19, s17, -1
	s_cmp_eq_u32 s61, 12
	s_cselect_b32 s21, s9, s19
	s_cselect_b32 s20, s57, s18
	s_cselect_b32 s19, s7, s60
	s_cselect_b32 s18, s58, s59
	v_lshl_add_u64 v[156:157], s[16:17], 0, v[136:137]
	s_add_i32 m0, s15, 0xc000
	ds_read_b128 v[172:175], v147
	ds_read_b128 v[176:179], v147 offset:1024
	ds_read_b128 v[180:183], v147 offset:2048
	ds_read_b128 v[184:187], v147 offset:3072
	ds_read_b128 v[188:191], v147 offset:4096
	ds_read_b128 v[192:195], v147 offset:5120
	ds_read_b128 v[196:199], v147 offset:6144
	ds_read_b128 v[200:203], v147 offset:7168
	global_load_lds_dwordx4 v[156:157], off
	v_lshl_add_u64 v[156:157], s[16:17], 0, v[138:139]
	s_add_i32 m0, s15, 0xe000
	s_nop 0
	global_load_lds_dwordx4 v[156:157], off
	s_waitcnt lgkmcnt(8)
	s_barrier
	s_waitcnt lgkmcnt(0)
	s_waitcnt lgkmcnt(0)
	v_mfma_f32_16x16x32_bf16 v[124:127], v[148:151], v[172:175], v[124:127]
	v_mfma_f32_16x16x32_bf16 v[120:123], v[164:167], v[172:175], v[120:123]
	v_mfma_f32_16x16x32_bf16 v[112:115], v[148:151], v[180:183], v[112:115]
	v_mfma_f32_16x16x32_bf16 v[104:107], v[164:167], v[180:183], v[104:107]
	v_mfma_f32_16x16x32_bf16 v[96:99], v[148:151], v[188:191], v[96:99]
	v_mfma_f32_16x16x32_bf16 v[88:91], v[164:167], v[188:191], v[88:91]
	v_mfma_f32_16x16x32_bf16 v[80:83], v[148:151], v[196:199], v[80:83]
	v_mfma_f32_16x16x32_bf16 v[72:75], v[164:167], v[196:199], v[72:75]
	v_mfma_f32_16x16x32_bf16 v[124:127], v[160:163], v[176:179], v[124:127]
	v_mfma_f32_16x16x32_bf16 v[120:123], v[168:171], v[176:179], v[120:123]
	v_mfma_f32_16x16x32_bf16 v[112:115], v[160:163], v[184:187], v[112:115]
	v_mfma_f32_16x16x32_bf16 v[104:107], v[168:171], v[184:187], v[104:107]
	v_mfma_f32_16x16x32_bf16 v[96:99], v[160:163], v[192:195], v[96:99]
	v_mfma_f32_16x16x32_bf16 v[88:91], v[168:171], v[192:195], v[88:91]
	v_mfma_f32_16x16x32_bf16 v[80:83], v[160:163], v[200:203], v[80:83]
	v_mfma_f32_16x16x32_bf16 v[72:75], v[168:171], v[200:203], v[72:75]
	s_barrier
	s_add_i32 s30, s50, s27
	v_lshl_add_u64 v[156:157], s[18:19], 0, v[130:131]
	s_mov_b32 m0, s30
	ds_read_b128 v[204:207], v152
	ds_read_b128 v[208:211], v152 offset:1024
	ds_read_b128 v[212:215], v152 offset:2048
	ds_read_b128 v[216:219], v152 offset:3072
	global_load_lds_dwordx4 v[156:157], off
	v_lshl_add_u64 v[220:221], s[18:19], 0, v[134:135]
	s_add_i32 m0, s30, 0x2000
	s_nop 0
	global_load_lds_dwordx4 v[220:221], off
	s_barrier
	s_waitcnt lgkmcnt(0)
	s_waitcnt lgkmcnt(0)
	v_mfma_f32_16x16x32_bf16 v[116:119], v[204:207], v[172:175], v[116:119]
	v_mfma_f32_16x16x32_bf16 v[108:111], v[212:215], v[172:175], v[108:111]
	v_mfma_f32_16x16x32_bf16 v[100:103], v[204:207], v[180:183], v[100:103]
	v_mfma_f32_16x16x32_bf16 v[92:95], v[212:215], v[180:183], v[92:95]
	v_mfma_f32_16x16x32_bf16 v[84:87], v[204:207], v[188:191], v[84:87]
	v_mfma_f32_16x16x32_bf16 v[76:79], v[212:215], v[188:191], v[76:79]
	v_mfma_f32_16x16x32_bf16 v[68:71], v[204:207], v[196:199], v[68:71]
	v_mfma_f32_16x16x32_bf16 v[64:67], v[212:215], v[196:199], v[64:67]
	v_mfma_f32_16x16x32_bf16 v[116:119], v[208:211], v[176:179], v[116:119]
	v_mfma_f32_16x16x32_bf16 v[108:111], v[216:219], v[176:179], v[108:111]
	v_mfma_f32_16x16x32_bf16 v[100:103], v[208:211], v[184:187], v[100:103]
	v_mfma_f32_16x16x32_bf16 v[92:95], v[216:219], v[184:187], v[92:95]
	v_mfma_f32_16x16x32_bf16 v[84:87], v[208:211], v[192:195], v[84:87]
	v_mfma_f32_16x16x32_bf16 v[76:79], v[216:219], v[192:195], v[76:79]
	v_mfma_f32_16x16x32_bf16 v[68:71], v[208:211], v[200:203], v[68:71]
	v_mfma_f32_16x16x32_bf16 v[64:67], v[216:219], v[200:203], v[64:67]
	s_mov_b32 m0, s15
	v_lshl_add_u64 v[222:223], s[20:21], 0, v[128:129]
	s_barrier
	ds_read_b128 v[172:175], v147 offset:16384
	ds_read_b128 v[176:179], v147 offset:17408
	ds_read_b128 v[180:183], v147 offset:18432
	ds_read_b128 v[184:187], v147 offset:19456
	ds_read_b128 v[188:191], v147 offset:20480
	ds_read_b128 v[192:195], v147 offset:21504
	ds_read_b128 v[196:199], v147 offset:22528
	ds_read_b128 v[200:203], v147 offset:23552
	global_load_lds_dwordx4 v[222:223], off
	v_lshl_add_u64 v[224:225], s[20:21], 0, v[132:133]
	s_mov_b32 m0, s42
	s_nop 0
	global_load_lds_dwordx4 v[224:225], off
	s_barrier
	s_waitcnt lgkmcnt(0)
	s_waitcnt lgkmcnt(0)
	v_mfma_f32_16x16x32_bf16 v[60:63], v[148:151], v[172:175], v[60:63]
	v_mfma_f32_16x16x32_bf16 v[56:59], v[164:167], v[172:175], v[56:59]
	v_mfma_f32_16x16x32_bf16 v[52:55], v[148:151], v[180:183], v[52:55]
	v_mfma_f32_16x16x32_bf16 v[44:47], v[164:167], v[180:183], v[44:47]
	v_mfma_f32_16x16x32_bf16 v[36:39], v[148:151], v[188:191], v[36:39]
	v_mfma_f32_16x16x32_bf16 v[28:31], v[164:167], v[188:191], v[28:31]
	v_mfma_f32_16x16x32_bf16 v[20:23], v[148:151], v[196:199], v[20:23]
	v_mfma_f32_16x16x32_bf16 v[12:15], v[164:167], v[196:199], v[12:15]
	v_mfma_f32_16x16x32_bf16 v[60:63], v[160:163], v[176:179], v[60:63]
	v_mfma_f32_16x16x32_bf16 v[56:59], v[168:171], v[176:179], v[56:59]
	v_mfma_f32_16x16x32_bf16 v[52:55], v[160:163], v[184:187], v[52:55]
	v_mfma_f32_16x16x32_bf16 v[44:47], v[168:171], v[184:187], v[44:47]
	v_mfma_f32_16x16x32_bf16 v[36:39], v[160:163], v[192:195], v[36:39]
	v_mfma_f32_16x16x32_bf16 v[28:31], v[168:171], v[192:195], v[28:31]
	v_mfma_f32_16x16x32_bf16 v[20:23], v[160:163], v[200:203], v[20:23]
	v_mfma_f32_16x16x32_bf16 v[12:15], v[168:171], v[200:203], v[12:15]
	s_barrier
; #define PG8_STAGE(bufoff, gbase, voff) do { _Pragma("unroll") for (int _i = 0; _i < 2; ++_i) \
;         __builtin_amdgcn_global_load_lds((const unsigned*)((const char*)(gbase) + (voff)[_i]), (PG8_LAS unsigned*)(lds + (bufoff) + ldsw + _i * 8192), 16, 0, 0); } while (0)
; #define PG8_LDA(dst, b, h) do { _Pragma("unroll") for (int m = 0; m < 4; ++m) _Pragma("unroll") for (int k = 0; k < 2; ++k) dst[m][k] = *(const PG8_LAS bf16x8*)(lds + PG8_SA(b, h) + aoff + m * 2048 + k * 1024); } while (0)
; #define PG8_LDB(dst, b, h) do { _Pragma("unroll") for (int n = 0; n < 2; ++n) _Pragma("unroll") for (int k = 0; k < 2; ++k) dst[n][k] = *(const PG8_LAS bf16x8*)(lds + PG8_SB(b, h) + boff + n * 2048 + k * 1024); } while (0)
; #define PG8_MMA(ai, bj, At, Bt) do { __builtin_amdgcn_s_setprio(1); _Pragma("unroll") for (int m = 0; m < 4; ++m) _Pragma("unroll") for (int n = 0; n < 2; ++n) _Pragma("unroll") for (int k = 0; k < 2; ++k) \
;         acc[ai][bj][m][n] = __builtin_amdgcn_mfma_f32_16x16x32_bf16(Bt[n][k], At[m][k], acc[ai][bj][m][n], 0, 0, 0); __builtin_amdgcn_s_setprio(0); } while (0)
; #define PG8_WAIT_V(n) asm volatile("s_waitcnt vmcnt(" #n ")" ::: "memory")
; #define PG8_BAR __builtin_amdgcn_s_barrier()
; template <class Epi, class Sched>
; __device__ __forceinline__ void gemm_phase(PG8_LAS unsigned char* lds, const Gemm g, const Sched& S, const Epi& E) {
;     ...
;             PG8_WAIT_L(8); PG8_BAR; PG8_WAIT_L(0); PG8_MMA(0, 0, At, B0); PG8_BAR; PG8_SCHED;
;             PG8_LDB(B1, 0, 1); PG8_STAGE(PG8_SB(0, 0), b2, voffB);
;             PG8_BAR; PG8_WAIT_L(0); PG8_MMA(0, 1, At, B1); PG8_BAR;
;             PG8_LDA(At, 0, 1); PG8_STAGE(PG8_SA(0, 0), a2, voffA);
;             PG8_BAR; PG8_WAIT_L(0); PG8_MMA(1, 0, At, B0); PG8_BAR; PG8_SCHED;
;             PG8_STAGE(PG8_SB(0, 1), b2 + hstep, voffB);
;             PG8_WAIT_V(6); PG8_BAR; PG8_MMA(1, 1, At, B1); PG8_BAR;
;             PG8_LDB(B0, 1, 0); PG8_SCHED; PG8_LDA(At, 1, 0); PG8_STAGE(PG8_SA(0, 1), a2 + hstep, voffA);
;             PG8_WAIT_L(8); PG8_BAR; PG8_WAIT_L(0); PG8_MMA(0, 0, At, B0); PG8_BAR; PG8_SCHED;
;             PG8_LDB(B1, 1, 1); PG8_STAGE(PG8_SB(1, 0), b3, voffB);
;             PG8_BAR; PG8_WAIT_L(0); PG8_MMA(0, 1, At, B1); PG8_BAR;
;             PG8_LDA(At, 1, 1); PG8_STAGE(PG8_SA(1, 0), a3, voffA);
;             PG8_BAR; PG8_WAIT_L(0); PG8_MMA(1, 0, At, B0); PG8_BAR; PG8_SCHED;
	s_add_u32 s30, s18, 0x40000
	s_addc_u32 s31, s19, 0
	s_add_i32 s38, s51, s27
	v_lshl_add_u64 v[148:149], s[30:31], 0, v[130:131]
	s_mov_b32 m0, s38
	s_nop 0
	global_load_lds_dwordx4 v[148:149], off
	v_lshl_add_u64 v[148:149], s[30:31], 0, v[134:135]
	s_add_i32 m0, s38, 0x2000
	s_nop 0
	global_load_lds_dwordx4 v[148:149], off
	s_waitcnt vmcnt(6)
	s_barrier
	v_mfma_f32_16x16x32_bf16 v[48:51], v[204:207], v[172:175], v[48:51]
	v_mfma_f32_16x16x32_bf16 v[40:43], v[212:215], v[172:175], v[40:43]
	v_mfma_f32_16x16x32_bf16 v[32:35], v[204:207], v[180:183], v[32:35]
	v_mfma_f32_16x16x32_bf16 v[24:27], v[212:215], v[180:183], v[24:27]
	v_mfma_f32_16x16x32_bf16 v[16:19], v[204:207], v[188:191], v[16:19]
	v_mfma_f32_16x16x32_bf16 v[8:11], v[212:215], v[188:191], v[8:11]
	v_mfma_f32_16x16x32_bf16 v[4:7], v[204:207], v[196:199], v[4:7]
	v_mfma_f32_16x16x32_bf16 v[0:3], v[212:215], v[196:199], v[0:3]
	v_mfma_f32_16x16x32_bf16 v[48:51], v[208:211], v[176:179], v[48:51]
	v_mfma_f32_16x16x32_bf16 v[40:43], v[216:219], v[176:179], v[40:43]
	v_mfma_f32_16x16x32_bf16 v[32:35], v[208:211], v[184:187], v[32:35]
	v_mfma_f32_16x16x32_bf16 v[24:27], v[216:219], v[184:187], v[24:27]
	v_mfma_f32_16x16x32_bf16 v[16:19], v[208:211], v[192:195], v[16:19]
	v_mfma_f32_16x16x32_bf16 v[8:11], v[216:219], v[192:195], v[8:11]
	v_mfma_f32_16x16x32_bf16 v[4:7], v[208:211], v[200:203], v[4:7]
	v_mfma_f32_16x16x32_bf16 v[0:3], v[216:219], v[200:203], v[0:3]
	s_add_i32 s30, 0, 0x18000
	v_add_u32_e32 v155, s30, v153
	s_barrier
	ds_read_b128 v[148:151], v155
	ds_read_b128 v[160:163], v155 offset:1024
	ds_read_b128 v[164:167], v155 offset:2048
	ds_read_b128 v[168:171], v155 offset:3072
	s_add_u32 s20, s20, 0x40000
	s_addc_u32 s21, s21, 0
	s_mov_b32 m0, s43
	v_lshl_add_u64 v[204:205], s[20:21], 0, v[128:129]
	ds_read_b128 v[172:175], v147 offset:32768
	ds_read_b128 v[176:179], v147 offset:33792
	ds_read_b128 v[180:183], v147 offset:34816
	ds_read_b128 v[184:187], v147 offset:35840
	ds_read_b128 v[188:191], v147 offset:36864
	ds_read_b128 v[192:195], v147 offset:37888
	ds_read_b128 v[196:199], v147 offset:38912
	ds_read_b128 v[200:203], v147 offset:39936
	global_load_lds_dwordx4 v[204:205], off
	v_lshl_add_u64 v[204:205], s[20:21], 0, v[132:133]
	s_mov_b32 m0, s44
	s_nop 0
	global_load_lds_dwordx4 v[204:205], off
	s_waitcnt lgkmcnt(8)
	s_barrier
	s_waitcnt lgkmcnt(0)
	s_waitcnt lgkmcnt(0)
	v_mfma_f32_16x16x32_bf16 v[124:127], v[148:151], v[172:175], v[124:127]
	v_mfma_f32_16x16x32_bf16 v[120:123], v[164:167], v[172:175], v[120:123]
	v_mfma_f32_16x16x32_bf16 v[112:115], v[148:151], v[180:183], v[112:115]
	v_mfma_f32_16x16x32_bf16 v[104:107], v[164:167], v[180:183], v[104:107]
	v_mfma_f32_16x16x32_bf16 v[96:99], v[148:151], v[188:191], v[96:99]
	v_mfma_f32_16x16x32_bf16 v[88:91], v[164:167], v[188:191], v[88:91]
	v_mfma_f32_16x16x32_bf16 v[80:83], v[148:151], v[196:199], v[80:83]
	v_mfma_f32_16x16x32_bf16 v[72:75], v[164:167], v[196:199], v[72:75]
	v_mfma_f32_16x16x32_bf16 v[124:127], v[160:163], v[176:179], v[124:127]
	v_mfma_f32_16x16x32_bf16 v[120:123], v[168:171], v[176:179], v[120:123]
	v_mfma_f32_16x16x32_bf16 v[112:115], v[160:163], v[184:187], v[112:115]
	v_mfma_f32_16x16x32_bf16 v[104:107], v[168:171], v[184:187], v[104:107]
	v_mfma_f32_16x16x32_bf16 v[96:99], v[160:163], v[192:195], v[96:99]
	v_mfma_f32_16x16x32_bf16 v[88:91], v[168:171], v[192:195], v[88:91]
	v_mfma_f32_16x16x32_bf16 v[80:83], v[160:163], v[200:203], v[80:83]
	v_mfma_f32_16x16x32_bf16 v[72:75], v[168:171], v[200:203], v[72:75]
	s_barrier
	s_add_i32 s20, 0, 0x1c000
	s_add_i32 s21, s30, s27
	v_add_u32_e32 v155, s20, v153
	v_lshl_add_u64 v[156:157], v[156:157], 0, s[0:1]
	s_mov_b32 m0, s21
	ds_read_b128 v[204:207], v155
	ds_read_b128 v[208:211], v155 offset:1024
	ds_read_b128 v[212:215], v155 offset:2048
	ds_read_b128 v[216:219], v155 offset:3072
	global_load_lds_dwordx4 v[156:157], off
	v_lshl_add_u64 v[156:157], v[220:221], 0, s[0:1]
	s_add_i32 m0, s21, 0x2000
	s_nop 0
	global_load_lds_dwordx4 v[156:157], off
	s_barrier
	s_waitcnt lgkmcnt(0)
	s_waitcnt lgkmcnt(0)
	v_mfma_f32_16x16x32_bf16 v[116:119], v[204:207], v[172:175], v[116:119]
	v_mfma_f32_16x16x32_bf16 v[108:111], v[212:215], v[172:175], v[108:111]
	v_mfma_f32_16x16x32_bf16 v[100:103], v[204:207], v[180:183], v[100:103]
	v_mfma_f32_16x16x32_bf16 v[92:95], v[212:215], v[180:183], v[92:95]
	v_mfma_f32_16x16x32_bf16 v[84:87], v[204:207], v[188:191], v[84:87]
	v_mfma_f32_16x16x32_bf16 v[76:79], v[212:215], v[188:191], v[76:79]
	v_mfma_f32_16x16x32_bf16 v[68:71], v[204:207], v[196:199], v[68:71]
	v_mfma_f32_16x16x32_bf16 v[64:67], v[212:215], v[196:199], v[64:67]
	v_mfma_f32_16x16x32_bf16 v[116:119], v[208:211], v[176:179], v[116:119]
	v_mfma_f32_16x16x32_bf16 v[108:111], v[216:219], v[176:179], v[108:111]
	v_mfma_f32_16x16x32_bf16 v[100:103], v[208:211], v[184:187], v[100:103]
	v_mfma_f32_16x16x32_bf16 v[92:95], v[216:219], v[184:187], v[92:95]
	v_mfma_f32_16x16x32_bf16 v[84:87], v[208:211], v[192:195], v[84:87]
	v_mfma_f32_16x16x32_bf16 v[76:79], v[216:219], v[192:195], v[76:79]
	v_mfma_f32_16x16x32_bf16 v[68:71], v[208:211], v[200:203], v[68:71]
	v_mfma_f32_16x16x32_bf16 v[64:67], v[216:219], v[200:203], v[64:67]
	s_mov_b32 m0, s46
	v_lshl_add_u64 v[156:157], v[222:223], 0, s[0:1]
	s_barrier
	ds_read_b128 v[172:175], v147 offset:49152
	ds_read_b128 v[176:179], v147 offset:50176
	ds_read_b128 v[180:183], v147 offset:51200
	ds_read_b128 v[184:187], v147 offset:52224
	ds_read_b128 v[188:191], v147 offset:53248
	ds_read_b128 v[192:195], v147 offset:54272
	ds_read_b128 v[196:199], v147 offset:55296
	ds_read_b128 v[200:203], v147 offset:56320
	global_load_lds_dwordx4 v[156:157], off
	v_lshl_add_u64 v[156:157], v[224:225], 0, s[0:1]
	s_mov_b32 m0, s47
	s_nop 0
	global_load_lds_dwordx4 v[156:157], off
	s_barrier
; #define PG8_STAGE(bufoff, gbase, voff) do { _Pragma("unroll") for (int _i = 0; _i < 2; ++_i) \
;         __builtin_amdgcn_global_load_lds((const unsigned*)((const char*)(gbase) + (voff)[_i]), (PG8_LAS unsigned*)(lds + (bufoff) + ldsw + _i * 8192), 16, 0, 0); } while (0)
; #define PG8_LDA(dst, b, h) do { _Pragma("unroll") for (int m = 0; m < 4; ++m) _Pragma("unroll") for (int k = 0; k < 2; ++k) dst[m][k] = *(const PG8_LAS bf16x8*)(lds + PG8_SA(b, h) + aoff + m * 2048 + k * 1024); } while (0)
; #define PG8_MMA(ai, bj, At, Bt) do { __builtin_amdgcn_s_setprio(1); _Pragma("unroll") for (int m = 0; m < 4; ++m) _Pragma("unroll") for (int n = 0; n < 2; ++n) _Pragma("unroll") for (int k = 0; k < 2; ++k) \
;         acc[ai][bj][m][n] = __builtin_amdgcn_mfma_f32_16x16x32_bf16(Bt[n][k], At[m][k], acc[ai][bj][m][n], 0, 0, 0); __builtin_amdgcn_s_setprio(0); } while (0)
; #define PG8_WAIT_V(n) asm volatile("s_waitcnt vmcnt(" #n ")" ::: "memory")
; #define PG8_WAIT_L(n) asm volatile("s_waitcnt lgkmcnt(" #n ")" ::: "memory")
; #define PG8_BAR __builtin_amdgcn_s_barrier()
; #define PG8_SCHED __builtin_amdgcn_sched_barrier(0)
; template <class Epi, class Sched>
; __device__ __forceinline__ void gemm_phase(PG8_LAS unsigned char* lds, const Gemm g, const Sched& S, const Epi& E) {
;     ...
;             PG8_BAR; PG8_WAIT_L(0); PG8_MMA(0, 1, At, B1); PG8_BAR;
;             PG8_LDA(At, 1, 1); PG8_STAGE(PG8_SA(1, 0), a3, voffA);
;             PG8_BAR; PG8_WAIT_L(0); PG8_MMA(1, 0, At, B0); PG8_BAR; PG8_SCHED;
;             PG8_STAGE(PG8_SB(1, 1), b3 + hstep, voffB);
;             PG8_WAIT_V(6); PG8_BAR; PG8_MMA(1, 1, At, B1); PG8_BAR;
	s_waitcnt lgkmcnt(0)
	s_waitcnt lgkmcnt(0)
	v_mfma_f32_16x16x32_bf16 v[60:63], v[148:151], v[172:175], v[60:63]
	v_mfma_f32_16x16x32_bf16 v[56:59], v[164:167], v[172:175], v[56:59]
	v_mfma_f32_16x16x32_bf16 v[52:55], v[148:151], v[180:183], v[52:55]
	v_mfma_f32_16x16x32_bf16 v[44:47], v[164:167], v[180:183], v[44:47]
	v_mfma_f32_16x16x32_bf16 v[36:39], v[148:151], v[188:191], v[36:39]
	v_mfma_f32_16x16x32_bf16 v[28:31], v[164:167], v[188:191], v[28:31]
	v_mfma_f32_16x16x32_bf16 v[20:23], v[148:151], v[196:199], v[20:23]
	v_mfma_f32_16x16x32_bf16 v[12:15], v[164:167], v[196:199], v[12:15]
	v_mfma_f32_16x16x32_bf16 v[60:63], v[160:163], v[176:179], v[60:63]
	v_mfma_f32_16x16x32_bf16 v[56:59], v[168:171], v[176:179], v[56:59]
	v_mfma_f32_16x16x32_bf16 v[52:55], v[160:163], v[184:187], v[52:55]
	v_mfma_f32_16x16x32_bf16 v[44:47], v[168:171], v[184:187], v[44:47]
	v_mfma_f32_16x16x32_bf16 v[36:39], v[160:163], v[192:195], v[36:39]
	v_mfma_f32_16x16x32_bf16 v[28:31], v[168:171], v[192:195], v[28:31]
	v_mfma_f32_16x16x32_bf16 v[20:23], v[160:163], v[200:203], v[20:23]
	v_mfma_f32_16x16x32_bf16 v[12:15], v[168:171], v[200:203], v[12:15]
	s_barrier
	s_add_u32 s18, s18, 0x40080
	s_addc_u32 s19, s19, 0
	s_add_i32 s20, s20, s27
	v_lshl_add_u64 v[148:149], s[18:19], 0, v[130:131]
	s_mov_b32 m0, s20
	s_nop 0
	global_load_lds_dwordx4 v[148:149], off
	v_lshl_add_u64 v[148:149], s[18:19], 0, v[134:135]
	s_add_i32 m0, s20, 0x2000
	s_nop 0
	global_load_lds_dwordx4 v[148:149], off
	s_waitcnt vmcnt(6)
	s_barrier
	v_mfma_f32_16x16x32_bf16 v[48:51], v[204:207], v[172:175], v[48:51]
	v_mfma_f32_16x16x32_bf16 v[40:43], v[212:215], v[172:175], v[40:43]
	v_mfma_f32_16x16x32_bf16 v[32:35], v[204:207], v[180:183], v[32:35]
	v_mfma_f32_16x16x32_bf16 v[24:27], v[212:215], v[180:183], v[24:27]
	v_mfma_f32_16x16x32_bf16 v[16:19], v[204:207], v[188:191], v[16:19]
	v_mfma_f32_16x16x32_bf16 v[8:11], v[212:215], v[188:191], v[8:11]
	v_mfma_f32_16x16x32_bf16 v[4:7], v[204:207], v[196:199], v[4:7]
	v_mfma_f32_16x16x32_bf16 v[0:3], v[212:215], v[196:199], v[0:3]
	v_mfma_f32_16x16x32_bf16 v[48:51], v[208:211], v[176:179], v[48:51]
	v_mfma_f32_16x16x32_bf16 v[40:43], v[216:219], v[176:179], v[40:43]
	v_mfma_f32_16x16x32_bf16 v[32:35], v[208:211], v[184:187], v[32:35]
	v_mfma_f32_16x16x32_bf16 v[24:27], v[216:219], v[184:187], v[24:27]
	v_mfma_f32_16x16x32_bf16 v[16:19], v[208:211], v[192:195], v[16:19]
	v_mfma_f32_16x16x32_bf16 v[8:11], v[216:219], v[192:195], v[8:11]
	v_mfma_f32_16x16x32_bf16 v[4:7], v[208:211], v[200:203], v[4:7]
	v_mfma_f32_16x16x32_bf16 v[0:3], v[216:219], v[200:203], v[0:3]
	s_add_i32 s61, s61, 2
	s_add_u32 s16, s16, 0x100
	s_addc_u32 s17, s17, 0
	s_add_u32 s59, s59, 0x100
	s_addc_u32 s60, s60, 0
	s_cmp_gt_u32 s61, 13
	s_barrier
	s_cbranch_scc0 .LBB0_613
; __device__ __forceinline__ uint4 pk8(f32x4 a, f32x4 b) { return make_uint4(cvt_pk_bf16(a[0], a[1]), cvt_pk_bf16(a[2], a[3]), cvt_pk_bf16(b[0], b[1]), cvt_pk_bf16(b[2], b[3])); }
;     __device__ __forceinline__ void operator()(AccRef acc, const Unit& u, int wr, int wc, int fr, int fq) const {
;         const int pi = u.pn / tpp; bf16_t* base = pi == 0 ? pl[0] : (pi == 1 ? pl[1] : (pi == 2 ? pl[2] : pl[3]));
;         const int cbase = (u.pn - pi * tpp) * 256 + wc * 32 + 8 * fq;
; #pragma unroll
;         for (int ai = 0; ai < 2; ++ai)
; #pragma unroll
;             for (int m = 0; m < 4; ++m) {
;                 const int r = u.pm * 256 + ai * 128 + wr * 64 + m * 16 + fr;
;                 float s = 1.f;
;                 if (SCALE == 1) s = rs[r];
;                 if (SCALE == 2) s = rsqrtf(rs[r] * (1.f / D) + EPS);
;                 bf16_t* rowp = base + (size_t)r * ldc + cbase;
; #pragma unroll
;                 for (int bj = 0; bj < 2; ++bj) *(uint4*)(rowp + bj * 128) = pk8(acc[ai][bj][m][0] * s, acc[ai][bj][m][1] * s);
;             }
	s_add_i32 s7, s56, 0x3e7
	s_cmpk_lt_u32 s7, 0x7cf
	s_cselect_b32 s7, 0x8000000, 0
	s_add_u32 s16, s88, s7
	s_mul_hi_i32 s7, s56, 0x10624dd3
	s_addc_u32 s17, s89, 0
	s_lshr_b32 s9, s7, 31
	s_lshr_b32 s7, s7, 6
	s_add_i32 s7, s7, s9
	s_mulk_i32 s7, 0x3e8
	s_sub_i32 s7, s56, s7
	v_lshl_or_b32 v148, s7, 8, v154
	v_lshl_add_u32 v150, s14, 8, v158
	v_ashrrev_i32_e32 v149, 31, v148
	v_ashrrev_i32_e32 v151, 31, v150
	v_lshl_add_u64 v[148:149], v[148:149], 1, s[16:17]
	v_bfe_i32 v250, v144, 0, 1
	v_and_b32_e32 v250, 0xfffff040, v250
	v_bfe_u32 v251, v146, 1, 1
	v_mul_u32_u24_e32 v251, 0xf80, v251
	v_add_u32_e32 v250, v250, v251
	v_and_b32_e32 v251, 1, v146
	v_lshl_add_u32 v250, v251, 6, v250
	v_ashrrev_i32_e32 v251, 31, v250
	v_lshl_add_u64 v[148:149], v[250:251], 0, v[148:149]
	v_lshlrev_b64 v[156:157], 12, v[150:151]
	v_lshl_add_u64 v[156:157], v[148:149], 0, v[156:157]
	v_cvt_pk_bf16_f32 v124, v124, v125
	v_cvt_pk_bf16_f32 v125, v126, v127
	v_cvt_pk_bf16_f32 v126, v120, v121
	v_cvt_pk_bf16_f32 v127, v122, v123
	global_store_dwordx4 v[156:157], v[124:127], off
	v_cvt_pk_bf16_f32 v116, v116, v117
	v_cvt_pk_bf16_f32 v117, v118, v119
	v_cvt_pk_bf16_f32 v118, v108, v109
	v_or_b32_e32 v108, 16, v150
	v_ashrrev_i32_e32 v109, 31, v108
	v_lshlrev_b64 v[108:109], 12, v[108:109]
	v_cvt_pk_bf16_f32 v119, v110, v111
	global_store_dwordx4 v[156:157], v[116:119], off offset:256
	s_and_b64 vcc, exec, s[4:5]
	s_mov_b32 s56, s6
	v_lshl_add_u64 v[116:117], v[148:149], 0, v[108:109]
	v_cvt_pk_bf16_f32 v108, v112, v113
	v_cvt_pk_bf16_f32 v109, v114, v115
	v_cvt_pk_bf16_f32 v110, v104, v105
	v_cvt_pk_bf16_f32 v111, v106, v107
	global_store_dwordx4 v[116:117], v[108:111], off
	v_cvt_pk_bf16_f32 v100, v100, v101
	v_cvt_pk_bf16_f32 v101, v102, v103
	v_cvt_pk_bf16_f32 v102, v92, v93
	v_or_b32_e32 v92, 32, v150
	v_ashrrev_i32_e32 v93, 31, v92
	v_lshlrev_b64 v[92:93], 12, v[92:93]
	v_cvt_pk_bf16_f32 v103, v94, v95
	global_store_dwordx4 v[116:117], v[100:103], off offset:256
	s_mov_b32 s14, s8
	s_mov_b64 s[18:19], s[12:13]
	v_lshl_add_u64 v[100:101], v[148:149], 0, v[92:93]
	v_cvt_pk_bf16_f32 v92, v96, v97
	v_cvt_pk_bf16_f32 v93, v98, v99
	v_cvt_pk_bf16_f32 v94, v88, v89
	v_cvt_pk_bf16_f32 v95, v90, v91
	global_store_dwordx4 v[100:101], v[92:95], off
	v_cvt_pk_bf16_f32 v84, v84, v85
	v_cvt_pk_bf16_f32 v85, v86, v87
	v_cvt_pk_bf16_f32 v86, v76, v77
	v_or_b32_e32 v76, 48, v150
	v_ashrrev_i32_e32 v77, 31, v76
	v_lshlrev_b64 v[76:77], 12, v[76:77]
	v_cvt_pk_bf16_f32 v87, v78, v79
	global_store_dwordx4 v[100:101], v[84:87], off offset:256
	s_mov_b64 s[16:17], s[10:11]
	s_nop 0
	v_lshl_add_u64 v[84:85], v[148:149], 0, v[76:77]
	v_cvt_pk_bf16_f32 v76, v80, v81
	v_cvt_pk_bf16_f32 v77, v82, v83
	v_cvt_pk_bf16_f32 v78, v72, v73
	v_cvt_pk_bf16_f32 v79, v74, v75
	global_store_dwordx4 v[84:85], v[76:79], off
	v_cvt_pk_bf16_f32 v68, v68, v69
	v_cvt_pk_bf16_f32 v69, v70, v71
	v_cvt_pk_bf16_f32 v70, v64, v65
	v_add_u32_e32 v64, 0x80, v150
	v_ashrrev_i32_e32 v65, 31, v64
	v_lshlrev_b64 v[64:65], 12, v[64:65]
	v_lshl_add_u64 v[64:65], v[148:149], 0, v[64:65]
	v_cvt_pk_bf16_f32 v71, v66, v67
	global_store_dwordx4 v[84:85], v[68:71], off offset:256
	v_cvt_pk_bf16_f32 v60, v60, v61
	v_cvt_pk_bf16_f32 v61, v62, v63
	v_cvt_pk_bf16_f32 v62, v56, v57
	v_cvt_pk_bf16_f32 v63, v58, v59
	global_store_dwordx4 v[64:65], v[60:63], off
	v_cvt_pk_bf16_f32 v48, v48, v49
	v_cvt_pk_bf16_f32 v49, v50, v51
	v_cvt_pk_bf16_f32 v50, v40, v41
	v_add_u32_e32 v40, 0x90, v150
	v_ashrrev_i32_e32 v41, 31, v40
	v_lshlrev_b64 v[40:41], 12, v[40:41]
	v_cvt_pk_bf16_f32 v51, v42, v43
	global_store_dwordx4 v[64:65], v[48:51], off offset:256
	s_nop 1
	v_lshl_add_u64 v[48:49], v[148:149], 0, v[40:41]
	v_cvt_pk_bf16_f32 v40, v52, v53
	v_cvt_pk_bf16_f32 v41, v54, v55
	v_cvt_pk_bf16_f32 v42, v44, v45
	v_cvt_pk_bf16_f32 v43, v46, v47
	global_store_dwordx4 v[48:49], v[40:43], off
	v_cvt_pk_bf16_f32 v32, v32, v33
	v_cvt_pk_bf16_f32 v33, v34, v35
	v_cvt_pk_bf16_f32 v34, v24, v25
	v_add_u32_e32 v24, 0xa0, v150
	v_ashrrev_i32_e32 v25, 31, v24
	v_lshlrev_b64 v[24:25], 12, v[24:25]
	v_cvt_pk_bf16_f32 v35, v26, v27
	global_store_dwordx4 v[48:49], v[32:35], off offset:256
	s_nop 1
	v_lshl_add_u64 v[32:33], v[148:149], 0, v[24:25]
	v_cvt_pk_bf16_f32 v24, v36, v37
	v_cvt_pk_bf16_f32 v25, v38, v39
	v_cvt_pk_bf16_f32 v26, v28, v29
	v_cvt_pk_bf16_f32 v27, v30, v31
	global_store_dwordx4 v[32:33], v[24:27], off
	v_cvt_pk_bf16_f32 v16, v16, v17
	v_cvt_pk_bf16_f32 v17, v18, v19
	v_cvt_pk_bf16_f32 v18, v8, v9
	v_add_u32_e32 v8, 0xb0, v150
	v_ashrrev_i32_e32 v9, 31, v8
	v_lshlrev_b64 v[8:9], 12, v[8:9]
	v_cvt_pk_bf16_f32 v19, v10, v11
	global_store_dwordx4 v[32:33], v[16:19], off offset:256
	s_nop 1
	v_lshl_add_u64 v[16:17], v[148:149], 0, v[8:9]
	v_cvt_pk_bf16_f32 v8, v20, v21
	v_cvt_pk_bf16_f32 v9, v22, v23
	v_cvt_pk_bf16_f32 v10, v12, v13
	v_cvt_pk_bf16_f32 v11, v14, v15
	global_store_dwordx4 v[16:17], v[8:11], off
	v_cvt_pk_bf16_f32 v4, v4, v5
	v_cvt_pk_bf16_f32 v5, v6, v7
	v_cvt_pk_bf16_f32 v6, v0, v1
	v_cvt_pk_bf16_f32 v7, v2, v3
	global_store_dwordx4 v[16:17], v[4:7], off offset:256
	s_cbranch_vccz .LBB0_606
	s_waitcnt vmcnt(0)
	s_cmpk_gt_u32 s3, 0xff
	s_cbranch_scc1 .LBB0_617
	s_barrier

; #define PG8_STAGE(bufoff, gbase, voff) do { _Pragma("unroll") for (int _i = 0; _i < 2; ++_i) \
;         __builtin_amdgcn_global_load_lds((const unsigned*)((const char*)(gbase) + (voff)[_i]), (PG8_LAS unsigned*)(lds + (bufoff) + ldsw + _i * 8192), 16, 0, 0); } while (0)
; #define PG8_LDA(dst, b, h) do { _Pragma("unroll") for (int m = 0; m < 4; ++m) _Pragma("unroll") for (int k = 0; k < 2; ++k) dst[m][k] = *(const PG8_LAS bf16x8*)(lds + PG8_SA(b, h) + aoff + m * 2048 + k * 1024); } while (0)
; #define PG8_WAIT_V(n) asm volatile("s_waitcnt vmcnt(" #n ")" ::: "memory")
; template <class Epi, class Sched>
; __device__ __forceinline__ void gemm_phase(PG8_LAS unsigned char* lds, const Gemm g, const Sched& S, const Epi& E) {
;     ...
;         for (int t = 0; t < nt; t += 2) {
;             const bool last = (t == nt - 2);
;             const char* a1 = cA + (size_t)(t + 1) * kstep;
;             const char* a2 = last ? nA : cA + (size_t)(t + 2) * kstep; const char* b2 = last ? nB : cB + (size_t)(t + 2) * kstep;
;             const char* a3 = a2 + kstep; const char* b3 = b2 + kstep;
;             if (last && has_next) S.a_ready(nxt);
;             PG8_LDB(B0, 0, 0); PG8_SCHED; PG8_LDA(At, 0, 0); PG8_STAGE(PG8_SA(1, 1), a1 + hstep, voffA);
;             PG8_WAIT_L(8); PG8_BAR; PG8_WAIT_L(0); PG8_MMA(0, 0, At, B0); PG8_BAR; PG8_SCHED;
;             PG8_LDB(B1, 0, 1); PG8_STAGE(PG8_SB(0, 0), b2, voffB);
;             PG8_BAR; PG8_WAIT_L(0); PG8_MMA(0, 1, At, B1); PG8_BAR;
;             PG8_LDA(At, 0, 1); PG8_STAGE(PG8_SA(0, 0), a2, voffA);
;             PG8_BAR; PG8_WAIT_L(0); PG8_MMA(1, 0, At, B0); PG8_BAR; PG8_SCHED;
;             PG8_STAGE(PG8_SB(0, 1), b2 + hstep, voffB);
;             PG8_WAIT_V(6); PG8_BAR; PG8_MMA(1, 1, At, B1); PG8_BAR;
;             PG8_LDB(B0, 1, 0); PG8_SCHED; PG8_LDA(At, 1, 0); PG8_STAGE(PG8_SA(0, 1), a2 + hstep, voffA);
;             PG8_WAIT_L(8); PG8_BAR; PG8_WAIT_L(0); PG8_MMA(0, 0, At, B0); PG8_BAR; PG8_SCHED;
;             PG8_LDB(B1, 1, 1); PG8_STAGE(PG8_SB(1, 0), b3, voffB);
;             PG8_BAR; PG8_WAIT_L(0); PG8_MMA(0, 1, At, B1); PG8_BAR;
;             PG8_LDA(At, 1, 1); PG8_STAGE(PG8_SA(1, 0), a3, voffA);
;             PG8_BAR; PG8_WAIT_L(0); PG8_MMA(1, 0, At, B0); PG8_BAR; PG8_SCHED;
;             PG8_STAGE(PG8_SB(1, 1), b3 + hstep, voffB);
;             PG8_WAIT_V(6); PG8_BAR; PG8_MMA(1, 1, At, B1); PG8_BAR;
;         }
.LBB0_688:
	ds_read_b128 v[148:151], v153
	ds_read_b128 v[156:159], v153 offset:1024
	ds_read_b128 v[160:163], v153 offset:2048
	ds_read_b128 v[164:167], v153 offset:3072
	s_add_u32 s20, s18, 0xfff80080
	s_addc_u32 s21, s19, -1
	s_cmp_eq_u32 s61, 28
	s_cselect_b32 s23, s11, s21
	s_cselect_b32 s22, s57, s20
	s_cselect_b32 s21, s9, s60
	s_cselect_b32 s20, s58, s59
	v_lshl_add_u64 v[200:201], s[18:19], 0, v[136:137]
	s_add_i32 m0, s17, 0xc000
	ds_read_b128 v[168:171], v154
	ds_read_b128 v[172:175], v154 offset:1024
	ds_read_b128 v[176:179], v154 offset:2048
	ds_read_b128 v[180:183], v154 offset:3072
	ds_read_b128 v[184:187], v154 offset:4096
	ds_read_b128 v[188:191], v154 offset:5120
	ds_read_b128 v[192:195], v154 offset:6144
	ds_read_b128 v[196:199], v154 offset:7168
	global_load_lds_dwordx4 v[200:201], off
	v_lshl_add_u64 v[200:201], s[18:19], 0, v[138:139]
	s_add_i32 m0, s17, 0xe000
	s_nop 0
	global_load_lds_dwordx4 v[200:201], off
	s_waitcnt lgkmcnt(8)
	s_barrier
	s_waitcnt lgkmcnt(0)
	s_waitcnt lgkmcnt(0)
	v_mfma_f32_16x16x32_bf16 v[124:127], v[148:151], v[168:171], v[124:127]
	v_mfma_f32_16x16x32_bf16 v[116:119], v[160:163], v[168:171], v[116:119]
	v_mfma_f32_16x16x32_bf16 v[108:111], v[148:151], v[176:179], v[108:111]
	v_mfma_f32_16x16x32_bf16 v[100:103], v[160:163], v[176:179], v[100:103]
	v_mfma_f32_16x16x32_bf16 v[92:95], v[148:151], v[184:187], v[92:95]
	v_mfma_f32_16x16x32_bf16 v[84:87], v[160:163], v[184:187], v[84:87]
	v_mfma_f32_16x16x32_bf16 v[76:79], v[148:151], v[192:195], v[76:79]
	v_mfma_f32_16x16x32_bf16 v[68:71], v[160:163], v[192:195], v[68:71]
	v_mfma_f32_16x16x32_bf16 v[124:127], v[156:159], v[172:175], v[124:127]
	v_mfma_f32_16x16x32_bf16 v[116:119], v[164:167], v[172:175], v[116:119]
	v_mfma_f32_16x16x32_bf16 v[108:111], v[156:159], v[180:183], v[108:111]
	v_mfma_f32_16x16x32_bf16 v[100:103], v[164:167], v[180:183], v[100:103]
	v_mfma_f32_16x16x32_bf16 v[92:95], v[156:159], v[188:191], v[92:95]
	v_mfma_f32_16x16x32_bf16 v[84:87], v[164:167], v[188:191], v[84:87]
	v_mfma_f32_16x16x32_bf16 v[76:79], v[156:159], v[196:199], v[76:79]
	v_mfma_f32_16x16x32_bf16 v[68:71], v[164:167], v[196:199], v[68:71]
	s_barrier
	s_add_i32 s30, s50, s27
	v_lshl_add_u64 v[216:217], s[20:21], 0, v[130:131]
	s_mov_b32 m0, s30
	ds_read_b128 v[200:203], v155
	ds_read_b128 v[204:207], v155 offset:1024
	ds_read_b128 v[208:211], v155 offset:2048
	ds_read_b128 v[212:215], v155 offset:3072
	global_load_lds_dwordx4 v[216:217], off
	v_lshl_add_u64 v[218:219], s[20:21], 0, v[134:135]
	s_add_i32 m0, s30, 0x2000
	s_nop 0
	global_load_lds_dwordx4 v[218:219], off
	s_barrier
	s_waitcnt lgkmcnt(0)
	s_waitcnt lgkmcnt(0)
	v_mfma_f32_16x16x32_bf16 v[120:123], v[200:203], v[168:171], v[120:123]
	v_mfma_f32_16x16x32_bf16 v[112:115], v[208:211], v[168:171], v[112:115]
	v_mfma_f32_16x16x32_bf16 v[104:107], v[200:203], v[176:179], v[104:107]
	v_mfma_f32_16x16x32_bf16 v[96:99], v[208:211], v[176:179], v[96:99]
	v_mfma_f32_16x16x32_bf16 v[88:91], v[200:203], v[184:187], v[88:91]
	v_mfma_f32_16x16x32_bf16 v[80:83], v[208:211], v[184:187], v[80:83]
	v_mfma_f32_16x16x32_bf16 v[72:75], v[200:203], v[192:195], v[72:75]
	v_mfma_f32_16x16x32_bf16 v[64:67], v[208:211], v[192:195], v[64:67]
	v_mfma_f32_16x16x32_bf16 v[120:123], v[204:207], v[172:175], v[120:123]
	v_mfma_f32_16x16x32_bf16 v[112:115], v[212:215], v[172:175], v[112:115]
	v_mfma_f32_16x16x32_bf16 v[104:107], v[204:207], v[180:183], v[104:107]
	v_mfma_f32_16x16x32_bf16 v[96:99], v[212:215], v[180:183], v[96:99]
	v_mfma_f32_16x16x32_bf16 v[88:91], v[204:207], v[188:191], v[88:91]
	v_mfma_f32_16x16x32_bf16 v[80:83], v[212:215], v[188:191], v[80:83]
	v_mfma_f32_16x16x32_bf16 v[72:75], v[204:207], v[196:199], v[72:75]
	v_mfma_f32_16x16x32_bf16 v[64:67], v[212:215], v[196:199], v[64:67]
	s_mov_b32 m0, s17
	v_lshl_add_u64 v[220:221], s[22:23], 0, v[128:129]
	s_barrier
	ds_read_b128 v[168:171], v154 offset:16384
	ds_read_b128 v[172:175], v154 offset:17408
	ds_read_b128 v[176:179], v154 offset:18432
	ds_read_b128 v[180:183], v154 offset:19456
	ds_read_b128 v[184:187], v154 offset:20480
	ds_read_b128 v[188:191], v154 offset:21504
	ds_read_b128 v[192:195], v154 offset:22528
	ds_read_b128 v[196:199], v154 offset:23552
	global_load_lds_dwordx4 v[220:221], off
	v_lshl_add_u64 v[222:223], s[22:23], 0, v[132:133]
	s_mov_b32 m0, s42
	s_nop 0
	global_load_lds_dwordx4 v[222:223], off
	s_barrier
	s_waitcnt lgkmcnt(0)
	s_waitcnt lgkmcnt(0)
	v_mfma_f32_16x16x32_bf16 v[60:63], v[148:151], v[168:171], v[60:63]
	v_mfma_f32_16x16x32_bf16 v[52:55], v[160:163], v[168:171], v[52:55]
	v_mfma_f32_16x16x32_bf16 v[44:47], v[148:151], v[176:179], v[44:47]
	v_mfma_f32_16x16x32_bf16 v[36:39], v[160:163], v[176:179], v[36:39]
	v_mfma_f32_16x16x32_bf16 v[28:31], v[148:151], v[184:187], v[28:31]
	v_mfma_f32_16x16x32_bf16 v[20:23], v[160:163], v[184:187], v[20:23]
	v_mfma_f32_16x16x32_bf16 v[12:15], v[148:151], v[192:195], v[12:15]
	v_mfma_f32_16x16x32_bf16 v[4:7], v[160:163], v[192:195], v[4:7]
	v_mfma_f32_16x16x32_bf16 v[60:63], v[156:159], v[172:175], v[60:63]
	v_mfma_f32_16x16x32_bf16 v[52:55], v[164:167], v[172:175], v[52:55]
	v_mfma_f32_16x16x32_bf16 v[44:47], v[156:159], v[180:183], v[44:47]
	v_mfma_f32_16x16x32_bf16 v[36:39], v[164:167], v[180:183], v[36:39]
	v_mfma_f32_16x16x32_bf16 v[28:31], v[156:159], v[188:191], v[28:31]
	v_mfma_f32_16x16x32_bf16 v[20:23], v[164:167], v[188:191], v[20:23]
	v_mfma_f32_16x16x32_bf16 v[12:15], v[156:159], v[196:199], v[12:15]
	v_mfma_f32_16x16x32_bf16 v[4:7], v[164:167], v[196:199], v[4:7]
	s_barrier
; #define PG8_STAGE(bufoff, gbase, voff) do { _Pragma("unroll") for (int _i = 0; _i < 2; ++_i) \
;         __builtin_amdgcn_global_load_lds((const unsigned*)((const char*)(gbase) + (voff)[_i]), (PG8_LAS unsigned*)(lds + (bufoff) + ldsw + _i * 8192), 16, 0, 0); } while (0)
; #define PG8_LDA(dst, b, h) do { _Pragma("unroll") for (int m = 0; m < 4; ++m) _Pragma("unroll") for (int k = 0; k < 2; ++k) dst[m][k] = *(const PG8_LAS bf16x8*)(lds + PG8_SA(b, h) + aoff + m * 2048 + k * 1024); } while (0)
; #define PG8_LDB(dst, b, h) do { _Pragma("unroll") for (int n = 0; n < 2; ++n) _Pragma("unroll") for (int k = 0; k < 2; ++k) dst[n][k] = *(const PG8_LAS bf16x8*)(lds + PG8_SB(b, h) + boff + n * 2048 + k * 1024); } while (0)
; #define PG8_MMA(ai, bj, At, Bt) do { __builtin_amdgcn_s_setprio(1); _Pragma("unroll") for (int m = 0; m < 4; ++m) _Pragma("unroll") for (int n = 0; n < 2; ++n) _Pragma("unroll") for (int k = 0; k < 2; ++k) \
;         acc[ai][bj][m][n] = __builtin_amdgcn_mfma_f32_16x16x32_bf16(Bt[n][k], At[m][k], acc[ai][bj][m][n], 0, 0, 0); __builtin_amdgcn_s_setprio(0); } while (0)
; #define PG8_WAIT_V(n) asm volatile("s_waitcnt vmcnt(" #n ")" ::: "memory")
; #define PG8_BAR __builtin_amdgcn_s_barrier()
; template <class Epi, class Sched>
; __device__ __forceinline__ void gemm_phase(PG8_LAS unsigned char* lds, const Gemm g, const Sched& S, const Epi& E) {
;     ...
;             PG8_WAIT_L(8); PG8_BAR; PG8_WAIT_L(0); PG8_MMA(0, 0, At, B0); PG8_BAR; PG8_SCHED;
;             PG8_LDB(B1, 0, 1); PG8_STAGE(PG8_SB(0, 0), b2, voffB);
;             PG8_BAR; PG8_WAIT_L(0); PG8_MMA(0, 1, At, B1); PG8_BAR;
;             PG8_LDA(At, 0, 1); PG8_STAGE(PG8_SA(0, 0), a2, voffA);
;             PG8_BAR; PG8_WAIT_L(0); PG8_MMA(1, 0, At, B0); PG8_BAR; PG8_SCHED;
;             PG8_STAGE(PG8_SB(0, 1), b2 + hstep, voffB);
;             PG8_WAIT_V(6); PG8_BAR; PG8_MMA(1, 1, At, B1); PG8_BAR;
;             PG8_LDB(B0, 1, 0); PG8_SCHED; PG8_LDA(At, 1, 0); PG8_STAGE(PG8_SA(0, 1), a2 + hstep, voffA);
;             PG8_WAIT_L(8); PG8_BAR; PG8_WAIT_L(0); PG8_MMA(0, 0, At, B0); PG8_BAR; PG8_SCHED;
;             PG8_LDB(B1, 1, 1); PG8_STAGE(PG8_SB(1, 0), b3, voffB);
;             PG8_BAR; PG8_WAIT_L(0); PG8_MMA(0, 1, At, B1); PG8_BAR;
;             PG8_LDA(At, 1, 1); PG8_STAGE(PG8_SA(1, 0), a3, voffA);
;             PG8_BAR; PG8_WAIT_L(0); PG8_MMA(1, 0, At, B0); PG8_BAR; PG8_SCHED;
	s_add_u32 s30, s20, 0x80000
	s_addc_u32 s31, s21, 0
	s_add_i32 s38, s51, s27
	v_lshl_add_u64 v[148:149], s[30:31], 0, v[130:131]
	s_mov_b32 m0, s38
	s_nop 0
	global_load_lds_dwordx4 v[148:149], off
	v_lshl_add_u64 v[148:149], s[30:31], 0, v[134:135]
	s_add_i32 m0, s38, 0x2000
	s_nop 0
	global_load_lds_dwordx4 v[148:149], off
	s_waitcnt vmcnt(6)
	s_barrier
	v_mfma_f32_16x16x32_bf16 v[56:59], v[200:203], v[168:171], v[56:59]
	v_mfma_f32_16x16x32_bf16 v[48:51], v[208:211], v[168:171], v[48:51]
	v_mfma_f32_16x16x32_bf16 v[40:43], v[200:203], v[176:179], v[40:43]
	v_mfma_f32_16x16x32_bf16 v[32:35], v[208:211], v[176:179], v[32:35]
	v_mfma_f32_16x16x32_bf16 v[24:27], v[200:203], v[184:187], v[24:27]
	v_mfma_f32_16x16x32_bf16 v[16:19], v[208:211], v[184:187], v[16:19]
	v_mfma_f32_16x16x32_bf16 v[8:11], v[200:203], v[192:195], v[8:11]
	v_mfma_f32_16x16x32_bf16 v[0:3], v[208:211], v[192:195], v[0:3]
	v_mfma_f32_16x16x32_bf16 v[56:59], v[204:207], v[172:175], v[56:59]
	v_mfma_f32_16x16x32_bf16 v[48:51], v[212:215], v[172:175], v[48:51]
	v_mfma_f32_16x16x32_bf16 v[40:43], v[204:207], v[180:183], v[40:43]
	v_mfma_f32_16x16x32_bf16 v[32:35], v[212:215], v[180:183], v[32:35]
	v_mfma_f32_16x16x32_bf16 v[24:27], v[204:207], v[188:191], v[24:27]
	v_mfma_f32_16x16x32_bf16 v[16:19], v[212:215], v[188:191], v[16:19]
	v_mfma_f32_16x16x32_bf16 v[8:11], v[204:207], v[196:199], v[8:11]
	v_mfma_f32_16x16x32_bf16 v[0:3], v[212:215], v[196:199], v[0:3]
	s_add_i32 s30, 0, 0x18000
	v_add_u32_e32 v164, s30, v147
	s_barrier
	ds_read_b128 v[148:151], v164
	ds_read_b128 v[156:159], v164 offset:1024
	ds_read_b128 v[160:163], v164 offset:2048
	ds_read_b128 v[164:167], v164 offset:3072
	s_add_u32 s22, s22, 0x80000
	s_addc_u32 s23, s23, 0
	s_mov_b32 m0, s43
	v_lshl_add_u64 v[200:201], s[22:23], 0, v[128:129]
	ds_read_b128 v[168:171], v154 offset:32768
	ds_read_b128 v[172:175], v154 offset:33792
	ds_read_b128 v[176:179], v154 offset:34816
	ds_read_b128 v[180:183], v154 offset:35840
	ds_read_b128 v[184:187], v154 offset:36864
	ds_read_b128 v[188:191], v154 offset:37888
	ds_read_b128 v[192:195], v154 offset:38912
	ds_read_b128 v[196:199], v154 offset:39936
	global_load_lds_dwordx4 v[200:201], off
	v_lshl_add_u64 v[200:201], s[22:23], 0, v[132:133]
	s_mov_b32 m0, s44
	s_nop 0
	global_load_lds_dwordx4 v[200:201], off
	s_waitcnt lgkmcnt(8)
	s_barrier
	s_waitcnt lgkmcnt(0)
	s_waitcnt lgkmcnt(0)
	v_mfma_f32_16x16x32_bf16 v[124:127], v[148:151], v[168:171], v[124:127]
	v_mfma_f32_16x16x32_bf16 v[116:119], v[160:163], v[168:171], v[116:119]
	v_mfma_f32_16x16x32_bf16 v[108:111], v[148:151], v[176:179], v[108:111]
	v_mfma_f32_16x16x32_bf16 v[100:103], v[160:163], v[176:179], v[100:103]
	v_mfma_f32_16x16x32_bf16 v[92:95], v[148:151], v[184:187], v[92:95]
	v_mfma_f32_16x16x32_bf16 v[84:87], v[160:163], v[184:187], v[84:87]
	v_mfma_f32_16x16x32_bf16 v[76:79], v[148:151], v[192:195], v[76:79]
	v_mfma_f32_16x16x32_bf16 v[68:71], v[160:163], v[192:195], v[68:71]
	v_mfma_f32_16x16x32_bf16 v[124:127], v[156:159], v[172:175], v[124:127]
	v_mfma_f32_16x16x32_bf16 v[116:119], v[164:167], v[172:175], v[116:119]
	v_mfma_f32_16x16x32_bf16 v[108:111], v[156:159], v[180:183], v[108:111]
	v_mfma_f32_16x16x32_bf16 v[100:103], v[164:167], v[180:183], v[100:103]
	v_mfma_f32_16x16x32_bf16 v[92:95], v[156:159], v[188:191], v[92:95]
	v_mfma_f32_16x16x32_bf16 v[84:87], v[164:167], v[188:191], v[84:87]
	v_mfma_f32_16x16x32_bf16 v[76:79], v[156:159], v[196:199], v[76:79]
	v_mfma_f32_16x16x32_bf16 v[68:71], v[164:167], v[196:199], v[68:71]
	s_barrier
	s_add_i32 s22, 0, 0x1c000
	s_add_i32 s23, s30, s27
	v_add_u32_e32 v212, s22, v147
	v_lshl_add_u64 v[216:217], v[216:217], 0, s[6:7]
	s_mov_b32 m0, s23
	ds_read_b128 v[200:203], v212
	ds_read_b128 v[204:207], v212 offset:1024
	ds_read_b128 v[208:211], v212 offset:2048
	ds_read_b128 v[212:215], v212 offset:3072
	global_load_lds_dwordx4 v[216:217], off
	v_lshl_add_u64 v[216:217], v[218:219], 0, s[6:7]
	s_add_i32 m0, s23, 0x2000
	s_nop 0
	global_load_lds_dwordx4 v[216:217], off
	s_barrier
	s_waitcnt lgkmcnt(0)
	s_waitcnt lgkmcnt(0)
	v_mfma_f32_16x16x32_bf16 v[120:123], v[200:203], v[168:171], v[120:123]
	v_mfma_f32_16x16x32_bf16 v[112:115], v[208:211], v[168:171], v[112:115]
	v_mfma_f32_16x16x32_bf16 v[104:107], v[200:203], v[176:179], v[104:107]
	v_mfma_f32_16x16x32_bf16 v[96:99], v[208:211], v[176:179], v[96:99]
	v_mfma_f32_16x16x32_bf16 v[88:91], v[200:203], v[184:187], v[88:91]
	v_mfma_f32_16x16x32_bf16 v[80:83], v[208:211], v[184:187], v[80:83]
	v_mfma_f32_16x16x32_bf16 v[72:75], v[200:203], v[192:195], v[72:75]
	v_mfma_f32_16x16x32_bf16 v[64:67], v[208:211], v[192:195], v[64:67]
	v_mfma_f32_16x16x32_bf16 v[120:123], v[204:207], v[172:175], v[120:123]
	v_mfma_f32_16x16x32_bf16 v[112:115], v[212:215], v[172:175], v[112:115]
	v_mfma_f32_16x16x32_bf16 v[104:107], v[204:207], v[180:183], v[104:107]
	v_mfma_f32_16x16x32_bf16 v[96:99], v[212:215], v[180:183], v[96:99]
	v_mfma_f32_16x16x32_bf16 v[88:91], v[204:207], v[188:191], v[88:91]
	v_mfma_f32_16x16x32_bf16 v[80:83], v[212:215], v[188:191], v[80:83]
	v_mfma_f32_16x16x32_bf16 v[72:75], v[204:207], v[196:199], v[72:75]
	v_mfma_f32_16x16x32_bf16 v[64:67], v[212:215], v[196:199], v[64:67]
	s_mov_b32 m0, s46
	v_lshl_add_u64 v[216:217], v[220:221], 0, s[6:7]
	s_barrier
	ds_read_b128 v[168:171], v154 offset:49152
	ds_read_b128 v[172:175], v154 offset:50176
	ds_read_b128 v[176:179], v154 offset:51200
	ds_read_b128 v[180:183], v154 offset:52224
	ds_read_b128 v[184:187], v154 offset:53248
	ds_read_b128 v[188:191], v154 offset:54272
	ds_read_b128 v[192:195], v154 offset:55296
	ds_read_b128 v[196:199], v154 offset:56320
	global_load_lds_dwordx4 v[216:217], off
	v_lshl_add_u64 v[216:217], v[222:223], 0, s[6:7]
	s_mov_b32 m0, s47
	s_nop 0
	global_load_lds_dwordx4 v[216:217], off
	s_barrier
; #define PG8_STAGE(bufoff, gbase, voff) do { _Pragma("unroll") for (int _i = 0; _i < 2; ++_i) \
;         __builtin_amdgcn_global_load_lds((const unsigned*)((const char*)(gbase) + (voff)[_i]), (PG8_LAS unsigned*)(lds + (bufoff) + ldsw + _i * 8192), 16, 0, 0); } while (0)
; #define PG8_LDA(dst, b, h) do { _Pragma("unroll") for (int m = 0; m < 4; ++m) _Pragma("unroll") for (int k = 0; k < 2; ++k) dst[m][k] = *(const PG8_LAS bf16x8*)(lds + PG8_SA(b, h) + aoff + m * 2048 + k * 1024); } while (0)
; #define PG8_LDB(dst, b, h) do { _Pragma("unroll") for (int n = 0; n < 2; ++n) _Pragma("unroll") for (int k = 0; k < 2; ++k) dst[n][k] = *(const PG8_LAS bf16x8*)(lds + PG8_SB(b, h) + boff + n * 2048 + k * 1024); } while (0)
; #define PG8_WAIT_V(n) asm volatile("s_waitcnt vmcnt(" #n ")" ::: "memory")
; #define PG8_WAIT_L(n) asm volatile("s_waitcnt lgkmcnt(" #n ")" ::: "memory")
; #define PG8_BAR __builtin_amdgcn_s_barrier()
; #define PG8_SCHED __builtin_amdgcn_sched_barrier(0)
; template <class Epi, class Sched>
; __device__ __forceinline__ void gemm_phase(PG8_LAS unsigned char* lds, const Gemm g, const Sched& S, const Epi& E) {
;     ...
;             PG8_WAIT_V(6); PG8_BAR; PG8_MMA(1, 1, At, B1); PG8_BAR;
;             PG8_LDB(B0, 1, 0); PG8_SCHED; PG8_LDA(At, 1, 0); PG8_STAGE(PG8_SA(0, 1), a2 + hstep, voffA);
;             PG8_WAIT_L(8); PG8_BAR; PG8_WAIT_L(0); PG8_MMA(0, 0, At, B0); PG8_BAR; PG8_SCHED;
;             PG8_LDB(B1, 1, 1); PG8_STAGE(PG8_SB(1, 0), b3, voffB);
;             PG8_BAR; PG8_WAIT_L(0); PG8_MMA(0, 1, At, B1); PG8_BAR;
;             PG8_LDA(At, 1, 1); PG8_STAGE(PG8_SA(1, 0), a3, voffA);
;             PG8_BAR; PG8_WAIT_L(0); PG8_MMA(1, 0, At, B0); PG8_BAR; PG8_SCHED;
;             PG8_STAGE(PG8_SB(1, 1), b3 + hstep, voffB);
;             PG8_WAIT_V(6); PG8_BAR; PG8_MMA(1, 1, At, B1); PG8_BAR;
;     __device__ __forceinline__ void operator()(AccRef acc, const Unit& u, int wr, int wc, int fr, int fq) const {
;         const int c0 = u.pn * 128 + wc * 32 + 8 * fq;
; #pragma unroll
;         for (int ai = 0; ai < 2; ++ai)
; #pragma unroll
;             for (int m = 0; m < 4; ++m) {
;                 const int r = u.pm * 256 + ai * 128 + wr * 64 + m * 16 + fr;
;                 const float s = rinv[r];
;                 const size_t o = (size_t)r * D + c0;
;                 const uint4 pa8 = *(const uint4*)(Pa + o), pb8 = *(const uint4*)(Pb + o);
	s_waitcnt lgkmcnt(0)
	s_waitcnt lgkmcnt(0)
	v_mfma_f32_16x16x32_bf16 v[60:63], v[148:151], v[168:171], v[60:63]
	v_mfma_f32_16x16x32_bf16 v[52:55], v[160:163], v[168:171], v[52:55]
	v_mfma_f32_16x16x32_bf16 v[44:47], v[148:151], v[176:179], v[44:47]
	v_mfma_f32_16x16x32_bf16 v[36:39], v[160:163], v[176:179], v[36:39]
	v_mfma_f32_16x16x32_bf16 v[28:31], v[148:151], v[184:187], v[28:31]
	v_mfma_f32_16x16x32_bf16 v[20:23], v[160:163], v[184:187], v[20:23]
	v_mfma_f32_16x16x32_bf16 v[12:15], v[148:151], v[192:195], v[12:15]
	v_mfma_f32_16x16x32_bf16 v[4:7], v[160:163], v[192:195], v[4:7]
	v_mfma_f32_16x16x32_bf16 v[60:63], v[156:159], v[172:175], v[60:63]
	v_mfma_f32_16x16x32_bf16 v[52:55], v[164:167], v[172:175], v[52:55]
	v_mfma_f32_16x16x32_bf16 v[44:47], v[156:159], v[180:183], v[44:47]
	v_mfma_f32_16x16x32_bf16 v[36:39], v[164:167], v[180:183], v[36:39]
	v_mfma_f32_16x16x32_bf16 v[28:31], v[156:159], v[188:191], v[28:31]
	v_mfma_f32_16x16x32_bf16 v[20:23], v[164:167], v[188:191], v[20:23]
	v_mfma_f32_16x16x32_bf16 v[12:15], v[156:159], v[196:199], v[12:15]
	v_mfma_f32_16x16x32_bf16 v[4:7], v[164:167], v[196:199], v[4:7]
	s_barrier
	s_add_u32 s20, s20, 0x80080
	s_addc_u32 s21, s21, 0
	s_add_i32 s22, s22, s27
	v_lshl_add_u64 v[148:149], s[20:21], 0, v[130:131]
	s_mov_b32 m0, s22
	s_nop 0
	global_load_lds_dwordx4 v[148:149], off
	v_lshl_add_u64 v[148:149], s[20:21], 0, v[134:135]
	s_add_i32 m0, s22, 0x2000
	s_nop 0
	global_load_lds_dwordx4 v[148:149], off
	s_waitcnt vmcnt(6)
	s_barrier
	v_mfma_f32_16x16x32_bf16 v[56:59], v[200:203], v[168:171], v[56:59]
	v_mfma_f32_16x16x32_bf16 v[48:51], v[208:211], v[168:171], v[48:51]
	v_mfma_f32_16x16x32_bf16 v[40:43], v[200:203], v[176:179], v[40:43]
	v_mfma_f32_16x16x32_bf16 v[32:35], v[208:211], v[176:179], v[32:35]
	v_mfma_f32_16x16x32_bf16 v[24:27], v[200:203], v[184:187], v[24:27]
	v_mfma_f32_16x16x32_bf16 v[16:19], v[208:211], v[184:187], v[16:19]
	v_mfma_f32_16x16x32_bf16 v[8:11], v[200:203], v[192:195], v[8:11]
	v_mfma_f32_16x16x32_bf16 v[0:3], v[208:211], v[192:195], v[0:3]
	v_mfma_f32_16x16x32_bf16 v[56:59], v[204:207], v[172:175], v[56:59]
	v_mfma_f32_16x16x32_bf16 v[48:51], v[212:215], v[172:175], v[48:51]
	v_mfma_f32_16x16x32_bf16 v[40:43], v[204:207], v[180:183], v[40:43]
	v_mfma_f32_16x16x32_bf16 v[32:35], v[212:215], v[180:183], v[32:35]
	v_mfma_f32_16x16x32_bf16 v[24:27], v[204:207], v[188:191], v[24:27]
	v_mfma_f32_16x16x32_bf16 v[16:19], v[212:215], v[188:191], v[16:19]
	v_mfma_f32_16x16x32_bf16 v[8:11], v[204:207], v[196:199], v[8:11]
	v_mfma_f32_16x16x32_bf16 v[0:3], v[212:215], v[196:199], v[0:3]
	s_add_i32 s61, s61, 2
	s_add_u32 s18, s18, 0x100
	s_addc_u32 s19, s19, 0
	s_add_u32 s59, s59, 0x100
	s_addc_u32 s60, s60, 0
	s_cmp_gt_u32 s61, 29
	s_barrier
	s_cbranch_scc0 .LBB0_688
	v_bfe_i32 v254, v144, 0, 1
	v_and_b32_e32 v254, 0xfffff040, v254
	v_bfe_u32 v255, v146, 1, 1
	v_mul_u32_u24_e32 v255, 0xf80, v255
	v_add_u32_e32 v254, v254, v255
	v_and_b32_e32 v255, 1, v146
	v_lshl_add_u32 v254, v255, 6, v254
	v_ashrrev_i32_e32 v255, 31, v254
	v_lshl_add_u64 v[250:251], s[88:89], 0, v[254:255]
	v_lshl_add_u64 v[252:253], s[0:1], 0, v[254:255]
	v_lshl_add_u32 v148, s16, 8, v145
	v_ashrrev_i32_e32 v149, 31, v148
	v_lshl_add_u64 v[150:151], v[148:149], 2, s[28:29]
	global_load_dword v166, v[150:151], off
	v_lshl_or_b32 v150, s56, 7, v152
	v_ashrrev_i32_e32 v151, 31, v150
	v_lshlrev_b64 v[156:157], 11, v[148:149]
	v_lshl_add_u64 v[156:157], v[156:157], 0, v[150:151]
	v_lshlrev_b64 v[164:165], 1, v[156:157]
	v_lshl_add_u64 v[156:157], v[250:251], 0, v[164:165]
	v_lshl_add_u64 v[160:161], v[252:253], 0, v[164:165]
	global_load_dwordx4 v[156:159], v[156:157], off
	s_and_b64 vcc, exec, s[4:5]
	global_load_dwordx4 v[160:163], v[160:161], off
	s_mov_b32 s56, s8
	s_mov_b32 s16, s10
	s_mov_b64 s[20:21], s[14:15]
	s_mov_b64 s[18:19], s[12:13]
	v_add_u32_e32 v244, 0x10, v148
	v_ashrrev_i32_e32 v245, 31, v244
	v_lshl_add_u64 v[246:247], v[244:245], 2, s[28:29]
	global_load_dword v182, v[246:247], off
	v_lshlrev_b64 v[244:245], 11, v[244:245]
	v_lshl_add_u64 v[244:245], v[244:245], 0, v[150:151]
	v_lshlrev_b64 v[244:245], 1, v[244:245]
	v_lshl_add_u64 v[246:247], v[250:251], 0, v[244:245]
	global_load_dwordx4 v[174:177], v[246:247], off
	v_lshl_add_u64 v[246:247], v[252:253], 0, v[244:245]
	global_load_dwordx4 v[178:181], v[246:247], off
	v_add_u32_e32 v244, 0x20, v148
	v_ashrrev_i32_e32 v245, 31, v244
	v_lshl_add_u64 v[246:247], v[244:245], 2, s[28:29]
	global_load_dword v192, v[246:247], off
	v_lshlrev_b64 v[244:245], 11, v[244:245]
	v_lshl_add_u64 v[244:245], v[244:245], 0, v[150:151]
	v_lshlrev_b64 v[244:245], 1, v[244:245]
	v_lshl_add_u64 v[246:247], v[250:251], 0, v[244:245]
	global_load_dwordx4 v[184:187], v[246:247], off
	v_lshl_add_u64 v[246:247], v[252:253], 0, v[244:245]
	global_load_dwordx4 v[188:191], v[246:247], off
	v_add_u32_e32 v244, 0x30, v148
	v_ashrrev_i32_e32 v245, 31, v244
	v_lshl_add_u64 v[246:247], v[244:245], 2, s[28:29]
	global_load_dword v202, v[246:247], off
	v_lshlrev_b64 v[244:245], 11, v[244:245]
	v_lshl_add_u64 v[244:245], v[244:245], 0, v[150:151]
	v_lshlrev_b64 v[244:245], 1, v[244:245]
	v_lshl_add_u64 v[246:247], v[250:251], 0, v[244:245]
	global_load_dwordx4 v[194:197], v[246:247], off
	v_lshl_add_u64 v[246:247], v[252:253], 0, v[244:245]
	global_load_dwordx4 v[198:201], v[246:247], off
	v_add_u32_e32 v244, 0x80, v148
	v_ashrrev_i32_e32 v245, 31, v244
	v_lshl_add_u64 v[246:247], v[244:245], 2, s[28:29]
	global_load_dword v212, v[246:247], off
	v_lshlrev_b64 v[244:245], 11, v[244:245]
	v_lshl_add_u64 v[244:245], v[244:245], 0, v[150:151]
	v_lshlrev_b64 v[244:245], 1, v[244:245]
; __device__ __forceinline__ f32x4 unpk4(uint2 u) { f32x4 r; r[0] = __uint_as_float(u.x << 16); r[1] = __uint_as_float(u.x & 0xffff0000u); r[2] = __uint_as_float(u.y << 16); r[3] = __uint_as_float(u.y & 0xffff0000u); return r; }
; __device__ __forceinline__ float sigm(float x) { return __builtin_amdgcn_rcpf(1.f + __expf(-x)); }
; __device__ __forceinline__ uint4 pk8(f32x4 a, f32x4 b) { return make_uint4(cvt_pk_bf16(a[0], a[1]), cvt_pk_bf16(a[2], a[3]), cvt_pk_bf16(b[0], b[1]), cvt_pk_bf16(b[2], b[3])); }
;     __device__ __forceinline__ void operator()(AccRef acc, const Unit& u, int wr, int wc, int fr, int fq) const {
;     ...
;             for (int m = 0; m < 4; ++m) {
;                 const int r = u.pm * 256 + ai * 128 + wr * 64 + m * 16 + fr;
;                 const float s = rinv[r];
;                 const size_t o = (size_t)r * D + c0;
;                 const uint4 pa8 = *(const uint4*)(Pa + o), pb8 = *(const uint4*)(Pb + o);
;                 f32x4 v[2];
; #pragma unroll
;                 for (int n = 0; n < 2; ++n) {
;                     const f32x4 pa = unpk4(n == 0 ? make_uint2(pa8.x, pa8.y) : make_uint2(pa8.z, pa8.w)), pb = unpk4(n == 0 ? make_uint2(pb8.x, pb8.y) : make_uint2(pb8.z, pb8.w));
; #pragma unroll
;                     for (int e = 0; e < 4; ++e) v[n][e] = sigm(acc[ai][0][m][n][e] * s) * pa[e] + sigm(acc[ai][1][m][n][e] * s) * pb[e];
;                 }
;                 *(uint4*)(O + o) = pk8(v[0], v[1]);
	v_lshl_add_u64 v[246:247], v[250:251], 0, v[244:245]
	global_load_dwordx4 v[204:207], v[246:247], off
	v_lshl_add_u64 v[246:247], v[252:253], 0, v[244:245]
	global_load_dwordx4 v[208:211], v[246:247], off
	v_add_u32_e32 v244, 0x90, v148
	v_ashrrev_i32_e32 v245, 31, v244
	v_lshl_add_u64 v[246:247], v[244:245], 2, s[28:29]
	global_load_dword v222, v[246:247], off
	v_lshlrev_b64 v[244:245], 11, v[244:245]
	v_lshl_add_u64 v[244:245], v[244:245], 0, v[150:151]
	v_lshlrev_b64 v[244:245], 1, v[244:245]
	v_lshl_add_u64 v[246:247], v[250:251], 0, v[244:245]
	global_load_dwordx4 v[214:217], v[246:247], off
	v_lshl_add_u64 v[246:247], v[252:253], 0, v[244:245]
	global_load_dwordx4 v[218:221], v[246:247], off
	v_add_u32_e32 v244, 0xa0, v148
	v_ashrrev_i32_e32 v245, 31, v244
	v_lshl_add_u64 v[246:247], v[244:245], 2, s[28:29]
	global_load_dword v232, v[246:247], off
	v_lshlrev_b64 v[244:245], 11, v[244:245]
	v_lshl_add_u64 v[244:245], v[244:245], 0, v[150:151]
	v_lshlrev_b64 v[244:245], 1, v[244:245]
	v_lshl_add_u64 v[246:247], v[250:251], 0, v[244:245]
	global_load_dwordx4 v[224:227], v[246:247], off
	v_lshl_add_u64 v[246:247], v[252:253], 0, v[244:245]
	global_load_dwordx4 v[228:231], v[246:247], off
	v_add_u32_e32 v244, 0xb0, v148
	v_ashrrev_i32_e32 v245, 31, v244
	v_lshl_add_u64 v[246:247], v[244:245], 2, s[28:29]
	global_load_dword v242, v[246:247], off
	v_lshlrev_b64 v[244:245], 11, v[244:245]
	v_lshl_add_u64 v[244:245], v[244:245], 0, v[150:151]
	v_lshlrev_b64 v[244:245], 1, v[244:245]
	v_lshl_add_u64 v[246:247], v[250:251], 0, v[244:245]
	global_load_dwordx4 v[234:237], v[246:247], off
	v_lshl_add_u64 v[246:247], v[252:253], 0, v[244:245]
	global_load_dwordx4 v[238:241], v[246:247], off
	s_waitcnt vmcnt(21)
	v_mul_f32_e32 v121, v121, v166
	v_mul_f32_e32 v112, v112, v166
	v_mul_f32_e32 v121, 0xbfb8aa3b, v121
	v_mul_f32_e32 v112, 0xbfb8aa3b, v112
	v_exp_f32_e32 v121, v121
	v_exp_f32_e32 v112, v112
	v_mul_f32_e32 v113, v113, v166
	v_mul_f32_e32 v116, v116, v166
	v_mul_f32_e32 v113, 0xbfb8aa3b, v113
	v_add_f32_e32 v121, 1.0, v121
	v_add_f32_e32 v112, 1.0, v112
	v_mul_f32_e32 v116, 0xbfb8aa3b, v116
	v_exp_f32_e32 v113, v113
	v_rcp_f32_e32 v121, v121
	v_rcp_f32_e32 v112, v112
	v_exp_f32_e32 v116, v116
	v_lshlrev_b32_e32 v168, 16, v160
	v_and_b32_e32 v160, 0xffff0000, v160
	v_lshlrev_b32_e32 v172, 16, v162
	v_mul_f32_e32 v121, v121, v160
	v_mul_f32_e32 v160, v112, v172
	v_add_f32_e32 v112, 1.0, v113
	v_mul_f32_e32 v113, v118, v166
	v_add_f32_e32 v116, 1.0, v116
	v_mul_f32_e32 v113, 0xbfb8aa3b, v113
	v_rcp_f32_e32 v116, v116
	v_rcp_f32_e32 v112, v112
	v_exp_f32_e32 v113, v113
	v_mul_f32_e32 v120, v120, v166
	v_lshlrev_b32_e32 v170, 16, v158
	v_and_b32_e32 v162, 0xffff0000, v162
	v_mul_f32_e32 v124, v124, v166
	v_mul_f32_e32 v117, v117, v166
	v_mul_f32_e32 v120, 0xbfb8aa3b, v120
	v_fmac_f32_e32 v160, v116, v170
	v_mul_f32_e32 v116, v112, v162
	v_add_f32_e32 v112, 1.0, v113
	v_mul_f32_e32 v113, v114, v166
	v_mul_f32_e32 v115, v115, v166
	v_mul_f32_e32 v125, v125, v166
	v_mul_f32_e32 v122, v122, v166
	v_mul_f32_e32 v123, v123, v166
	v_mul_f32_e32 v124, 0xbfb8aa3b, v124
	v_mul_f32_e32 v117, 0xbfb8aa3b, v117
	v_exp_f32_e32 v120, v120
	v_mul_f32_e32 v113, 0xbfb8aa3b, v113
	v_mul_f32_e32 v114, v119, v166
	v_mul_f32_e32 v115, 0xbfb8aa3b, v115
	v_mul_f32_e32 v126, v126, v166
	v_mul_f32_e32 v127, v127, v166
	v_mul_f32_e32 v125, 0xbfb8aa3b, v125
	v_mul_f32_e32 v122, 0xbfb8aa3b, v122
	v_mul_f32_e32 v123, 0xbfb8aa3b, v123
	v_exp_f32_e32 v124, v124
	v_exp_f32_e32 v117, v117
	v_exp_f32_e32 v113, v113
	v_mul_f32_e32 v114, 0xbfb8aa3b, v114
	v_exp_f32_e32 v115, v115
	v_mul_f32_e32 v126, 0xbfb8aa3b, v126
	v_mul_f32_e32 v127, 0xbfb8aa3b, v127
	v_exp_f32_e32 v125, v125
	v_exp_f32_e32 v122, v122
	v_exp_f32_e32 v123, v123
	v_exp_f32_e32 v114, v114
	v_exp_f32_e32 v126, v126
	v_exp_f32_e32 v127, v127
	v_add_f32_e32 v120, 1.0, v120
	v_add_f32_e32 v124, 1.0, v124
	v_add_f32_e32 v117, 1.0, v117
	v_rcp_f32_e32 v120, v120
	v_add_f32_e32 v113, 1.0, v113
	v_add_f32_e32 v115, 1.0, v115
	v_add_f32_e32 v125, 1.0, v125
	v_add_f32_e32 v122, 1.0, v122
	v_add_f32_e32 v123, 1.0, v123
	v_rcp_f32_e32 v124, v124
	v_rcp_f32_e32 v117, v117
	v_rcp_f32_e32 v113, v113
	v_add_f32_e32 v114, 1.0, v114
	v_rcp_f32_e32 v115, v115
	v_add_f32_e32 v126, 1.0, v126
	v_add_f32_e32 v127, 1.0, v127
	v_rcp_f32_e32 v125, v125
	v_rcp_f32_e32 v122, v122
	v_rcp_f32_e32 v123, v123
	v_rcp_f32_e32 v112, v112
	v_rcp_f32_e32 v114, v114
	v_rcp_f32_e32 v126, v126
	v_rcp_f32_e32 v127, v127
	v_lshlrev_b32_e32 v149, 16, v156
	v_and_b32_e32 v158, 0xffff0000, v158
	v_lshlrev_b32_e32 v173, 16, v163
	v_and_b32_e32 v163, 0xffff0000, v163
	v_mul_f32_e32 v120, v120, v168
	v_and_b32_e32 v156, 0xffff0000, v156
	v_lshlrev_b32_e32 v169, 16, v161
	v_and_b32_e32 v161, 0xffff0000, v161
	v_lshlrev_b32_e32 v171, 16, v159
	v_and_b32_e32 v159, 0xffff0000, v159
	v_fmac_f32_e32 v120, v124, v149
	v_fmac_f32_e32 v116, v117, v158
	v_mul_f32_e32 v117, v113, v173
	v_mul_f32_e32 v115, v115, v163
	v_lshlrev_b32_e32 v167, 16, v157
	v_and_b32_e32 v157, 0xffff0000, v157
	v_mul_f32_e32 v122, v122, v169
	v_mul_f32_e32 v123, v123, v161
	v_fmac_f32_e32 v121, v125, v156
	v_fmac_f32_e32 v117, v112, v171
	v_fmac_f32_e32 v115, v114, v159
	v_cvt_pk_bf16_f32 v112, v120, v121
	v_or_b32_e32 v120, 16, v148
	v_fmac_f32_e32 v122, v126, v167
	v_fmac_f32_e32 v123, v127, v157
	v_cvt_pk_bf16_f32 v113, v122, v123
	v_cvt_pk_bf16_f32 v114, v160, v116
	v_cvt_pk_bf16_f32 v115, v117, v115
	v_lshl_add_u64 v[116:117], s[36:37], 0, v[164:165]
	v_ashrrev_i32_e32 v121, 31, v120
	global_store_dwordx4 v[116:117], v[112:115], off
	s_nop 1
	v_lshlrev_b64 v[112:113], 11, v[120:121]
	v_lshl_add_u64 v[120:121], v[120:121], 2, s[28:29]
	v_lshl_add_u64 v[112:113], v[112:113], 0, v[150:151]
	v_lshlrev_b64 v[122:123], 1, v[112:113]
	v_lshl_add_u64 v[112:113], s[88:89], 0, v[122:123]
	v_lshl_add_u64 v[116:117], s[0:1], 0, v[122:123]
	s_waitcnt vmcnt(19)
; __device__ __forceinline__ f32x4 unpk4(uint2 u) { f32x4 r; r[0] = __uint_as_float(u.x << 16); r[1] = __uint_as_float(u.x & 0xffff0000u); r[2] = __uint_as_float(u.y << 16); r[3] = __uint_as_float(u.y & 0xffff0000u); return r; }
; __device__ __forceinline__ float sigm(float x) { return __builtin_amdgcn_rcpf(1.f + __expf(-x)); }
;     __device__ __forceinline__ void operator()(AccRef acc, const Unit& u, int wr, int wc, int fr, int fq) const {
;     ...
; #pragma unroll
;                 for (int n = 0; n < 2; ++n) {
;                     const f32x4 pa = unpk4(n == 0 ? make_uint2(pa8.x, pa8.y) : make_uint2(pa8.z, pa8.w)), pb = unpk4(n == 0 ? make_uint2(pb8.x, pb8.y) : make_uint2(pb8.z, pb8.w));
; #pragma unroll
;                     for (int e = 0; e < 4; ++e) v[n][e] = sigm(acc[ai][0][m][n][e] * s) * pa[e] + sigm(acc[ai][1][m][n][e] * s) * pb[e];
;                 }
	v_mul_f32_e32 v104, v104, v182
	v_mul_f32_e32 v108, v108, v182
	v_mul_f32_e32 v104, 0xbfb8aa3b, v104
	v_mul_f32_e32 v108, 0xbfb8aa3b, v108
	v_exp_f32_e32 v104, v104
	v_mul_f32_e32 v105, v105, v182
	v_exp_f32_e32 v108, v108
	v_mul_f32_e32 v109, v109, v182
	v_mul_f32_e32 v107, v107, v182
	v_mul_f32_e32 v105, 0xbfb8aa3b, v105
	v_mul_f32_e32 v111, v111, v182
	v_mul_f32_e32 v109, 0xbfb8aa3b, v109
	v_mul_f32_e32 v107, 0xbfb8aa3b, v107
	v_exp_f32_e32 v105, v105
	v_mul_f32_e32 v96, v96, v182
	v_mul_f32_e32 v111, 0xbfb8aa3b, v111
	v_exp_f32_e32 v109, v109
	v_exp_f32_e32 v107, v107
	v_add_f32_e32 v104, 1.0, v104
	v_mul_f32_e32 v100, v100, v182
	v_mul_f32_e32 v96, 0xbfb8aa3b, v96
	v_mul_f32_e32 v97, v97, v182
	v_exp_f32_e32 v111, v111
	v_add_f32_e32 v108, 1.0, v108
	v_rcp_f32_e32 v104, v104
	v_mul_f32_e32 v100, 0xbfb8aa3b, v100
	v_exp_f32_e32 v96, v96
	v_mul_f32_e32 v97, 0xbfb8aa3b, v97
	v_rcp_f32_e32 v108, v108
	v_exp_f32_e32 v100, v100
	v_exp_f32_e32 v97, v97
	v_add_f32_e32 v105, 1.0, v105
	v_add_f32_e32 v109, 1.0, v109
	v_rcp_f32_e32 v105, v105
	v_add_f32_e32 v107, 1.0, v107
	v_lshlrev_b32_e32 v121, 16, v174
	v_add_f32_e32 v111, 1.0, v111
	v_rcp_f32_e32 v109, v109
	v_rcp_f32_e32 v107, v107
	v_add_f32_e32 v96, 1.0, v96
	v_add_f32_e32 v100, 1.0, v100
	v_rcp_f32_e32 v96, v96
	v_mul_f32_e32 v101, v101, v182
	v_add_f32_e32 v97, 1.0, v97
	v_rcp_f32_e32 v100, v100
	v_mul_f32_e32 v101, 0xbfb8aa3b, v101
	v_rcp_f32_e32 v97, v97
	v_and_b32_e32 v174, 0xffff0000, v174
	v_exp_f32_e32 v101, v101
	v_lshlrev_b32_e32 v124, 16, v175
	v_and_b32_e32 v175, 0xffff0000, v175
	v_mul_f32_e32 v106, v106, v182
	v_mul_f32_e32 v110, v110, v182
	v_mul_f32_e32 v106, 0xbfb8aa3b, v106
	v_mul_f32_e32 v110, 0xbfb8aa3b, v110
	v_exp_f32_e32 v106, v106
	v_mul_f32_e32 v99, v99, v182
	v_exp_f32_e32 v110, v110
	v_mul_f32_e32 v99, 0xbfb8aa3b, v99
	v_exp_f32_e32 v99, v99
	v_add_f32_e32 v106, 1.0, v106
	v_add_f32_e32 v110, 1.0, v110
	v_rcp_f32_e32 v106, v106
	v_rcp_f32_e32 v110, v110
	v_add_f32_e32 v99, 1.0, v99
	v_rcp_f32_e32 v99, v99
	s_waitcnt vmcnt(19)
	v_lshlrev_b32_e32 v125, 16, v178
	v_mul_f32_e32 v104, v104, v125
	v_fmac_f32_e32 v104, v108, v121
	v_rcp_f32_e32 v108, v111
	v_and_b32_e32 v178, 0xffff0000, v178
	v_lshlrev_b32_e32 v126, 16, v179
	v_and_b32_e32 v179, 0xffff0000, v179
	v_mul_f32_e32 v105, v105, v178
	v_fmac_f32_e32 v105, v109, v174
	v_mul_f32_e32 v107, v107, v179
	v_lshlrev_b32_e32 v174, 16, v180
	v_fmac_f32_e32 v107, v108, v175
	v_lshlrev_b32_e32 v108, 16, v176
	v_and_b32_e32 v175, 0xffff0000, v180
	v_mul_f32_e32 v174, v96, v174
	v_fmac_f32_e32 v174, v100, v108
	v_mul_f32_e32 v100, v97, v175
	v_mul_f32_e32 v97, v98, v182
	v_add_f32_e32 v96, 1.0, v101
	v_mul_f32_e32 v101, v102, v182
	v_mul_f32_e32 v97, 0xbfb8aa3b, v97
	v_mul_f32_e32 v98, v103, v182
	v_mul_f32_e32 v101, 0xbfb8aa3b, v101
	v_exp_f32_e32 v97, v97
	v_mul_f32_e32 v98, 0xbfb8aa3b, v98
	v_rcp_f32_e32 v96, v96
	v_exp_f32_e32 v101, v101
	v_exp_f32_e32 v98, v98
	v_and_b32_e32 v109, 0xffff0000, v176
	v_add_f32_e32 v97, 1.0, v97
	v_fmac_f32_e32 v100, v96, v109
	v_add_f32_e32 v96, 1.0, v101
	v_rcp_f32_e32 v97, v97
	v_add_f32_e32 v98, 1.0, v98
	v_rcp_f32_e32 v96, v96
	v_rcp_f32_e32 v98, v98
	v_mul_f32_e32 v106, v106, v126
	v_fmac_f32_e32 v106, v110, v124
	v_lshlrev_b32_e32 v110, 16, v177
	v_and_b32_e32 v111, 0xffff0000, v177
	v_lshlrev_b32_e32 v176, 16, v181
	v_and_b32_e32 v177, 0xffff0000, v181
	v_mul_f32_e32 v101, v97, v176
	v_mul_f32_e32 v99, v99, v177
	v_fmac_f32_e32 v101, v96, v110
	v_fmac_f32_e32 v99, v98, v111

; __device__ __forceinline__ unsigned cvt_pk_bf16(float lo, float hi) { unsigned r; asm volatile("v_cvt_pk_bf16_f32 %0, %1, %2" : "=v"(r) : "v"(lo), "v"(hi)); return r; }
; __device__ __forceinline__ uint4 pk8(f32x4 a, f32x4 b) { return make_uint4(cvt_pk_bf16(a[0], a[1]), cvt_pk_bf16(a[2], a[3]), cvt_pk_bf16(b[0], b[1]), cvt_pk_bf16(b[2], b[3])); }
	v_cvt_pk_bf16_f32 v96, v104, v105

;     __device__ __forceinline__ void operator()(AccRef acc, const Unit& u, int wr, int wc, int fr, int fq) const {
;     ...
;                 const int r = u.pm * 256 + ai * 128 + wr * 64 + m * 16 + fr;
	v_or_b32_e32 v104, 32, v148

; __device__ __forceinline__ unsigned cvt_pk_bf16(float lo, float hi) { unsigned r; asm volatile("v_cvt_pk_bf16_f32 %0, %1, %2" : "=v"(r) : "v"(lo), "v"(hi)); return r; }
; __device__ __forceinline__ uint4 pk8(f32x4 a, f32x4 b) { return make_uint4(cvt_pk_bf16(a[0], a[1]), cvt_pk_bf16(a[2], a[3]), cvt_pk_bf16(b[0], b[1]), cvt_pk_bf16(b[2], b[3])); }
	v_cvt_pk_bf16_f32 v97, v106, v107


; __device__ __forceinline__ unsigned cvt_pk_bf16(float lo, float hi) { unsigned r; asm volatile("v_cvt_pk_bf16_f32 %0, %1, %2" : "=v"(r) : "v"(lo), "v"(hi)); return r; }
; __device__ __forceinline__ uint4 pk8(f32x4 a, f32x4 b) { return make_uint4(cvt_pk_bf16(a[0], a[1]), cvt_pk_bf16(a[2], a[3]), cvt_pk_bf16(b[0], b[1]), cvt_pk_bf16(b[2], b[3])); }
	v_cvt_pk_bf16_f32 v98, v174, v100


; __device__ __forceinline__ unsigned cvt_pk_bf16(float lo, float hi) { unsigned r; asm volatile("v_cvt_pk_bf16_f32 %0, %1, %2" : "=v"(r) : "v"(lo), "v"(hi)); return r; }
; __device__ __forceinline__ uint4 pk8(f32x4 a, f32x4 b) { return make_uint4(cvt_pk_bf16(a[0], a[1]), cvt_pk_bf16(a[2], a[3]), cvt_pk_bf16(b[0], b[1]), cvt_pk_bf16(b[2], b[3])); }
	v_cvt_pk_bf16_f32 v99, v101, v99

; __device__ __forceinline__ f32x4 unpk4(uint2 u) { f32x4 r; r[0] = __uint_as_float(u.x << 16); r[1] = __uint_as_float(u.x & 0xffff0000u); r[2] = __uint_as_float(u.y << 16); r[3] = __uint_as_float(u.y & 0xffff0000u); return r; }
; __device__ __forceinline__ float sigm(float x) { return __builtin_amdgcn_rcpf(1.f + __expf(-x)); }
; __device__ __forceinline__ uint4 pk8(f32x4 a, f32x4 b) { return make_uint4(cvt_pk_bf16(a[0], a[1]), cvt_pk_bf16(a[2], a[3]), cvt_pk_bf16(b[0], b[1]), cvt_pk_bf16(b[2], b[3])); }
;     __device__ __forceinline__ void operator()(AccRef acc, const Unit& u, int wr, int wc, int fr, int fq) const {
;     ...
;             for (int m = 0; m < 4; ++m) {
;                 const int r = u.pm * 256 + ai * 128 + wr * 64 + m * 16 + fr;
;                 const float s = rinv[r];
;                 const size_t o = (size_t)r * D + c0;
;                 const uint4 pa8 = *(const uint4*)(Pa + o), pb8 = *(const uint4*)(Pb + o);
;                 f32x4 v[2];
; #pragma unroll
;                 for (int n = 0; n < 2; ++n) {
;                     const f32x4 pa = unpk4(n == 0 ? make_uint2(pa8.x, pa8.y) : make_uint2(pa8.z, pa8.w)), pb = unpk4(n == 0 ? make_uint2(pb8.x, pb8.y) : make_uint2(pb8.z, pb8.w));
; #pragma unroll
;                     for (int e = 0; e < 4; ++e) v[n][e] = sigm(acc[ai][0][m][n][e] * s) * pa[e] + sigm(acc[ai][1][m][n][e] * s) * pb[e];
;                 }
;                 *(uint4*)(O + o) = pk8(v[0], v[1]);
	v_lshl_add_u64 v[100:101], s[36:37], 0, v[122:123]
	v_ashrrev_i32_e32 v105, 31, v104
	global_store_dwordx4 v[100:101], v[96:99], off
	s_nop 1
	v_lshlrev_b64 v[96:97], 11, v[104:105]
	v_lshl_add_u64 v[104:105], v[104:105], 2, s[28:29]
	v_lshl_add_u64 v[96:97], v[96:97], 0, v[150:151]
	v_lshlrev_b64 v[106:107], 1, v[96:97]
	v_lshl_add_u64 v[96:97], s[88:89], 0, v[106:107]
	v_lshl_add_u64 v[100:101], s[0:1], 0, v[106:107]
	s_waitcnt vmcnt(17)
	v_mul_f32_e32 v89, v89, v192
	v_mul_f32_e32 v93, v93, v192
	v_mul_f32_e32 v89, 0xbfb8aa3b, v89
	v_mul_f32_e32 v93, 0xbfb8aa3b, v93
	v_exp_f32_e32 v89, v89
	v_exp_f32_e32 v93, v93
	v_mul_f32_e32 v88, v88, v192
	v_mul_f32_e32 v92, v92, v192
	v_add_f32_e32 v89, 1.0, v89
	v_mul_f32_e32 v88, 0xbfb8aa3b, v88
	v_add_f32_e32 v93, 1.0, v93
	v_rcp_f32_e32 v89, v89
	v_mul_f32_e32 v92, 0xbfb8aa3b, v92
	v_exp_f32_e32 v88, v88
	v_rcp_f32_e32 v93, v93
	v_exp_f32_e32 v92, v92
	v_lshlrev_b32_e32 v105, 16, v184
	v_and_b32_e32 v184, 0xffff0000, v184
	v_mul_f32_e32 v90, v90, v192
	v_mul_f32_e32 v91, v91, v192
	v_add_f32_e32 v88, 1.0, v88
	v_mul_f32_e32 v94, v94, v192
	v_mul_f32_e32 v90, 0xbfb8aa3b, v90
	v_mul_f32_e32 v91, 0xbfb8aa3b, v91
	v_mul_f32_e32 v80, v80, v192
	v_add_f32_e32 v92, 1.0, v92
	v_rcp_f32_e32 v88, v88
	v_mul_f32_e32 v94, 0xbfb8aa3b, v94
	v_exp_f32_e32 v90, v90
	v_exp_f32_e32 v91, v91
	v_mul_f32_e32 v84, v84, v192
	v_mul_f32_e32 v80, 0xbfb8aa3b, v80
	v_mul_f32_e32 v81, v81, v192
	v_rcp_f32_e32 v92, v92
	v_exp_f32_e32 v94, v94
	v_mul_f32_e32 v84, 0xbfb8aa3b, v84
	v_exp_f32_e32 v80, v80
	v_mul_f32_e32 v81, 0xbfb8aa3b, v81
	v_exp_f32_e32 v84, v84
	v_exp_f32_e32 v81, v81
	v_add_f32_e32 v90, 1.0, v90
	v_add_f32_e32 v91, 1.0, v91
	v_rcp_f32_e32 v90, v90
	v_rcp_f32_e32 v91, v91
	v_add_f32_e32 v80, 1.0, v80
	v_add_f32_e32 v84, 1.0, v84
	v_rcp_f32_e32 v80, v80
	v_mul_f32_e32 v85, v85, v192
	v_add_f32_e32 v81, 1.0, v81
	v_rcp_f32_e32 v84, v84
	v_mul_f32_e32 v85, 0xbfb8aa3b, v85
	v_rcp_f32_e32 v81, v81
	v_exp_f32_e32 v85, v85
	v_lshlrev_b32_e32 v108, 16, v185
	v_and_b32_e32 v185, 0xffff0000, v185
	v_mul_f32_e32 v83, v83, v192
	v_mul_f32_e32 v83, 0xbfb8aa3b, v83
	v_exp_f32_e32 v83, v83
	s_waitcnt vmcnt(17)
	v_lshlrev_b32_e32 v109, 16, v188
	v_and_b32_e32 v188, 0xffff0000, v188
	v_mul_f32_e32 v89, v89, v188
	v_fmac_f32_e32 v89, v93, v184
	v_mul_f32_e32 v93, v95, v192
	v_mul_f32_e32 v93, 0xbfb8aa3b, v93
	v_exp_f32_e32 v93, v93
	v_mul_f32_e32 v88, v88, v109
	v_fmac_f32_e32 v88, v92, v105
	v_add_f32_e32 v92, 1.0, v94
	v_add_f32_e32 v93, 1.0, v93
	v_rcp_f32_e32 v92, v92
	v_rcp_f32_e32 v93, v93
	v_lshlrev_b32_e32 v110, 16, v189
	v_and_b32_e32 v189, 0xffff0000, v189
	v_mul_f32_e32 v90, v90, v110
	v_mul_f32_e32 v91, v91, v189
	v_lshlrev_b32_e32 v184, 16, v190
	v_fmac_f32_e32 v90, v92, v108
	v_fmac_f32_e32 v91, v93, v185
	v_lshlrev_b32_e32 v92, 16, v186
	v_and_b32_e32 v185, 0xffff0000, v190
	v_mul_f32_e32 v184, v80, v184
	v_fmac_f32_e32 v184, v84, v92
	v_mul_f32_e32 v84, v81, v185
	v_mul_f32_e32 v81, v82, v192
	v_add_f32_e32 v80, 1.0, v85
	v_mul_f32_e32 v85, v86, v192
	v_mul_f32_e32 v81, 0xbfb8aa3b, v81
	v_mul_f32_e32 v82, v87, v192
	v_mul_f32_e32 v85, 0xbfb8aa3b, v85
	v_exp_f32_e32 v81, v81
	v_mul_f32_e32 v82, 0xbfb8aa3b, v82
	v_rcp_f32_e32 v80, v80
	v_exp_f32_e32 v85, v85
	v_exp_f32_e32 v82, v82
	v_and_b32_e32 v93, 0xffff0000, v186
	v_add_f32_e32 v81, 1.0, v81
	v_add_f32_e32 v83, 1.0, v83
	v_fmac_f32_e32 v84, v80, v93
	v_add_f32_e32 v80, 1.0, v85
	v_rcp_f32_e32 v81, v81
	v_add_f32_e32 v82, 1.0, v82
	v_rcp_f32_e32 v83, v83
	v_rcp_f32_e32 v80, v80
	v_rcp_f32_e32 v82, v82
	v_lshlrev_b32_e32 v94, 16, v187
	v_and_b32_e32 v95, 0xffff0000, v187
	v_lshlrev_b32_e32 v186, 16, v191
	v_and_b32_e32 v187, 0xffff0000, v191
	v_mul_f32_e32 v85, v81, v186
	v_mul_f32_e32 v83, v83, v187
	v_fmac_f32_e32 v85, v80, v94
	v_fmac_f32_e32 v83, v82, v95

; __device__ __forceinline__ unsigned cvt_pk_bf16(float lo, float hi) { unsigned r; asm volatile("v_cvt_pk_bf16_f32 %0, %1, %2" : "=v"(r) : "v"(lo), "v"(hi)); return r; }
; __device__ __forceinline__ uint4 pk8(f32x4 a, f32x4 b) { return make_uint4(cvt_pk_bf16(a[0], a[1]), cvt_pk_bf16(a[2], a[3]), cvt_pk_bf16(b[0], b[1]), cvt_pk_bf16(b[2], b[3])); }
	v_cvt_pk_bf16_f32 v80, v88, v89

;     __device__ __forceinline__ void operator()(AccRef acc, const Unit& u, int wr, int wc, int fr, int fq) const {
;     ...
;                 const int r = u.pm * 256 + ai * 128 + wr * 64 + m * 16 + fr;
	v_or_b32_e32 v88, 48, v148

; __device__ __forceinline__ unsigned cvt_pk_bf16(float lo, float hi) { unsigned r; asm volatile("v_cvt_pk_bf16_f32 %0, %1, %2" : "=v"(r) : "v"(lo), "v"(hi)); return r; }
; __device__ __forceinline__ uint4 pk8(f32x4 a, f32x4 b) { return make_uint4(cvt_pk_bf16(a[0], a[1]), cvt_pk_bf16(a[2], a[3]), cvt_pk_bf16(b[0], b[1]), cvt_pk_bf16(b[2], b[3])); }
	v_cvt_pk_bf16_f32 v81, v90, v91


; __device__ __forceinline__ unsigned cvt_pk_bf16(float lo, float hi) { unsigned r; asm volatile("v_cvt_pk_bf16_f32 %0, %1, %2" : "=v"(r) : "v"(lo), "v"(hi)); return r; }
; __device__ __forceinline__ uint4 pk8(f32x4 a, f32x4 b) { return make_uint4(cvt_pk_bf16(a[0], a[1]), cvt_pk_bf16(a[2], a[3]), cvt_pk_bf16(b[0], b[1]), cvt_pk_bf16(b[2], b[3])); }
	v_cvt_pk_bf16_f32 v82, v184, v84


; __device__ __forceinline__ unsigned cvt_pk_bf16(float lo, float hi) { unsigned r; asm volatile("v_cvt_pk_bf16_f32 %0, %1, %2" : "=v"(r) : "v"(lo), "v"(hi)); return r; }
; __device__ __forceinline__ uint4 pk8(f32x4 a, f32x4 b) { return make_uint4(cvt_pk_bf16(a[0], a[1]), cvt_pk_bf16(a[2], a[3]), cvt_pk_bf16(b[0], b[1]), cvt_pk_bf16(b[2], b[3])); }
	v_cvt_pk_bf16_f32 v83, v85, v83

; __device__ __forceinline__ f32x4 unpk4(uint2 u) { f32x4 r; r[0] = __uint_as_float(u.x << 16); r[1] = __uint_as_float(u.x & 0xffff0000u); r[2] = __uint_as_float(u.y << 16); r[3] = __uint_as_float(u.y & 0xffff0000u); return r; }
; __device__ __forceinline__ float sigm(float x) { return __builtin_amdgcn_rcpf(1.f + __expf(-x)); }
; __device__ __forceinline__ uint4 pk8(f32x4 a, f32x4 b) { return make_uint4(cvt_pk_bf16(a[0], a[1]), cvt_pk_bf16(a[2], a[3]), cvt_pk_bf16(b[0], b[1]), cvt_pk_bf16(b[2], b[3])); }
;     __device__ __forceinline__ void operator()(AccRef acc, const Unit& u, int wr, int wc, int fr, int fq) const {
;     ...
;             for (int m = 0; m < 4; ++m) {
;                 const int r = u.pm * 256 + ai * 128 + wr * 64 + m * 16 + fr;
;                 const float s = rinv[r];
;                 const size_t o = (size_t)r * D + c0;
;                 const uint4 pa8 = *(const uint4*)(Pa + o), pb8 = *(const uint4*)(Pb + o);
;                 f32x4 v[2];
; #pragma unroll
;                 for (int n = 0; n < 2; ++n) {
;                     const f32x4 pa = unpk4(n == 0 ? make_uint2(pa8.x, pa8.y) : make_uint2(pa8.z, pa8.w)), pb = unpk4(n == 0 ? make_uint2(pb8.x, pb8.y) : make_uint2(pb8.z, pb8.w));
; #pragma unroll
;                     for (int e = 0; e < 4; ++e) v[n][e] = sigm(acc[ai][0][m][n][e] * s) * pa[e] + sigm(acc[ai][1][m][n][e] * s) * pb[e];
;                 }
;                 *(uint4*)(O + o) = pk8(v[0], v[1]);
	v_lshl_add_u64 v[84:85], s[36:37], 0, v[106:107]
	v_ashrrev_i32_e32 v89, 31, v88
	global_store_dwordx4 v[84:85], v[80:83], off
	s_nop 1
	v_lshlrev_b64 v[80:81], 11, v[88:89]
	v_lshl_add_u64 v[88:89], v[88:89], 2, s[28:29]
	v_lshl_add_u64 v[80:81], v[80:81], 0, v[150:151]
	v_lshlrev_b64 v[90:91], 1, v[80:81]
	v_lshl_add_u64 v[80:81], s[88:89], 0, v[90:91]
	v_lshl_add_u64 v[84:85], s[0:1], 0, v[90:91]
	s_waitcnt vmcnt(15)
	v_mul_f32_e32 v73, v73, v202
	v_mul_f32_e32 v77, v77, v202
	v_mul_f32_e32 v73, 0xbfb8aa3b, v73
	v_mul_f32_e32 v77, 0xbfb8aa3b, v77
	v_exp_f32_e32 v73, v73
	v_exp_f32_e32 v77, v77
	v_mul_f32_e32 v72, v72, v202
	v_mul_f32_e32 v76, v76, v202
	v_add_f32_e32 v73, 1.0, v73
	v_mul_f32_e32 v72, 0xbfb8aa3b, v72
	v_add_f32_e32 v77, 1.0, v77
	v_rcp_f32_e32 v73, v73
	v_mul_f32_e32 v76, 0xbfb8aa3b, v76
	v_exp_f32_e32 v72, v72
	v_rcp_f32_e32 v77, v77
	v_exp_f32_e32 v76, v76
	v_lshlrev_b32_e32 v89, 16, v194
	v_and_b32_e32 v194, 0xffff0000, v194
	v_mul_f32_e32 v74, v74, v202
	v_mul_f32_e32 v75, v75, v202
	v_add_f32_e32 v72, 1.0, v72
	v_mul_f32_e32 v78, v78, v202
	v_mul_f32_e32 v74, 0xbfb8aa3b, v74
	v_mul_f32_e32 v75, 0xbfb8aa3b, v75
	v_mul_f32_e32 v64, v64, v202
	v_add_f32_e32 v76, 1.0, v76
	v_rcp_f32_e32 v72, v72
	v_mul_f32_e32 v78, 0xbfb8aa3b, v78
	v_exp_f32_e32 v74, v74
	v_exp_f32_e32 v75, v75
	v_mul_f32_e32 v68, v68, v202
	v_mul_f32_e32 v64, 0xbfb8aa3b, v64
	v_mul_f32_e32 v65, v65, v202
	v_rcp_f32_e32 v76, v76
	v_exp_f32_e32 v78, v78
	v_mul_f32_e32 v68, 0xbfb8aa3b, v68
	v_exp_f32_e32 v64, v64
	v_mul_f32_e32 v65, 0xbfb8aa3b, v65
	v_exp_f32_e32 v68, v68
	v_exp_f32_e32 v65, v65
	v_add_f32_e32 v74, 1.0, v74
	v_add_f32_e32 v75, 1.0, v75
	v_rcp_f32_e32 v74, v74
	v_rcp_f32_e32 v75, v75
	v_add_f32_e32 v64, 1.0, v64
	v_add_f32_e32 v68, 1.0, v68
	v_rcp_f32_e32 v64, v64
	v_mul_f32_e32 v69, v69, v202
	v_add_f32_e32 v65, 1.0, v65
	v_rcp_f32_e32 v68, v68
	v_mul_f32_e32 v69, 0xbfb8aa3b, v69
	v_rcp_f32_e32 v65, v65
	v_exp_f32_e32 v69, v69
	v_lshlrev_b32_e32 v92, 16, v195
	v_and_b32_e32 v195, 0xffff0000, v195
	v_mul_f32_e32 v67, v67, v202
	v_mul_f32_e32 v67, 0xbfb8aa3b, v67
	v_exp_f32_e32 v67, v67
	s_waitcnt vmcnt(15)
	v_lshlrev_b32_e32 v93, 16, v198
	v_and_b32_e32 v198, 0xffff0000, v198
	v_mul_f32_e32 v73, v73, v198
	v_fmac_f32_e32 v73, v77, v194
	v_mul_f32_e32 v77, v79, v202
	v_mul_f32_e32 v77, 0xbfb8aa3b, v77
	v_exp_f32_e32 v77, v77
	v_mul_f32_e32 v72, v72, v93
	v_fmac_f32_e32 v72, v76, v89
	v_add_f32_e32 v76, 1.0, v78
	v_add_f32_e32 v77, 1.0, v77
	v_rcp_f32_e32 v76, v76
	v_rcp_f32_e32 v77, v77
	v_lshlrev_b32_e32 v94, 16, v199
	v_and_b32_e32 v199, 0xffff0000, v199
	v_mul_f32_e32 v74, v74, v94
	v_mul_f32_e32 v75, v75, v199
	v_lshlrev_b32_e32 v194, 16, v200
	v_fmac_f32_e32 v74, v76, v92
	v_fmac_f32_e32 v75, v77, v195
	v_lshlrev_b32_e32 v76, 16, v196
	v_and_b32_e32 v195, 0xffff0000, v200
	v_mul_f32_e32 v194, v64, v194
	v_fmac_f32_e32 v194, v68, v76
	v_mul_f32_e32 v68, v65, v195
	v_mul_f32_e32 v65, v66, v202
	v_add_f32_e32 v64, 1.0, v69
	v_mul_f32_e32 v69, v70, v202
	v_mul_f32_e32 v65, 0xbfb8aa3b, v65
	v_mul_f32_e32 v66, v71, v202
	v_mul_f32_e32 v69, 0xbfb8aa3b, v69
	v_exp_f32_e32 v65, v65
	v_mul_f32_e32 v66, 0xbfb8aa3b, v66
	v_rcp_f32_e32 v64, v64
	v_exp_f32_e32 v69, v69
	v_exp_f32_e32 v66, v66
	v_and_b32_e32 v77, 0xffff0000, v196
	v_add_f32_e32 v65, 1.0, v65
	v_add_f32_e32 v67, 1.0, v67
	v_fmac_f32_e32 v68, v64, v77
	v_add_f32_e32 v64, 1.0, v69
	v_rcp_f32_e32 v65, v65
	v_add_f32_e32 v66, 1.0, v66
	v_rcp_f32_e32 v67, v67
	v_rcp_f32_e32 v64, v64
	v_rcp_f32_e32 v66, v66
	v_lshlrev_b32_e32 v78, 16, v197
	v_and_b32_e32 v79, 0xffff0000, v197
	v_lshlrev_b32_e32 v196, 16, v201
	v_and_b32_e32 v197, 0xffff0000, v201
	v_mul_f32_e32 v69, v65, v196
	v_mul_f32_e32 v67, v67, v197
	v_fmac_f32_e32 v69, v64, v78
	v_fmac_f32_e32 v67, v66, v79

; __device__ __forceinline__ unsigned cvt_pk_bf16(float lo, float hi) { unsigned r; asm volatile("v_cvt_pk_bf16_f32 %0, %1, %2" : "=v"(r) : "v"(lo), "v"(hi)); return r; }
; __device__ __forceinline__ uint4 pk8(f32x4 a, f32x4 b) { return make_uint4(cvt_pk_bf16(a[0], a[1]), cvt_pk_bf16(a[2], a[3]), cvt_pk_bf16(b[0], b[1]), cvt_pk_bf16(b[2], b[3])); }
	v_cvt_pk_bf16_f32 v64, v72, v73

;     __device__ __forceinline__ void operator()(AccRef acc, const Unit& u, int wr, int wc, int fr, int fq) const {
;     ...
;                 const int r = u.pm * 256 + ai * 128 + wr * 64 + m * 16 + fr;
	v_add_u32_e32 v72, 0x80, v148

; __device__ __forceinline__ unsigned cvt_pk_bf16(float lo, float hi) { unsigned r; asm volatile("v_cvt_pk_bf16_f32 %0, %1, %2" : "=v"(r) : "v"(lo), "v"(hi)); return r; }
; __device__ __forceinline__ uint4 pk8(f32x4 a, f32x4 b) { return make_uint4(cvt_pk_bf16(a[0], a[1]), cvt_pk_bf16(a[2], a[3]), cvt_pk_bf16(b[0], b[1]), cvt_pk_bf16(b[2], b[3])); }
	v_cvt_pk_bf16_f32 v65, v74, v75


; __device__ __forceinline__ unsigned cvt_pk_bf16(float lo, float hi) { unsigned r; asm volatile("v_cvt_pk_bf16_f32 %0, %1, %2" : "=v"(r) : "v"(lo), "v"(hi)); return r; }
; __device__ __forceinline__ uint4 pk8(f32x4 a, f32x4 b) { return make_uint4(cvt_pk_bf16(a[0], a[1]), cvt_pk_bf16(a[2], a[3]), cvt_pk_bf16(b[0], b[1]), cvt_pk_bf16(b[2], b[3])); }
	v_cvt_pk_bf16_f32 v66, v194, v68


; __device__ __forceinline__ unsigned cvt_pk_bf16(float lo, float hi) { unsigned r; asm volatile("v_cvt_pk_bf16_f32 %0, %1, %2" : "=v"(r) : "v"(lo), "v"(hi)); return r; }
; __device__ __forceinline__ uint4 pk8(f32x4 a, f32x4 b) { return make_uint4(cvt_pk_bf16(a[0], a[1]), cvt_pk_bf16(a[2], a[3]), cvt_pk_bf16(b[0], b[1]), cvt_pk_bf16(b[2], b[3])); }
	v_cvt_pk_bf16_f32 v67, v69, v67

; __device__ __forceinline__ f32x4 unpk4(uint2 u) { f32x4 r; r[0] = __uint_as_float(u.x << 16); r[1] = __uint_as_float(u.x & 0xffff0000u); r[2] = __uint_as_float(u.y << 16); r[3] = __uint_as_float(u.y & 0xffff0000u); return r; }
; __device__ __forceinline__ float sigm(float x) { return __builtin_amdgcn_rcpf(1.f + __expf(-x)); }
; __device__ __forceinline__ uint4 pk8(f32x4 a, f32x4 b) { return make_uint4(cvt_pk_bf16(a[0], a[1]), cvt_pk_bf16(a[2], a[3]), cvt_pk_bf16(b[0], b[1]), cvt_pk_bf16(b[2], b[3])); }
;     __device__ __forceinline__ void operator()(AccRef acc, const Unit& u, int wr, int wc, int fr, int fq) const {
;     ...
;             for (int m = 0; m < 4; ++m) {
;                 const int r = u.pm * 256 + ai * 128 + wr * 64 + m * 16 + fr;
;                 const float s = rinv[r];
;                 const size_t o = (size_t)r * D + c0;
;                 const uint4 pa8 = *(const uint4*)(Pa + o), pb8 = *(const uint4*)(Pb + o);
;                 f32x4 v[2];
; #pragma unroll
;                 for (int n = 0; n < 2; ++n) {
;                     const f32x4 pa = unpk4(n == 0 ? make_uint2(pa8.x, pa8.y) : make_uint2(pa8.z, pa8.w)), pb = unpk4(n == 0 ? make_uint2(pb8.x, pb8.y) : make_uint2(pb8.z, pb8.w));
; #pragma unroll
;                     for (int e = 0; e < 4; ++e) v[n][e] = sigm(acc[ai][0][m][n][e] * s) * pa[e] + sigm(acc[ai][1][m][n][e] * s) * pb[e];
;                 }
;                 *(uint4*)(O + o) = pk8(v[0], v[1]);
	v_lshl_add_u64 v[68:69], s[36:37], 0, v[90:91]
	v_ashrrev_i32_e32 v73, 31, v72
	global_store_dwordx4 v[68:69], v[64:67], off
	s_nop 1
	v_lshlrev_b64 v[64:65], 11, v[72:73]
	v_lshl_add_u64 v[72:73], v[72:73], 2, s[28:29]
	v_lshl_add_u64 v[64:65], v[64:65], 0, v[150:151]
	v_lshlrev_b64 v[74:75], 1, v[64:65]
	v_lshl_add_u64 v[64:65], s[88:89], 0, v[74:75]
	v_lshl_add_u64 v[68:69], s[0:1], 0, v[74:75]
	s_waitcnt vmcnt(13)
	v_mul_f32_e32 v57, v57, v212
	v_mul_f32_e32 v61, v61, v212
	v_mul_f32_e32 v57, 0xbfb8aa3b, v57
	v_mul_f32_e32 v61, 0xbfb8aa3b, v61
	v_exp_f32_e32 v57, v57
	v_exp_f32_e32 v61, v61
	v_mul_f32_e32 v56, v56, v212
	v_mul_f32_e32 v60, v60, v212
	v_add_f32_e32 v57, 1.0, v57
	v_mul_f32_e32 v56, 0xbfb8aa3b, v56
	v_add_f32_e32 v61, 1.0, v61
	v_rcp_f32_e32 v57, v57
	v_mul_f32_e32 v60, 0xbfb8aa3b, v60
	v_exp_f32_e32 v56, v56
	v_rcp_f32_e32 v61, v61
	v_exp_f32_e32 v60, v60
	v_lshlrev_b32_e32 v73, 16, v204
	v_and_b32_e32 v204, 0xffff0000, v204
	v_mul_f32_e32 v58, v58, v212
	v_mul_f32_e32 v59, v59, v212
	v_add_f32_e32 v56, 1.0, v56
	v_mul_f32_e32 v62, v62, v212
	v_mul_f32_e32 v58, 0xbfb8aa3b, v58
	v_mul_f32_e32 v59, 0xbfb8aa3b, v59
	v_mul_f32_e32 v48, v48, v212
	v_add_f32_e32 v60, 1.0, v60
	v_rcp_f32_e32 v56, v56
	v_mul_f32_e32 v62, 0xbfb8aa3b, v62
	v_exp_f32_e32 v58, v58
	v_exp_f32_e32 v59, v59
	v_mul_f32_e32 v52, v52, v212
	v_mul_f32_e32 v48, 0xbfb8aa3b, v48
	v_mul_f32_e32 v49, v49, v212
	v_rcp_f32_e32 v60, v60
	v_exp_f32_e32 v62, v62
	v_mul_f32_e32 v52, 0xbfb8aa3b, v52
	v_exp_f32_e32 v48, v48
	v_mul_f32_e32 v49, 0xbfb8aa3b, v49
	v_exp_f32_e32 v52, v52
	v_exp_f32_e32 v49, v49
	v_add_f32_e32 v58, 1.0, v58
	v_add_f32_e32 v59, 1.0, v59
	v_rcp_f32_e32 v58, v58
	v_rcp_f32_e32 v59, v59
	v_add_f32_e32 v48, 1.0, v48
	v_add_f32_e32 v52, 1.0, v52
	v_rcp_f32_e32 v48, v48
	v_mul_f32_e32 v53, v53, v212
	v_add_f32_e32 v49, 1.0, v49
	v_rcp_f32_e32 v52, v52
	v_mul_f32_e32 v53, 0xbfb8aa3b, v53
	v_rcp_f32_e32 v49, v49
	v_exp_f32_e32 v53, v53
	v_lshlrev_b32_e32 v76, 16, v205
	v_and_b32_e32 v205, 0xffff0000, v205
	v_mul_f32_e32 v51, v51, v212
	v_mul_f32_e32 v51, 0xbfb8aa3b, v51
	v_exp_f32_e32 v51, v51
	s_waitcnt vmcnt(13)
	v_lshlrev_b32_e32 v77, 16, v208
	v_and_b32_e32 v208, 0xffff0000, v208
	v_mul_f32_e32 v57, v57, v208
	v_fmac_f32_e32 v57, v61, v204
	v_mul_f32_e32 v61, v63, v212
	v_mul_f32_e32 v61, 0xbfb8aa3b, v61
	v_exp_f32_e32 v61, v61
	v_mul_f32_e32 v56, v56, v77
	v_fmac_f32_e32 v56, v60, v73
	v_add_f32_e32 v60, 1.0, v62
	v_add_f32_e32 v61, 1.0, v61
	v_rcp_f32_e32 v60, v60
	v_rcp_f32_e32 v61, v61
	v_lshlrev_b32_e32 v78, 16, v209
	v_and_b32_e32 v209, 0xffff0000, v209
	v_mul_f32_e32 v58, v58, v78
	v_mul_f32_e32 v59, v59, v209
	v_lshlrev_b32_e32 v204, 16, v210
	v_fmac_f32_e32 v58, v60, v76
	v_fmac_f32_e32 v59, v61, v205
	v_lshlrev_b32_e32 v60, 16, v206
	v_and_b32_e32 v205, 0xffff0000, v210
	v_mul_f32_e32 v204, v48, v204
	v_fmac_f32_e32 v204, v52, v60
	v_mul_f32_e32 v52, v49, v205
	v_mul_f32_e32 v49, v50, v212
	v_add_f32_e32 v48, 1.0, v53
	v_mul_f32_e32 v53, v54, v212
	v_mul_f32_e32 v49, 0xbfb8aa3b, v49
	v_mul_f32_e32 v50, v55, v212
	v_mul_f32_e32 v53, 0xbfb8aa3b, v53
	v_exp_f32_e32 v49, v49
	v_mul_f32_e32 v50, 0xbfb8aa3b, v50
	v_rcp_f32_e32 v48, v48
	v_exp_f32_e32 v53, v53
	v_exp_f32_e32 v50, v50
	v_and_b32_e32 v61, 0xffff0000, v206
	v_add_f32_e32 v49, 1.0, v49
	v_add_f32_e32 v51, 1.0, v51
	v_fmac_f32_e32 v52, v48, v61
	v_add_f32_e32 v48, 1.0, v53
	v_rcp_f32_e32 v49, v49
	v_add_f32_e32 v50, 1.0, v50
	v_rcp_f32_e32 v51, v51
	v_rcp_f32_e32 v48, v48
	v_rcp_f32_e32 v50, v50
	v_lshlrev_b32_e32 v62, 16, v207
	v_and_b32_e32 v63, 0xffff0000, v207
	v_lshlrev_b32_e32 v206, 16, v211
	v_and_b32_e32 v207, 0xffff0000, v211
	v_mul_f32_e32 v53, v49, v206
	v_mul_f32_e32 v51, v51, v207
	v_fmac_f32_e32 v53, v48, v62
	v_fmac_f32_e32 v51, v50, v63

; __device__ __forceinline__ unsigned cvt_pk_bf16(float lo, float hi) { unsigned r; asm volatile("v_cvt_pk_bf16_f32 %0, %1, %2" : "=v"(r) : "v"(lo), "v"(hi)); return r; }
; __device__ __forceinline__ uint4 pk8(f32x4 a, f32x4 b) { return make_uint4(cvt_pk_bf16(a[0], a[1]), cvt_pk_bf16(a[2], a[3]), cvt_pk_bf16(b[0], b[1]), cvt_pk_bf16(b[2], b[3])); }
	v_cvt_pk_bf16_f32 v48, v56, v57

;     __device__ __forceinline__ void operator()(AccRef acc, const Unit& u, int wr, int wc, int fr, int fq) const {
;     ...
;                 const int r = u.pm * 256 + ai * 128 + wr * 64 + m * 16 + fr;
	v_add_u32_e32 v56, 0x90, v148

; __device__ __forceinline__ unsigned cvt_pk_bf16(float lo, float hi) { unsigned r; asm volatile("v_cvt_pk_bf16_f32 %0, %1, %2" : "=v"(r) : "v"(lo), "v"(hi)); return r; }
; __device__ __forceinline__ uint4 pk8(f32x4 a, f32x4 b) { return make_uint4(cvt_pk_bf16(a[0], a[1]), cvt_pk_bf16(a[2], a[3]), cvt_pk_bf16(b[0], b[1]), cvt_pk_bf16(b[2], b[3])); }
	v_cvt_pk_bf16_f32 v49, v58, v59


; __device__ __forceinline__ unsigned cvt_pk_bf16(float lo, float hi) { unsigned r; asm volatile("v_cvt_pk_bf16_f32 %0, %1, %2" : "=v"(r) : "v"(lo), "v"(hi)); return r; }
; __device__ __forceinline__ uint4 pk8(f32x4 a, f32x4 b) { return make_uint4(cvt_pk_bf16(a[0], a[1]), cvt_pk_bf16(a[2], a[3]), cvt_pk_bf16(b[0], b[1]), cvt_pk_bf16(b[2], b[3])); }
	v_cvt_pk_bf16_f32 v50, v204, v52


; __device__ __forceinline__ unsigned cvt_pk_bf16(float lo, float hi) { unsigned r; asm volatile("v_cvt_pk_bf16_f32 %0, %1, %2" : "=v"(r) : "v"(lo), "v"(hi)); return r; }
; __device__ __forceinline__ uint4 pk8(f32x4 a, f32x4 b) { return make_uint4(cvt_pk_bf16(a[0], a[1]), cvt_pk_bf16(a[2], a[3]), cvt_pk_bf16(b[0], b[1]), cvt_pk_bf16(b[2], b[3])); }
	v_cvt_pk_bf16_f32 v51, v53, v51

; __device__ __forceinline__ f32x4 unpk4(uint2 u) { f32x4 r; r[0] = __uint_as_float(u.x << 16); r[1] = __uint_as_float(u.x & 0xffff0000u); r[2] = __uint_as_float(u.y << 16); r[3] = __uint_as_float(u.y & 0xffff0000u); return r; }
; __device__ __forceinline__ float sigm(float x) { return __builtin_amdgcn_rcpf(1.f + __expf(-x)); }
; __device__ __forceinline__ uint4 pk8(f32x4 a, f32x4 b) { return make_uint4(cvt_pk_bf16(a[0], a[1]), cvt_pk_bf16(a[2], a[3]), cvt_pk_bf16(b[0], b[1]), cvt_pk_bf16(b[2], b[3])); }
;     __device__ __forceinline__ void operator()(AccRef acc, const Unit& u, int wr, int wc, int fr, int fq) const {
;         const int c0 = u.pn * 128 + wc * 32 + 8 * fq;
; #pragma unroll
;         for (int ai = 0; ai < 2; ++ai)
; #pragma unroll
;             for (int m = 0; m < 4; ++m) {
;                 const int r = u.pm * 256 + ai * 128 + wr * 64 + m * 16 + fr;
;                 const float s = rinv[r];
;                 const size_t o = (size_t)r * D + c0;
;                 const uint4 pa8 = *(const uint4*)(Pa + o), pb8 = *(const uint4*)(Pb + o);
;                 f32x4 v[2];
; #pragma unroll
;                 for (int n = 0; n < 2; ++n) {
;                     const f32x4 pa = unpk4(n == 0 ? make_uint2(pa8.x, pa8.y) : make_uint2(pa8.z, pa8.w)), pb = unpk4(n == 0 ? make_uint2(pb8.x, pb8.y) : make_uint2(pb8.z, pb8.w));
; #pragma unroll
;                     for (int e = 0; e < 4; ++e) v[n][e] = sigm(acc[ai][0][m][n][e] * s) * pa[e] + sigm(acc[ai][1][m][n][e] * s) * pb[e];
;                 }
;                 *(uint4*)(O + o) = pk8(v[0], v[1]);
	v_lshl_add_u64 v[52:53], s[36:37], 0, v[74:75]
	v_ashrrev_i32_e32 v57, 31, v56
	global_store_dwordx4 v[52:53], v[48:51], off
	s_nop 1
	v_lshlrev_b64 v[48:49], 11, v[56:57]
	v_lshl_add_u64 v[56:57], v[56:57], 2, s[28:29]
	v_lshl_add_u64 v[48:49], v[48:49], 0, v[150:151]
	v_lshlrev_b64 v[58:59], 1, v[48:49]
	v_lshl_add_u64 v[48:49], s[88:89], 0, v[58:59]
	v_lshl_add_u64 v[52:53], s[0:1], 0, v[58:59]
	s_waitcnt vmcnt(11)
	v_mul_f32_e32 v41, v41, v222
	v_mul_f32_e32 v45, v45, v222
	v_mul_f32_e32 v41, 0xbfb8aa3b, v41
	v_mul_f32_e32 v45, 0xbfb8aa3b, v45
	v_exp_f32_e32 v41, v41
	v_exp_f32_e32 v45, v45
	v_mul_f32_e32 v40, v40, v222
	v_mul_f32_e32 v44, v44, v222
	v_add_f32_e32 v41, 1.0, v41
	v_mul_f32_e32 v40, 0xbfb8aa3b, v40
	v_add_f32_e32 v45, 1.0, v45
	v_rcp_f32_e32 v41, v41
	v_mul_f32_e32 v44, 0xbfb8aa3b, v44
	v_exp_f32_e32 v40, v40
	v_rcp_f32_e32 v45, v45
	v_exp_f32_e32 v44, v44
	v_lshlrev_b32_e32 v57, 16, v214
	v_and_b32_e32 v214, 0xffff0000, v214
	v_mul_f32_e32 v42, v42, v222
	v_mul_f32_e32 v43, v43, v222
	v_add_f32_e32 v40, 1.0, v40
	v_mul_f32_e32 v46, v46, v222
	v_mul_f32_e32 v42, 0xbfb8aa3b, v42
	v_mul_f32_e32 v43, 0xbfb8aa3b, v43
	v_mul_f32_e32 v32, v32, v222
	v_add_f32_e32 v44, 1.0, v44
	v_rcp_f32_e32 v40, v40
	v_mul_f32_e32 v46, 0xbfb8aa3b, v46
	v_exp_f32_e32 v42, v42
	v_exp_f32_e32 v43, v43
	v_mul_f32_e32 v36, v36, v222
	v_mul_f32_e32 v32, 0xbfb8aa3b, v32
	v_mul_f32_e32 v33, v33, v222
	v_rcp_f32_e32 v44, v44
	v_exp_f32_e32 v46, v46
	v_mul_f32_e32 v36, 0xbfb8aa3b, v36
	v_exp_f32_e32 v32, v32
	v_mul_f32_e32 v33, 0xbfb8aa3b, v33
	v_exp_f32_e32 v36, v36
	v_exp_f32_e32 v33, v33
	v_add_f32_e32 v42, 1.0, v42
	v_add_f32_e32 v43, 1.0, v43
	v_rcp_f32_e32 v42, v42
	v_rcp_f32_e32 v43, v43
	v_add_f32_e32 v32, 1.0, v32
	v_add_f32_e32 v36, 1.0, v36
	v_rcp_f32_e32 v32, v32
	v_mul_f32_e32 v37, v37, v222
	v_add_f32_e32 v33, 1.0, v33
	v_rcp_f32_e32 v36, v36
	v_mul_f32_e32 v37, 0xbfb8aa3b, v37
	v_rcp_f32_e32 v33, v33
	v_exp_f32_e32 v37, v37
	v_lshlrev_b32_e32 v60, 16, v215
	v_and_b32_e32 v215, 0xffff0000, v215
	v_mul_f32_e32 v35, v35, v222
	v_mul_f32_e32 v35, 0xbfb8aa3b, v35
	v_exp_f32_e32 v35, v35
	s_waitcnt vmcnt(11)
	v_lshlrev_b32_e32 v61, 16, v218
	v_and_b32_e32 v218, 0xffff0000, v218
	v_mul_f32_e32 v41, v41, v218
	v_fmac_f32_e32 v41, v45, v214
	v_mul_f32_e32 v45, v47, v222
	v_mul_f32_e32 v45, 0xbfb8aa3b, v45
	v_exp_f32_e32 v45, v45
	v_mul_f32_e32 v40, v40, v61
	v_fmac_f32_e32 v40, v44, v57
	v_add_f32_e32 v44, 1.0, v46
	v_add_f32_e32 v45, 1.0, v45
	v_rcp_f32_e32 v44, v44
	v_rcp_f32_e32 v45, v45
	v_lshlrev_b32_e32 v62, 16, v219
	v_and_b32_e32 v219, 0xffff0000, v219
	v_mul_f32_e32 v42, v42, v62
	v_mul_f32_e32 v43, v43, v219
	v_lshlrev_b32_e32 v214, 16, v220
	v_fmac_f32_e32 v42, v44, v60
	v_fmac_f32_e32 v43, v45, v215
	v_lshlrev_b32_e32 v44, 16, v216
	v_and_b32_e32 v215, 0xffff0000, v220
	v_mul_f32_e32 v214, v32, v214
	v_fmac_f32_e32 v214, v36, v44
	v_mul_f32_e32 v36, v33, v215
	v_mul_f32_e32 v33, v34, v222
	v_add_f32_e32 v32, 1.0, v37
	v_mul_f32_e32 v37, v38, v222
	v_mul_f32_e32 v33, 0xbfb8aa3b, v33
	v_mul_f32_e32 v34, v39, v222
	v_mul_f32_e32 v37, 0xbfb8aa3b, v37
	v_exp_f32_e32 v33, v33
	v_mul_f32_e32 v34, 0xbfb8aa3b, v34
	v_rcp_f32_e32 v32, v32
	v_exp_f32_e32 v37, v37
	v_exp_f32_e32 v34, v34
	v_and_b32_e32 v45, 0xffff0000, v216
	v_add_f32_e32 v33, 1.0, v33
	v_add_f32_e32 v35, 1.0, v35
	v_fmac_f32_e32 v36, v32, v45
	v_add_f32_e32 v32, 1.0, v37
	v_rcp_f32_e32 v33, v33
	v_add_f32_e32 v34, 1.0, v34
	v_rcp_f32_e32 v35, v35
	v_rcp_f32_e32 v32, v32
	v_rcp_f32_e32 v34, v34
	v_lshlrev_b32_e32 v46, 16, v217
	v_and_b32_e32 v47, 0xffff0000, v217
	v_lshlrev_b32_e32 v216, 16, v221
	v_and_b32_e32 v217, 0xffff0000, v221
	v_mul_f32_e32 v37, v33, v216
	v_mul_f32_e32 v35, v35, v217
	v_fmac_f32_e32 v37, v32, v46
	v_fmac_f32_e32 v35, v34, v47

; __device__ __forceinline__ unsigned cvt_pk_bf16(float lo, float hi) { unsigned r; asm volatile("v_cvt_pk_bf16_f32 %0, %1, %2" : "=v"(r) : "v"(lo), "v"(hi)); return r; }
; __device__ __forceinline__ uint4 pk8(f32x4 a, f32x4 b) { return make_uint4(cvt_pk_bf16(a[0], a[1]), cvt_pk_bf16(a[2], a[3]), cvt_pk_bf16(b[0], b[1]), cvt_pk_bf16(b[2], b[3])); }
;     __device__ __forceinline__ void operator()(AccRef acc, const Unit& u, int wr, int wc, int fr, int fq) const {
;     ...
;                 *(uint4*)(O + o) = pk8(v[0], v[1]);
	v_cvt_pk_bf16_f32 v32, v40, v41

;     __device__ __forceinline__ void operator()(AccRef acc, const Unit& u, int wr, int wc, int fr, int fq) const {
;     ...
;                 const int r = u.pm * 256 + ai * 128 + wr * 64 + m * 16 + fr;
	v_add_u32_e32 v40, 0xa0, v148

; __device__ __forceinline__ unsigned cvt_pk_bf16(float lo, float hi) { unsigned r; asm volatile("v_cvt_pk_bf16_f32 %0, %1, %2" : "=v"(r) : "v"(lo), "v"(hi)); return r; }
; __device__ __forceinline__ uint4 pk8(f32x4 a, f32x4 b) { return make_uint4(cvt_pk_bf16(a[0], a[1]), cvt_pk_bf16(a[2], a[3]), cvt_pk_bf16(b[0], b[1]), cvt_pk_bf16(b[2], b[3])); }
;     __device__ __forceinline__ void operator()(AccRef acc, const Unit& u, int wr, int wc, int fr, int fq) const {
;     ...
;                 *(uint4*)(O + o) = pk8(v[0], v[1]);
	v_cvt_pk_bf16_f32 v33, v42, v43


; __device__ __forceinline__ unsigned cvt_pk_bf16(float lo, float hi) { unsigned r; asm volatile("v_cvt_pk_bf16_f32 %0, %1, %2" : "=v"(r) : "v"(lo), "v"(hi)); return r; }
; __device__ __forceinline__ uint4 pk8(f32x4 a, f32x4 b) { return make_uint4(cvt_pk_bf16(a[0], a[1]), cvt_pk_bf16(a[2], a[3]), cvt_pk_bf16(b[0], b[1]), cvt_pk_bf16(b[2], b[3])); }
;     __device__ __forceinline__ void operator()(AccRef acc, const Unit& u, int wr, int wc, int fr, int fq) const {
;     ...
;                 *(uint4*)(O + o) = pk8(v[0], v[1]);
	v_cvt_pk_bf16_f32 v34, v214, v36


; __device__ __forceinline__ unsigned cvt_pk_bf16(float lo, float hi) { unsigned r; asm volatile("v_cvt_pk_bf16_f32 %0, %1, %2" : "=v"(r) : "v"(lo), "v"(hi)); return r; }
; __device__ __forceinline__ uint4 pk8(f32x4 a, f32x4 b) { return make_uint4(cvt_pk_bf16(a[0], a[1]), cvt_pk_bf16(a[2], a[3]), cvt_pk_bf16(b[0], b[1]), cvt_pk_bf16(b[2], b[3])); }
;     __device__ __forceinline__ void operator()(AccRef acc, const Unit& u, int wr, int wc, int fr, int fq) const {
;     ...
;                 *(uint4*)(O + o) = pk8(v[0], v[1]);
	v_cvt_pk_bf16_f32 v35, v37, v35

; __device__ __forceinline__ f32x4 unpk4(uint2 u) { f32x4 r; r[0] = __uint_as_float(u.x << 16); r[1] = __uint_as_float(u.x & 0xffff0000u); r[2] = __uint_as_float(u.y << 16); r[3] = __uint_as_float(u.y & 0xffff0000u); return r; }
; __device__ __forceinline__ float sigm(float x) { return __builtin_amdgcn_rcpf(1.f + __expf(-x)); }
; __device__ __forceinline__ uint4 pk8(f32x4 a, f32x4 b) { return make_uint4(cvt_pk_bf16(a[0], a[1]), cvt_pk_bf16(a[2], a[3]), cvt_pk_bf16(b[0], b[1]), cvt_pk_bf16(b[2], b[3])); }
;     __device__ __forceinline__ void operator()(AccRef acc, const Unit& u, int wr, int wc, int fr, int fq) const {
;         const int c0 = u.pn * 128 + wc * 32 + 8 * fq;
; #pragma unroll
;         for (int ai = 0; ai < 2; ++ai)
; #pragma unroll
;             for (int m = 0; m < 4; ++m) {
;                 const int r = u.pm * 256 + ai * 128 + wr * 64 + m * 16 + fr;
;                 const float s = rinv[r];
;                 const size_t o = (size_t)r * D + c0;
;                 const uint4 pa8 = *(const uint4*)(Pa + o), pb8 = *(const uint4*)(Pb + o);
;                 f32x4 v[2];
; #pragma unroll
;                 for (int n = 0; n < 2; ++n) {
;                     const f32x4 pa = unpk4(n == 0 ? make_uint2(pa8.x, pa8.y) : make_uint2(pa8.z, pa8.w)), pb = unpk4(n == 0 ? make_uint2(pb8.x, pb8.y) : make_uint2(pb8.z, pb8.w));
; #pragma unroll
;                     for (int e = 0; e < 4; ++e) v[n][e] = sigm(acc[ai][0][m][n][e] * s) * pa[e] + sigm(acc[ai][1][m][n][e] * s) * pb[e];
;                 }
;                 *(uint4*)(O + o) = pk8(v[0], v[1]);
	v_lshl_add_u64 v[36:37], s[36:37], 0, v[58:59]
	v_ashrrev_i32_e32 v41, 31, v40
	global_store_dwordx4 v[36:37], v[32:35], off
	s_nop 1
	v_lshlrev_b64 v[32:33], 11, v[40:41]
	v_lshl_add_u64 v[40:41], v[40:41], 2, s[28:29]
	v_lshl_add_u64 v[32:33], v[32:33], 0, v[150:151]
	v_lshlrev_b64 v[42:43], 1, v[32:33]
	v_lshl_add_u64 v[32:33], s[88:89], 0, v[42:43]
	v_lshl_add_u64 v[36:37], s[0:1], 0, v[42:43]
	s_waitcnt vmcnt(9)
	v_mul_f32_e32 v25, v25, v232
	v_mul_f32_e32 v29, v29, v232
	v_mul_f32_e32 v25, 0xbfb8aa3b, v25
	v_mul_f32_e32 v29, 0xbfb8aa3b, v29
	v_exp_f32_e32 v25, v25
	v_exp_f32_e32 v29, v29
	v_mul_f32_e32 v24, v24, v232
	v_mul_f32_e32 v28, v28, v232
	v_add_f32_e32 v25, 1.0, v25
	v_mul_f32_e32 v24, 0xbfb8aa3b, v24
	v_add_f32_e32 v29, 1.0, v29
	v_rcp_f32_e32 v25, v25
	v_mul_f32_e32 v28, 0xbfb8aa3b, v28
	v_exp_f32_e32 v24, v24
	v_rcp_f32_e32 v29, v29
	v_exp_f32_e32 v28, v28
	v_lshlrev_b32_e32 v41, 16, v224
	v_and_b32_e32 v224, 0xffff0000, v224
	v_mul_f32_e32 v26, v26, v232
	v_mul_f32_e32 v27, v27, v232
	v_add_f32_e32 v24, 1.0, v24
	v_mul_f32_e32 v30, v30, v232
	v_mul_f32_e32 v26, 0xbfb8aa3b, v26
	v_mul_f32_e32 v27, 0xbfb8aa3b, v27
	v_mul_f32_e32 v16, v16, v232
	v_add_f32_e32 v28, 1.0, v28
	v_rcp_f32_e32 v24, v24
	v_mul_f32_e32 v30, 0xbfb8aa3b, v30
	v_exp_f32_e32 v26, v26
	v_exp_f32_e32 v27, v27
	v_mul_f32_e32 v20, v20, v232
	v_mul_f32_e32 v16, 0xbfb8aa3b, v16
	v_mul_f32_e32 v17, v17, v232
	v_rcp_f32_e32 v28, v28
	v_exp_f32_e32 v30, v30
	v_mul_f32_e32 v20, 0xbfb8aa3b, v20
	v_exp_f32_e32 v16, v16
	v_mul_f32_e32 v17, 0xbfb8aa3b, v17
	v_exp_f32_e32 v20, v20
	v_exp_f32_e32 v17, v17
	v_add_f32_e32 v26, 1.0, v26
	v_add_f32_e32 v27, 1.0, v27
	v_rcp_f32_e32 v26, v26
	v_rcp_f32_e32 v27, v27
	v_add_f32_e32 v16, 1.0, v16
	v_add_f32_e32 v20, 1.0, v20
	v_rcp_f32_e32 v16, v16
	v_mul_f32_e32 v21, v21, v232
	v_add_f32_e32 v17, 1.0, v17
	v_rcp_f32_e32 v20, v20
	v_mul_f32_e32 v21, 0xbfb8aa3b, v21
	v_rcp_f32_e32 v17, v17
	v_exp_f32_e32 v21, v21
	v_lshlrev_b32_e32 v44, 16, v225
	v_and_b32_e32 v225, 0xffff0000, v225
	v_mul_f32_e32 v19, v19, v232
	v_mul_f32_e32 v19, 0xbfb8aa3b, v19
	v_exp_f32_e32 v19, v19
	s_waitcnt vmcnt(9)
	v_lshlrev_b32_e32 v45, 16, v228
	v_and_b32_e32 v228, 0xffff0000, v228
	v_mul_f32_e32 v25, v25, v228
	v_fmac_f32_e32 v25, v29, v224
	v_mul_f32_e32 v29, v31, v232
	v_mul_f32_e32 v29, 0xbfb8aa3b, v29
	v_exp_f32_e32 v29, v29
	v_mul_f32_e32 v24, v24, v45
	v_fmac_f32_e32 v24, v28, v41
	v_add_f32_e32 v28, 1.0, v30
	v_add_f32_e32 v29, 1.0, v29
	v_rcp_f32_e32 v28, v28
	v_rcp_f32_e32 v29, v29
	v_lshlrev_b32_e32 v46, 16, v229
	v_and_b32_e32 v229, 0xffff0000, v229
	v_mul_f32_e32 v26, v26, v46
	v_mul_f32_e32 v27, v27, v229
	v_lshlrev_b32_e32 v224, 16, v230
	v_fmac_f32_e32 v26, v28, v44
	v_fmac_f32_e32 v27, v29, v225
	v_lshlrev_b32_e32 v28, 16, v226
	v_and_b32_e32 v225, 0xffff0000, v230
	v_mul_f32_e32 v224, v16, v224
	v_fmac_f32_e32 v224, v20, v28
	v_mul_f32_e32 v20, v17, v225
	v_mul_f32_e32 v17, v18, v232
	v_add_f32_e32 v16, 1.0, v21
	v_mul_f32_e32 v21, v22, v232
	v_mul_f32_e32 v17, 0xbfb8aa3b, v17
	v_mul_f32_e32 v18, v23, v232
	v_mul_f32_e32 v21, 0xbfb8aa3b, v21
	v_exp_f32_e32 v17, v17
	v_mul_f32_e32 v18, 0xbfb8aa3b, v18
	v_rcp_f32_e32 v16, v16
	v_exp_f32_e32 v21, v21
	v_exp_f32_e32 v18, v18
	v_and_b32_e32 v29, 0xffff0000, v226
	v_add_f32_e32 v17, 1.0, v17
	v_add_f32_e32 v19, 1.0, v19
	v_fmac_f32_e32 v20, v16, v29
	v_add_f32_e32 v16, 1.0, v21
	v_rcp_f32_e32 v17, v17
	v_add_f32_e32 v18, 1.0, v18
	v_rcp_f32_e32 v19, v19
	v_rcp_f32_e32 v16, v16
	v_rcp_f32_e32 v18, v18
	v_lshlrev_b32_e32 v30, 16, v227
	v_and_b32_e32 v31, 0xffff0000, v227
	v_lshlrev_b32_e32 v226, 16, v231
	v_and_b32_e32 v227, 0xffff0000, v231
	v_mul_f32_e32 v21, v17, v226
	v_mul_f32_e32 v19, v19, v227
	v_fmac_f32_e32 v21, v16, v30
	v_fmac_f32_e32 v19, v18, v31

; __device__ __forceinline__ unsigned cvt_pk_bf16(float lo, float hi) { unsigned r; asm volatile("v_cvt_pk_bf16_f32 %0, %1, %2" : "=v"(r) : "v"(lo), "v"(hi)); return r; }
; __device__ __forceinline__ uint4 pk8(f32x4 a, f32x4 b) { return make_uint4(cvt_pk_bf16(a[0], a[1]), cvt_pk_bf16(a[2], a[3]), cvt_pk_bf16(b[0], b[1]), cvt_pk_bf16(b[2], b[3])); }
;     __device__ __forceinline__ void operator()(AccRef acc, const Unit& u, int wr, int wc, int fr, int fq) const {
;     ...
;                 *(uint4*)(O + o) = pk8(v[0], v[1]);
	v_cvt_pk_bf16_f32 v16, v24, v25

;     __device__ __forceinline__ void operator()(AccRef acc, const Unit& u, int wr, int wc, int fr, int fq) const {
;     ...
;                 const int r = u.pm * 256 + ai * 128 + wr * 64 + m * 16 + fr;
	v_add_u32_e32 v24, 0xb0, v148

; __device__ __forceinline__ unsigned cvt_pk_bf16(float lo, float hi) { unsigned r; asm volatile("v_cvt_pk_bf16_f32 %0, %1, %2" : "=v"(r) : "v"(lo), "v"(hi)); return r; }
; __device__ __forceinline__ uint4 pk8(f32x4 a, f32x4 b) { return make_uint4(cvt_pk_bf16(a[0], a[1]), cvt_pk_bf16(a[2], a[3]), cvt_pk_bf16(b[0], b[1]), cvt_pk_bf16(b[2], b[3])); }
;     __device__ __forceinline__ void operator()(AccRef acc, const Unit& u, int wr, int wc, int fr, int fq) const {
;     ...
;                 *(uint4*)(O + o) = pk8(v[0], v[1]);
	v_cvt_pk_bf16_f32 v17, v26, v27


; __device__ __forceinline__ unsigned cvt_pk_bf16(float lo, float hi) { unsigned r; asm volatile("v_cvt_pk_bf16_f32 %0, %1, %2" : "=v"(r) : "v"(lo), "v"(hi)); return r; }
; __device__ __forceinline__ uint4 pk8(f32x4 a, f32x4 b) { return make_uint4(cvt_pk_bf16(a[0], a[1]), cvt_pk_bf16(a[2], a[3]), cvt_pk_bf16(b[0], b[1]), cvt_pk_bf16(b[2], b[3])); }
;     __device__ __forceinline__ void operator()(AccRef acc, const Unit& u, int wr, int wc, int fr, int fq) const {
;     ...
;                 *(uint4*)(O + o) = pk8(v[0], v[1]);
	v_cvt_pk_bf16_f32 v18, v224, v20


; __device__ __forceinline__ unsigned cvt_pk_bf16(float lo, float hi) { unsigned r; asm volatile("v_cvt_pk_bf16_f32 %0, %1, %2" : "=v"(r) : "v"(lo), "v"(hi)); return r; }
; __device__ __forceinline__ uint4 pk8(f32x4 a, f32x4 b) { return make_uint4(cvt_pk_bf16(a[0], a[1]), cvt_pk_bf16(a[2], a[3]), cvt_pk_bf16(b[0], b[1]), cvt_pk_bf16(b[2], b[3])); }
;     __device__ __forceinline__ void operator()(AccRef acc, const Unit& u, int wr, int wc, int fr, int fq) const {
;     ...
;                 *(uint4*)(O + o) = pk8(v[0], v[1]);
	v_cvt_pk_bf16_f32 v19, v21, v19

; __device__ __forceinline__ f32x4 unpk4(uint2 u) { f32x4 r; r[0] = __uint_as_float(u.x << 16); r[1] = __uint_as_float(u.x & 0xffff0000u); r[2] = __uint_as_float(u.y << 16); r[3] = __uint_as_float(u.y & 0xffff0000u); return r; }
; __device__ __forceinline__ float sigm(float x) { return __builtin_amdgcn_rcpf(1.f + __expf(-x)); }
; __device__ __forceinline__ uint4 pk8(f32x4 a, f32x4 b) { return make_uint4(cvt_pk_bf16(a[0], a[1]), cvt_pk_bf16(a[2], a[3]), cvt_pk_bf16(b[0], b[1]), cvt_pk_bf16(b[2], b[3])); }
;     __device__ __forceinline__ void operator()(AccRef acc, const Unit& u, int wr, int wc, int fr, int fq) const {
;         const int c0 = u.pn * 128 + wc * 32 + 8 * fq;
; #pragma unroll
;         for (int ai = 0; ai < 2; ++ai)
; #pragma unroll
;             for (int m = 0; m < 4; ++m) {
;                 const int r = u.pm * 256 + ai * 128 + wr * 64 + m * 16 + fr;
;                 const float s = rinv[r];
;                 const size_t o = (size_t)r * D + c0;
;                 const uint4 pa8 = *(const uint4*)(Pa + o), pb8 = *(const uint4*)(Pb + o);
;                 f32x4 v[2];
; #pragma unroll
;                 for (int n = 0; n < 2; ++n) {
;                     const f32x4 pa = unpk4(n == 0 ? make_uint2(pa8.x, pa8.y) : make_uint2(pa8.z, pa8.w)), pb = unpk4(n == 0 ? make_uint2(pb8.x, pb8.y) : make_uint2(pb8.z, pb8.w));
; #pragma unroll
;                     for (int e = 0; e < 4; ++e) v[n][e] = sigm(acc[ai][0][m][n][e] * s) * pa[e] + sigm(acc[ai][1][m][n][e] * s) * pb[e];
;                 }
;                 *(uint4*)(O + o) = pk8(v[0], v[1]);
	v_lshl_add_u64 v[20:21], s[36:37], 0, v[42:43]
	v_ashrrev_i32_e32 v25, 31, v24
	global_store_dwordx4 v[20:21], v[16:19], off
	s_nop 1
	v_lshlrev_b64 v[16:17], 11, v[24:25]
	v_lshl_add_u64 v[24:25], v[24:25], 2, s[28:29]
	v_lshl_add_u64 v[16:17], v[16:17], 0, v[150:151]
	v_lshlrev_b64 v[26:27], 1, v[16:17]
	v_lshl_add_u64 v[16:17], s[88:89], 0, v[26:27]
	v_lshl_add_u64 v[20:21], s[0:1], 0, v[26:27]
	s_waitcnt vmcnt(7)
	v_mul_f32_e32 v9, v9, v242
	v_mul_f32_e32 v13, v13, v242
	v_mul_f32_e32 v9, 0xbfb8aa3b, v9
	v_mul_f32_e32 v13, 0xbfb8aa3b, v13
	v_exp_f32_e32 v9, v9
	v_exp_f32_e32 v13, v13
	v_mul_f32_e32 v8, v8, v242
	v_mul_f32_e32 v12, v12, v242
	v_add_f32_e32 v9, 1.0, v9
	v_mul_f32_e32 v8, 0xbfb8aa3b, v8
	v_add_f32_e32 v13, 1.0, v13
	v_rcp_f32_e32 v9, v9
	v_mul_f32_e32 v12, 0xbfb8aa3b, v12
	v_exp_f32_e32 v8, v8
	v_rcp_f32_e32 v13, v13
	v_exp_f32_e32 v12, v12
	v_lshlrev_b32_e32 v25, 16, v234
	v_and_b32_e32 v234, 0xffff0000, v234
	v_mul_f32_e32 v10, v10, v242
	v_mul_f32_e32 v11, v11, v242
	v_add_f32_e32 v8, 1.0, v8
	v_mul_f32_e32 v14, v14, v242
	v_mul_f32_e32 v10, 0xbfb8aa3b, v10
	v_mul_f32_e32 v11, 0xbfb8aa3b, v11
	v_mul_f32_e32 v0, v0, v242
	v_add_f32_e32 v12, 1.0, v12
	v_rcp_f32_e32 v8, v8
	v_mul_f32_e32 v14, 0xbfb8aa3b, v14
	v_exp_f32_e32 v10, v10
	v_exp_f32_e32 v11, v11
	v_mul_f32_e32 v4, v4, v242
	v_mul_f32_e32 v0, 0xbfb8aa3b, v0
	v_mul_f32_e32 v1, v1, v242
	v_rcp_f32_e32 v12, v12
	v_exp_f32_e32 v14, v14
	v_mul_f32_e32 v4, 0xbfb8aa3b, v4
	v_exp_f32_e32 v0, v0
	v_mul_f32_e32 v1, 0xbfb8aa3b, v1
	v_exp_f32_e32 v4, v4
	v_exp_f32_e32 v1, v1
	v_add_f32_e32 v10, 1.0, v10
	v_add_f32_e32 v11, 1.0, v11
	v_rcp_f32_e32 v10, v10
	v_rcp_f32_e32 v11, v11
	v_add_f32_e32 v0, 1.0, v0
	v_add_f32_e32 v4, 1.0, v4
	v_rcp_f32_e32 v0, v0
	v_mul_f32_e32 v5, v5, v242
	v_add_f32_e32 v1, 1.0, v1
	v_rcp_f32_e32 v4, v4
	v_mul_f32_e32 v5, 0xbfb8aa3b, v5
	v_rcp_f32_e32 v1, v1
	v_exp_f32_e32 v5, v5
	v_lshlrev_b32_e32 v28, 16, v235
	v_and_b32_e32 v235, 0xffff0000, v235
	v_mul_f32_e32 v3, v3, v242
	v_mul_f32_e32 v3, 0xbfb8aa3b, v3
	v_exp_f32_e32 v3, v3
	s_waitcnt vmcnt(7)
	v_lshlrev_b32_e32 v29, 16, v238
	v_and_b32_e32 v238, 0xffff0000, v238
	v_mul_f32_e32 v9, v9, v238
	v_fmac_f32_e32 v9, v13, v234
	v_mul_f32_e32 v13, v15, v242
	v_mul_f32_e32 v13, 0xbfb8aa3b, v13
	v_exp_f32_e32 v13, v13
	v_mul_f32_e32 v8, v8, v29
	v_fmac_f32_e32 v8, v12, v25
	v_add_f32_e32 v12, 1.0, v14
	v_add_f32_e32 v13, 1.0, v13
	v_rcp_f32_e32 v12, v12
	v_rcp_f32_e32 v13, v13
	v_lshlrev_b32_e32 v30, 16, v239
	v_and_b32_e32 v239, 0xffff0000, v239
	v_mul_f32_e32 v10, v10, v30
	v_mul_f32_e32 v11, v11, v239
	v_lshlrev_b32_e32 v234, 16, v240
	v_fmac_f32_e32 v10, v12, v28
	v_fmac_f32_e32 v11, v13, v235
	v_lshlrev_b32_e32 v12, 16, v236
	v_and_b32_e32 v235, 0xffff0000, v240
	v_mul_f32_e32 v234, v0, v234
	v_fmac_f32_e32 v234, v4, v12
	v_mul_f32_e32 v4, v1, v235
	v_mul_f32_e32 v1, v2, v242
	v_add_f32_e32 v0, 1.0, v5
	v_mul_f32_e32 v5, v6, v242
	v_mul_f32_e32 v1, 0xbfb8aa3b, v1
	v_mul_f32_e32 v2, v7, v242
	v_mul_f32_e32 v5, 0xbfb8aa3b, v5
	v_exp_f32_e32 v1, v1
	v_mul_f32_e32 v2, 0xbfb8aa3b, v2
	v_rcp_f32_e32 v0, v0
	v_exp_f32_e32 v5, v5
	v_exp_f32_e32 v2, v2
	v_and_b32_e32 v13, 0xffff0000, v236
	v_add_f32_e32 v1, 1.0, v1
	v_add_f32_e32 v3, 1.0, v3
	v_fmac_f32_e32 v4, v0, v13
	v_add_f32_e32 v0, 1.0, v5
	v_rcp_f32_e32 v1, v1
	v_add_f32_e32 v2, 1.0, v2
	v_rcp_f32_e32 v3, v3
	v_rcp_f32_e32 v0, v0
	v_rcp_f32_e32 v2, v2
	v_lshlrev_b32_e32 v14, 16, v237
	v_and_b32_e32 v15, 0xffff0000, v237
	v_lshlrev_b32_e32 v236, 16, v241
	v_and_b32_e32 v237, 0xffff0000, v241
	v_mul_f32_e32 v5, v1, v236
	v_mul_f32_e32 v3, v3, v237
	v_fmac_f32_e32 v5, v0, v14
	v_fmac_f32_e32 v3, v2, v15

; __device__ __forceinline__ unsigned cvt_pk_bf16(float lo, float hi) { unsigned r; asm volatile("v_cvt_pk_bf16_f32 %0, %1, %2" : "=v"(r) : "v"(lo), "v"(hi)); return r; }
; __device__ __forceinline__ uint4 pk8(f32x4 a, f32x4 b) { return make_uint4(cvt_pk_bf16(a[0], a[1]), cvt_pk_bf16(a[2], a[3]), cvt_pk_bf16(b[0], b[1]), cvt_pk_bf16(b[2], b[3])); }
;     __device__ __forceinline__ void operator()(AccRef acc, const Unit& u, int wr, int wc, int fr, int fq) const {
;     ...
;                 *(uint4*)(O + o) = pk8(v[0], v[1]);
	v_cvt_pk_bf16_f32 v0, v8, v9


; __device__ __forceinline__ unsigned cvt_pk_bf16(float lo, float hi) { unsigned r; asm volatile("v_cvt_pk_bf16_f32 %0, %1, %2" : "=v"(r) : "v"(lo), "v"(hi)); return r; }
; __device__ __forceinline__ uint4 pk8(f32x4 a, f32x4 b) { return make_uint4(cvt_pk_bf16(a[0], a[1]), cvt_pk_bf16(a[2], a[3]), cvt_pk_bf16(b[0], b[1]), cvt_pk_bf16(b[2], b[3])); }
;     __device__ __forceinline__ void operator()(AccRef acc, const Unit& u, int wr, int wc, int fr, int fq) const {
;     ...
;                 *(uint4*)(O + o) = pk8(v[0], v[1]);
	v_cvt_pk_bf16_f32 v1, v10, v11


; __device__ __forceinline__ unsigned cvt_pk_bf16(float lo, float hi) { unsigned r; asm volatile("v_cvt_pk_bf16_f32 %0, %1, %2" : "=v"(r) : "v"(lo), "v"(hi)); return r; }
; __device__ __forceinline__ uint4 pk8(f32x4 a, f32x4 b) { return make_uint4(cvt_pk_bf16(a[0], a[1]), cvt_pk_bf16(a[2], a[3]), cvt_pk_bf16(b[0], b[1]), cvt_pk_bf16(b[2], b[3])); }
;     __device__ __forceinline__ void operator()(AccRef acc, const Unit& u, int wr, int wc, int fr, int fq) const {
;     ...
;                 *(uint4*)(O + o) = pk8(v[0], v[1]);
	v_cvt_pk_bf16_f32 v2, v234, v4


; __device__ __forceinline__ unsigned cvt_pk_bf16(float lo, float hi) { unsigned r; asm volatile("v_cvt_pk_bf16_f32 %0, %1, %2" : "=v"(r) : "v"(lo), "v"(hi)); return r; }
; __device__ __forceinline__ uint4 pk8(f32x4 a, f32x4 b) { return make_uint4(cvt_pk_bf16(a[0], a[1]), cvt_pk_bf16(a[2], a[3]), cvt_pk_bf16(b[0], b[1]), cvt_pk_bf16(b[2], b[3])); }
;     __device__ __forceinline__ void operator()(AccRef acc, const Unit& u, int wr, int wc, int fr, int fq) const {
;     ...
;                 *(uint4*)(O + o) = pk8(v[0], v[1]);
	v_cvt_pk_bf16_f32 v3, v5, v3

; #define PG8_WAIT_V(n) asm volatile("s_waitcnt vmcnt(" #n ")" ::: "memory")
; #define PG8_BAR __builtin_amdgcn_s_barrier()
; __device__ __forceinline__ uint4 pk8(f32x4 a, f32x4 b) { return make_uint4(cvt_pk_bf16(a[0], a[1]), cvt_pk_bf16(a[2], a[3]), cvt_pk_bf16(b[0], b[1]), cvt_pk_bf16(b[2], b[3])); }
; template <class Epi, class Sched>
; __device__ __forceinline__ void gemm_phase(PG8_LAS unsigned char* lds, const Gemm g, const Sched& S, const Epi& E) {
;     ...
;         if (!has_next) break;
; #pragma unroll
;         for (int a = 0; a < 2; ++a)
; #pragma unroll
;             for (int b = 0; b < 2; ++b)
; #pragma unroll
;                 for (int m = 0; m < 4; ++m)
; #pragma unroll
;                     for (int n = 0; n < 2; ++n) acc[a][b][m][n] = (f32x4){0.f, 0.f, 0.f, 0.f};
;         cur = nxt; cA = nA; cB = nB; ++ui;
;     }
;     PG8_WAIT_V(0);
;     if (wr == 0) PG8_BAR;
;     PG8_BAR;
;     __device__ __forceinline__ void operator()(AccRef acc, const Unit& u, int wr, int wc, int fr, int fq) const {
;     ...
;                 *(uint4*)(O + o) = pk8(v[0], v[1]);
	v_lshl_add_u64 v[4:5], s[36:37], 0, v[26:27]
	global_store_dwordx4 v[4:5], v[0:3], off
	s_cbranch_vccz .LBB0_681
	s_waitcnt vmcnt(0)
	s_cmpk_gt_u32 s3, 0xff
	s_cbranch_scc1 .LBB0_692
	s_barrier

; __global__ __launch_bounds__(512, 2) void mega(Params P) {
	.amdhsa_kernel _Z4mega6Params
		.amdhsa_group_segment_fixed_size 0
		.amdhsa_private_segment_fixed_size 0
		.amdhsa_kernarg_size 488
		.amdhsa_user_sgpr_count 2
		.amdhsa_user_sgpr_dispatch_ptr 0
		.amdhsa_user_sgpr_queue_ptr 0
		.amdhsa_user_sgpr_kernarg_segment_ptr 1
		.amdhsa_user_sgpr_dispatch_id 0
		.amdhsa_user_sgpr_kernarg_preload_length 0
		.amdhsa_user_sgpr_kernarg_preload_offset 0
		.amdhsa_user_sgpr_private_segment_size 0
		.amdhsa_uses_dynamic_stack 0
		.amdhsa_enable_private_segment 0
		.amdhsa_system_sgpr_workgroup_id_x 1
		.amdhsa_system_sgpr_workgroup_id_y 0
		.amdhsa_system_sgpr_workgroup_id_z 0
		.amdhsa_system_sgpr_workgroup_info 0
		.amdhsa_system_vgpr_workitem_id 2
		.amdhsa_next_free_vgpr 256
		.amdhsa_next_free_sgpr 102
		.amdhsa_accum_offset 256
		.amdhsa_reserve_vcc 1
		.amdhsa_float_round_mode_32 0
		.amdhsa_float_round_mode_16_64 0
		.amdhsa_float_denorm_mode_32 3
		.amdhsa_float_denorm_mode_16_64 3
		.amdhsa_dx10_clamp 1
		.amdhsa_ieee_mode 1
		.amdhsa_fp16_overflow 0
		.amdhsa_tg_split 0
		.amdhsa_exception_fp_ieee_invalid_op 0
		.amdhsa_exception_fp_denorm_src 0
		.amdhsa_exception_fp_ieee_div_zero 0
		.amdhsa_exception_fp_ieee_overflow 0
		.amdhsa_exception_fp_ieee_underflow 0
		.amdhsa_exception_fp_ieee_inexact 0
		.amdhsa_exception_int_div_zero 0
	.end_amdhsa_kernel

; __global__ __launch_bounds__(512, 2) void mega(Params P) {
amdhsa.kernels:
  - .agpr_count:     0
    .args:
      - .offset:         0
        .size:           232
        .value_kind:     by_value
      - .offset:         232
        .size:           4
        .value_kind:     hidden_block_count_x
      - .offset:         236
        .size:           4
        .value_kind:     hidden_block_count_y
      - .offset:         240
        .size:           4
        .value_kind:     hidden_block_count_z
      - .offset:         244
        .size:           2
        .value_kind:     hidden_group_size_x
      - .offset:         246
        .size:           2
        .value_kind:     hidden_group_size_y
      - .offset:         248
        .size:           2
        .value_kind:     hidden_group_size_z
      - .offset:         250
        .size:           2
        .value_kind:     hidden_remainder_x
      - .offset:         252
        .size:           2
        .value_kind:     hidden_remainder_y
      - .offset:         254
        .size:           2
        .value_kind:     hidden_remainder_z
      - .offset:         272
        .size:           8
        .value_kind:     hidden_global_offset_x
      - .offset:         280
        .size:           8
        .value_kind:     hidden_global_offset_y
      - .offset:         288
        .size:           8
        .value_kind:     hidden_global_offset_z
      - .offset:         296
        .size:           2
        .value_kind:     hidden_grid_dims
      - .offset:         320
        .size:           8
        .value_kind:     hidden_multigrid_sync_arg
      - .offset:         352
        .size:           4
        .value_kind:     hidden_dynamic_lds_size
    .group_segment_fixed_size: 0
    .kernarg_segment_align: 8
    .kernarg_segment_size: 488
    .language:       OpenCL C
    .language_version:
      - 2
      - 0
    .max_flat_workgroup_size: 512
    .name:           _Z4mega6Params
    .private_segment_fixed_size: 0
    .sgpr_count:     108
    .sgpr_spill_count: 38
    .symbol:         _Z4mega6Params.kd
    .uniform_work_group_size: 1
    .uses_dynamic_stack: false
    .vgpr_count:     256
    .vgpr_spill_count: 0
    .wavefront_size: 64
